# first K-loop iteration peeled per tile with C=0 on the first MFMA of each accumulator; the 128 accumulator-zeroing v_mov per tile removed
# speedup vs baseline: 1.0009x; 1.0009x over previous
; #define PG8_STAGE(bufoff, gbase, voff) do { _Pragma("unroll") for (int _i = 0; _i < 2; ++_i) \
;         __builtin_amdgcn_global_load_lds((const unsigned*)((const char*)(gbase) + (voff)[_i]), (LAS unsigned*)(lds + (bufoff) + ldsw + _i * 8192), 16, 0, 0); } while (0)
; #define PG8_LDA(dst, b, h) do { _Pragma("unroll") for (int m = 0; m < 4; ++m) _Pragma("unroll") for (int k = 0; k < 2; ++k) dst[m][k] = *(const LAS bf16x8*)(lds + PG8_SA(b, h) + aoff + m * 2048 + k * 1024); } while (0)
; #define PG8_LDB(dst, b, h) do { _Pragma("unroll") for (int n = 0; n < 2; ++n) _Pragma("unroll") for (int k = 0; k < 2; ++k) dst[n][k] = *(const LAS bf16x8*)(lds + PG8_SB(b, h) + boff + n * 2048 + k * 1024); } while (0)
; template <class Epi>
; __device__ __forceinline__ void gemm_phase(LAS unsigned char* lds, const Gemm g, const StaticOrder& S, const Epi& E) {
;     ...
;     for (;;) {
;         const bool has_next = S.next(ui + 1, nxt);
;         const char* nA = has_next ? (const char*)g.A + (size_t)nxt.pm * tstep : cA; const char* nB = has_next ? (const char*)g.Bt + (size_t)nxt.pn * tstep : cB;
;         for (int t = 0; t < nt; t += 2) {
;             const bool last = (t == nt - 2);
;             const char* a1 = cA + (size_t)(t + 1) * kstep;
;             const char* a2 = last ? nA : cA + (size_t)(t + 2) * kstep; const char* b2 = last ? nB : cB + (size_t)(t + 2) * kstep;
;             const char* a3 = a2 + kstep; const char* b3 = b2 + kstep;
;             PG8_LDB(B0, 0, 0); PG8_SCHED; PG8_LDA(At, 0, 0); PG8_STAGE(PG8_SA(1, 1), a1 + hstep, voffA);
;             PG8_WAIT_L(8); PG8_BAR; PG8_WAIT_L(0); PG8_MMA(0, 0, At, B0); PG8_BAR; PG8_SCHED;
;             PG8_LDB(B1, 0, 1); PG8_STAGE(PG8_SB(0, 0), b2, voffB);
;             PG8_BAR; PG8_WAIT_L(0); PG8_MMA(0, 1, At, B1); PG8_BAR;
;             PG8_LDA(At, 0, 1); PG8_STAGE(PG8_SA(0, 0), a2, voffA);
;             PG8_BAR; PG8_WAIT_L(0); PG8_MMA(1, 0, At, B0); PG8_BAR; PG8_SCHED;
;             PG8_STAGE(PG8_SB(0, 1), b2 + hstep, voffB);
;             PG8_WAIT_V(6); PG8_BAR; PG8_MMA(1, 1, At, B1); PG8_BAR;
;     ...
; #pragma unroll
;         for (int a = 0; a < 2; ++a)
; #pragma unroll
;             for (int b = 0; b < 2; ++b)
; #pragma unroll
;                 for (int m = 0; m < 4; ++m)
; #pragma unroll
;                     for (int n = 0; n < 2; ++n) acc[a][b][m][n] = (f32x4){0.f, 0.f, 0.f, 0.f};
.LBB0_258:
	s_ashr_i32 s9, s8, 31
	v_cmp_lt_i64_e32 vcc, s[10:11], v[140:141]
	s_lshl_b64 s[10:11], s[8:9], 20
	s_add_u32 s10, s23, s10
	s_addc_u32 s11, s24, s11
	s_and_b64 s[12:13], vcc, exec
	s_cselect_b32 s9, s11, s17
	s_cselect_b32 s63, s10, s16
	s_ashr_i32 s7, s6, 31
	s_lshl_b64 s[12:13], s[6:7], 20
	s_add_u32 s12, s25, s12
	s_addc_u32 s13, s30, s13
	s_and_b64 s[20:21], vcc, exec
	s_cselect_b32 s7, s13, s19
	s_cselect_b32 s64, s12, s18
	s_add_u32 s16, s16, 0x80080
	s_addc_u32 s17, s17, 0
	s_add_u32 s65, s18, 0x100
	s_addc_u32 s66, s19, 0
	s_mov_b32 s67, -2
	ds_read_b128 v[160:163], v148
	ds_read_b128 v[166:169], v148 offset:1024
	ds_read_b128 v[170:173], v148 offset:2048
	ds_read_b128 v[174:177], v148 offset:3072
	s_add_u32 s18, s16, 0xfff80080
	s_addc_u32 s19, s17, -1
	s_cmp_eq_u32 s67, 28
	s_cselect_b32 s21, s9, s19
	s_cselect_b32 s20, s63, s18
	s_cselect_b32 s19, s7, s66
	s_cselect_b32 s18, s64, s65
	v_lshl_add_u64 v[212:213], s[16:17], 0, v[136:137]
	s_add_i32 m0, s35, 0xc000
	ds_read_b128 v[180:183], v149
	ds_read_b128 v[184:187], v149 offset:1024
	ds_read_b128 v[188:191], v149 offset:2048
	ds_read_b128 v[192:195], v149 offset:3072
	ds_read_b128 v[196:199], v149 offset:4096
	ds_read_b128 v[200:203], v149 offset:5120
	ds_read_b128 v[204:207], v149 offset:6144
	ds_read_b128 v[208:211], v149 offset:7168
	global_load_lds_dwordx4 v[212:213], off
	v_lshl_add_u64 v[212:213], s[16:17], 0, v[138:139]
	s_add_i32 m0, s35, 0xe000
	s_nop 0
	global_load_lds_dwordx4 v[212:213], off
	ds_read_b128 v[212:215], v150
	ds_read_b128 v[216:219], v150 offset:1024
	ds_read_b128 v[220:223], v150 offset:2048
	ds_read_b128 v[224:227], v150 offset:3072
	s_waitcnt lgkmcnt(0)
	s_waitcnt vmcnt(8)
	s_setprio 1
	s_barrier
	v_mfma_f32_16x16x32_bf16 v[124:127], v[160:163], v[180:183], 0
	v_mfma_f32_16x16x32_bf16 v[116:119], v[170:173], v[180:183], 0
	v_mfma_f32_16x16x32_bf16 v[108:111], v[160:163], v[188:191], 0
	v_mfma_f32_16x16x32_bf16 v[100:103], v[170:173], v[188:191], 0
	v_mfma_f32_16x16x32_bf16 v[92:95], v[160:163], v[196:199], 0
	v_mfma_f32_16x16x32_bf16 v[84:87], v[170:173], v[196:199], 0
	v_mfma_f32_16x16x32_bf16 v[76:79], v[160:163], v[204:207], 0
	v_mfma_f32_16x16x32_bf16 v[68:71], v[170:173], v[204:207], 0
	v_mfma_f32_16x16x32_bf16 v[124:127], v[166:169], v[184:187], v[124:127]
	v_mfma_f32_16x16x32_bf16 v[116:119], v[174:177], v[184:187], v[116:119]
	v_mfma_f32_16x16x32_bf16 v[108:111], v[166:169], v[192:195], v[108:111]
	v_mfma_f32_16x16x32_bf16 v[100:103], v[174:177], v[192:195], v[100:103]
	v_mfma_f32_16x16x32_bf16 v[92:95], v[166:169], v[200:203], v[92:95]
	v_mfma_f32_16x16x32_bf16 v[84:87], v[174:177], v[200:203], v[84:87]
	v_mfma_f32_16x16x32_bf16 v[76:79], v[166:169], v[208:211], v[76:79]
	v_mfma_f32_16x16x32_bf16 v[68:71], v[174:177], v[208:211], v[68:71]
	v_mfma_f32_16x16x32_bf16 v[120:123], v[212:215], v[180:183], 0
	v_mfma_f32_16x16x32_bf16 v[112:115], v[220:223], v[180:183], 0
	v_mfma_f32_16x16x32_bf16 v[104:107], v[212:215], v[188:191], 0
	v_mfma_f32_16x16x32_bf16 v[96:99], v[220:223], v[188:191], 0
	v_mfma_f32_16x16x32_bf16 v[88:91], v[212:215], v[196:199], 0
	v_mfma_f32_16x16x32_bf16 v[80:83], v[220:223], v[196:199], 0
	v_mfma_f32_16x16x32_bf16 v[72:75], v[212:215], v[204:207], 0
	v_mfma_f32_16x16x32_bf16 v[64:67], v[220:223], v[204:207], 0
	v_mfma_f32_16x16x32_bf16 v[120:123], v[216:219], v[184:187], v[120:123]
	v_mfma_f32_16x16x32_bf16 v[112:115], v[224:227], v[184:187], v[112:115]
	v_mfma_f32_16x16x32_bf16 v[104:107], v[216:219], v[192:195], v[104:107]
	v_mfma_f32_16x16x32_bf16 v[96:99], v[224:227], v[192:195], v[96:99]
	v_mfma_f32_16x16x32_bf16 v[88:91], v[216:219], v[200:203], v[88:91]
	v_mfma_f32_16x16x32_bf16 v[80:83], v[224:227], v[200:203], v[80:83]
	v_mfma_f32_16x16x32_bf16 v[72:75], v[216:219], v[208:211], v[72:75]
	v_mfma_f32_16x16x32_bf16 v[64:67], v[224:227], v[208:211], v[64:67]
	s_barrier
	s_setprio 0
	s_add_i32 s68, s60, s31
	v_lshl_add_u64 v[228:229], s[18:19], 0, v[132:133]
	s_mov_b32 m0, s68
	s_nop 0
	global_load_lds_dwordx4 v[228:229], off
	v_lshl_add_u64 v[230:231], s[18:19], 0, v[128:129]
	s_add_i32 m0, s68, 0x2000
	s_nop 0
	global_load_lds_dwordx4 v[230:231], off
	s_mov_b32 m0, s35
	v_lshl_add_u64 v[232:233], s[20:21], 0, v[134:135]
	ds_read_b128 v[180:183], v149 offset:16384
	ds_read_b128 v[184:187], v149 offset:17408
	ds_read_b128 v[188:191], v149 offset:18432
	ds_read_b128 v[192:195], v149 offset:19456
	ds_read_b128 v[196:199], v149 offset:20480
	ds_read_b128 v[200:203], v149 offset:21504
	ds_read_b128 v[204:207], v149 offset:22528
	ds_read_b128 v[208:211], v149 offset:23552
	global_load_lds_dwordx4 v[232:233], off
	v_lshl_add_u64 v[234:235], s[20:21], 0, v[130:131]
	s_mov_b32 m0, s38
	s_nop 0
	global_load_lds_dwordx4 v[234:235], off
	s_add_u32 s68, s18, 0x80000
	s_addc_u32 s69, s19, 0
	s_add_i32 s70, s61, s31
	v_lshl_add_u64 v[252:253], s[68:69], 0, v[132:133]
	s_mov_b32 m0, s70
	s_nop 0
	global_load_lds_dwordx4 v[252:253], off
	v_lshl_add_u64 v[252:253], s[68:69], 0, v[128:129]
	s_add_i32 m0, s70, 0x2000
	s_nop 0
	global_load_lds_dwordx4 v[252:253], off
	s_waitcnt lgkmcnt(0)
	s_waitcnt vmcnt(8)
	s_setprio 1
	s_barrier
; #define PG8_STAGE(bufoff, gbase, voff) do { _Pragma("unroll") for (int _i = 0; _i < 2; ++_i) \
;         __builtin_amdgcn_global_load_lds((const unsigned*)((const char*)(gbase) + (voff)[_i]), (LAS unsigned*)(lds + (bufoff) + ldsw + _i * 8192), 16, 0, 0); } while (0)
; #define PG8_LDA(dst, b, h) do { _Pragma("unroll") for (int m = 0; m < 4; ++m) _Pragma("unroll") for (int k = 0; k < 2; ++k) dst[m][k] = *(const LAS bf16x8*)(lds + PG8_SA(b, h) + aoff + m * 2048 + k * 1024); } while (0)
; #define PG8_LDB(dst, b, h) do { _Pragma("unroll") for (int n = 0; n < 2; ++n) _Pragma("unroll") for (int k = 0; k < 2; ++k) dst[n][k] = *(const LAS bf16x8*)(lds + PG8_SB(b, h) + boff + n * 2048 + k * 1024); } while (0)
; #define PG8_WAIT_V(n) asm volatile("s_waitcnt vmcnt(" #n ")" ::: "memory")
; #define PG8_WAIT_L(n) asm volatile("s_waitcnt lgkmcnt(" #n ")" ::: "memory")
; #define PG8_BAR __builtin_amdgcn_s_barrier()
; #define PG8_SCHED __builtin_amdgcn_sched_barrier(0)
; template <class Epi>
; __device__ __forceinline__ void gemm_phase(LAS unsigned char* lds, const Gemm g, const StaticOrder& S, const Epi& E) {
;     ...
;             PG8_LDB(B0, 0, 0); PG8_SCHED; PG8_LDA(At, 0, 0); PG8_STAGE(PG8_SA(1, 1), a1 + hstep, voffA);
;             PG8_WAIT_L(8); PG8_BAR; PG8_WAIT_L(0); PG8_MMA(0, 0, At, B0); PG8_BAR; PG8_SCHED;
;             PG8_LDB(B1, 0, 1); PG8_STAGE(PG8_SB(0, 0), b2, voffB);
;             PG8_BAR; PG8_WAIT_L(0); PG8_MMA(0, 1, At, B1); PG8_BAR;
;             PG8_LDA(At, 0, 1); PG8_STAGE(PG8_SA(0, 0), a2, voffA);
;             PG8_BAR; PG8_WAIT_L(0); PG8_MMA(1, 0, At, B0); PG8_BAR; PG8_SCHED;
;             PG8_STAGE(PG8_SB(0, 1), b2 + hstep, voffB);
;             PG8_WAIT_V(6); PG8_BAR; PG8_MMA(1, 1, At, B1); PG8_BAR;
;             PG8_LDB(B0, 1, 0); PG8_SCHED; PG8_LDA(At, 1, 0); PG8_STAGE(PG8_SA(0, 1), a2 + hstep, voffA);
;             PG8_WAIT_L(8); PG8_BAR; PG8_WAIT_L(0); PG8_MMA(0, 0, At, B0); PG8_BAR; PG8_SCHED;
;             PG8_LDB(B1, 1, 1); PG8_STAGE(PG8_SB(1, 0), b3, voffB);
;             PG8_BAR; PG8_WAIT_L(0); PG8_MMA(0, 1, At, B1); PG8_BAR;
;             PG8_LDA(At, 1, 1); PG8_STAGE(PG8_SA(1, 0), a3, voffA);
;             PG8_BAR; PG8_WAIT_L(0); PG8_MMA(1, 0, At, B0); PG8_BAR; PG8_SCHED;
;             PG8_STAGE(PG8_SB(1, 1), b3 + hstep, voffB);
;             PG8_WAIT_V(6); PG8_BAR; PG8_MMA(1, 1, At, B1); PG8_BAR;
	v_mfma_f32_16x16x32_bf16 v[60:63], v[160:163], v[180:183], 0
	v_mfma_f32_16x16x32_bf16 v[52:55], v[170:173], v[180:183], 0
	v_mfma_f32_16x16x32_bf16 v[44:47], v[160:163], v[188:191], 0
	v_mfma_f32_16x16x32_bf16 v[36:39], v[170:173], v[188:191], 0
	v_mfma_f32_16x16x32_bf16 v[28:31], v[160:163], v[196:199], 0
	v_mfma_f32_16x16x32_bf16 v[20:23], v[170:173], v[196:199], 0
	v_mfma_f32_16x16x32_bf16 v[12:15], v[160:163], v[204:207], 0
	v_mfma_f32_16x16x32_bf16 v[4:7], v[170:173], v[204:207], 0
	v_mfma_f32_16x16x32_bf16 v[60:63], v[166:169], v[184:187], v[60:63]
	v_mfma_f32_16x16x32_bf16 v[52:55], v[174:177], v[184:187], v[52:55]
	v_mfma_f32_16x16x32_bf16 v[44:47], v[166:169], v[192:195], v[44:47]
	v_mfma_f32_16x16x32_bf16 v[36:39], v[174:177], v[192:195], v[36:39]
	v_mfma_f32_16x16x32_bf16 v[28:31], v[166:169], v[200:203], v[28:31]
	v_mfma_f32_16x16x32_bf16 v[20:23], v[174:177], v[200:203], v[20:23]
	v_mfma_f32_16x16x32_bf16 v[12:15], v[166:169], v[208:211], v[12:15]
	v_mfma_f32_16x16x32_bf16 v[4:7], v[174:177], v[208:211], v[4:7]
	v_mfma_f32_16x16x32_bf16 v[56:59], v[212:215], v[180:183], 0
	v_mfma_f32_16x16x32_bf16 v[48:51], v[220:223], v[180:183], 0
	v_mfma_f32_16x16x32_bf16 v[40:43], v[212:215], v[188:191], 0
	v_mfma_f32_16x16x32_bf16 v[32:35], v[220:223], v[188:191], 0
	v_mfma_f32_16x16x32_bf16 v[24:27], v[212:215], v[196:199], 0
	v_mfma_f32_16x16x32_bf16 v[16:19], v[220:223], v[196:199], 0
	v_mfma_f32_16x16x32_bf16 v[8:11], v[212:215], v[204:207], 0
	v_mfma_f32_16x16x32_bf16 v[0:3], v[220:223], v[204:207], 0
	v_mfma_f32_16x16x32_bf16 v[56:59], v[216:219], v[184:187], v[56:59]
	v_mfma_f32_16x16x32_bf16 v[48:51], v[224:227], v[184:187], v[48:51]
	v_mfma_f32_16x16x32_bf16 v[40:43], v[216:219], v[192:195], v[40:43]
	v_mfma_f32_16x16x32_bf16 v[32:35], v[224:227], v[192:195], v[32:35]
	v_mfma_f32_16x16x32_bf16 v[24:27], v[216:219], v[200:203], v[24:27]
	v_mfma_f32_16x16x32_bf16 v[16:19], v[224:227], v[200:203], v[16:19]
	v_mfma_f32_16x16x32_bf16 v[8:11], v[216:219], v[208:211], v[8:11]
	v_mfma_f32_16x16x32_bf16 v[0:3], v[224:227], v[208:211], v[0:3]
	s_barrier
	s_setprio 0
	s_add_i32 s68, 0, 0x18000
	v_add_u32_e32 v165, s68, v146
	ds_read_b128 v[160:163], v165
	ds_read_b128 v[166:169], v165 offset:1024
	ds_read_b128 v[170:173], v165 offset:2048
	ds_read_b128 v[174:177], v165 offset:3072
	s_add_u32 s20, s20, 0x80000
	s_addc_u32 s21, s21, 0
	s_mov_b32 m0, s39
	v_lshl_add_u64 v[212:213], s[20:21], 0, v[134:135]
	ds_read_b128 v[180:183], v149 offset:32768
	ds_read_b128 v[184:187], v149 offset:33792
	ds_read_b128 v[188:191], v149 offset:34816
	ds_read_b128 v[192:195], v149 offset:35840
	ds_read_b128 v[196:199], v149 offset:36864
	ds_read_b128 v[200:203], v149 offset:37888
	ds_read_b128 v[204:207], v149 offset:38912
	ds_read_b128 v[208:211], v149 offset:39936
	global_load_lds_dwordx4 v[212:213], off
	v_lshl_add_u64 v[212:213], s[20:21], 0, v[130:131]
	s_mov_b32 m0, s42
	s_nop 0
	global_load_lds_dwordx4 v[212:213], off
	s_add_i32 s20, 0, 0x1c000
	v_add_u32_e32 v165, s20, v146
	ds_read_b128 v[212:215], v165
	ds_read_b128 v[216:219], v165 offset:1024
	ds_read_b128 v[220:223], v165 offset:2048
	ds_read_b128 v[224:227], v165 offset:3072
	s_waitcnt lgkmcnt(0)
	s_waitcnt vmcnt(8)
	s_setprio 1
	s_barrier
	v_mfma_f32_16x16x32_bf16 v[124:127], v[160:163], v[180:183], v[124:127]
	v_mfma_f32_16x16x32_bf16 v[116:119], v[170:173], v[180:183], v[116:119]
	v_mfma_f32_16x16x32_bf16 v[108:111], v[160:163], v[188:191], v[108:111]
	v_mfma_f32_16x16x32_bf16 v[100:103], v[170:173], v[188:191], v[100:103]
	v_mfma_f32_16x16x32_bf16 v[92:95], v[160:163], v[196:199], v[92:95]
	v_mfma_f32_16x16x32_bf16 v[84:87], v[170:173], v[196:199], v[84:87]
	v_mfma_f32_16x16x32_bf16 v[76:79], v[160:163], v[204:207], v[76:79]
	v_mfma_f32_16x16x32_bf16 v[68:71], v[170:173], v[204:207], v[68:71]
	v_mfma_f32_16x16x32_bf16 v[124:127], v[166:169], v[184:187], v[124:127]
	v_mfma_f32_16x16x32_bf16 v[116:119], v[174:177], v[184:187], v[116:119]
	v_mfma_f32_16x16x32_bf16 v[108:111], v[166:169], v[192:195], v[108:111]
	v_mfma_f32_16x16x32_bf16 v[100:103], v[174:177], v[192:195], v[100:103]
	v_mfma_f32_16x16x32_bf16 v[92:95], v[166:169], v[200:203], v[92:95]
	v_mfma_f32_16x16x32_bf16 v[84:87], v[174:177], v[200:203], v[84:87]
	v_mfma_f32_16x16x32_bf16 v[76:79], v[166:169], v[208:211], v[76:79]
	v_mfma_f32_16x16x32_bf16 v[68:71], v[174:177], v[208:211], v[68:71]
	v_mfma_f32_16x16x32_bf16 v[120:123], v[212:215], v[180:183], v[120:123]
	v_mfma_f32_16x16x32_bf16 v[112:115], v[220:223], v[180:183], v[112:115]
	v_mfma_f32_16x16x32_bf16 v[104:107], v[212:215], v[188:191], v[104:107]
	v_mfma_f32_16x16x32_bf16 v[96:99], v[220:223], v[188:191], v[96:99]
	v_mfma_f32_16x16x32_bf16 v[88:91], v[212:215], v[196:199], v[88:91]
	v_mfma_f32_16x16x32_bf16 v[80:83], v[220:223], v[196:199], v[80:83]
	v_mfma_f32_16x16x32_bf16 v[72:75], v[212:215], v[204:207], v[72:75]
	v_mfma_f32_16x16x32_bf16 v[64:67], v[220:223], v[204:207], v[64:67]
	v_mfma_f32_16x16x32_bf16 v[120:123], v[216:219], v[184:187], v[120:123]
	v_mfma_f32_16x16x32_bf16 v[112:115], v[224:227], v[184:187], v[112:115]
	v_mfma_f32_16x16x32_bf16 v[104:107], v[216:219], v[192:195], v[104:107]
	v_mfma_f32_16x16x32_bf16 v[96:99], v[224:227], v[192:195], v[96:99]
	v_mfma_f32_16x16x32_bf16 v[88:91], v[216:219], v[200:203], v[88:91]
	v_mfma_f32_16x16x32_bf16 v[80:83], v[224:227], v[200:203], v[80:83]
	v_mfma_f32_16x16x32_bf16 v[72:75], v[216:219], v[208:211], v[72:75]
	v_mfma_f32_16x16x32_bf16 v[64:67], v[224:227], v[208:211], v[64:67]
	s_barrier
; #define PG8_STAGE(bufoff, gbase, voff) do { _Pragma("unroll") for (int _i = 0; _i < 2; ++_i) \
;         __builtin_amdgcn_global_load_lds((const unsigned*)((const char*)(gbase) + (voff)[_i]), (LAS unsigned*)(lds + (bufoff) + ldsw + _i * 8192), 16, 0, 0); } while (0)
; #define PG8_LDA(dst, b, h) do { _Pragma("unroll") for (int m = 0; m < 4; ++m) _Pragma("unroll") for (int k = 0; k < 2; ++k) dst[m][k] = *(const LAS bf16x8*)(lds + PG8_SA(b, h) + aoff + m * 2048 + k * 1024); } while (0)
; #define PG8_LDB(dst, b, h) do { _Pragma("unroll") for (int n = 0; n < 2; ++n) _Pragma("unroll") for (int k = 0; k < 2; ++k) dst[n][k] = *(const LAS bf16x8*)(lds + PG8_SB(b, h) + boff + n * 2048 + k * 1024); } while (0)
; #define PG8_MMA(ai, bj, At, Bt) do { __builtin_amdgcn_s_setprio(1); _Pragma("unroll") for (int m = 0; m < 4; ++m) _Pragma("unroll") for (int n = 0; n < 2; ++n) _Pragma("unroll") for (int k = 0; k < 2; ++k) \
;         acc[ai][bj][m][n] = __builtin_amdgcn_mfma_f32_16x16x32_bf16(Bt[n][k], At[m][k], acc[ai][bj][m][n], 0, 0, 0); __builtin_amdgcn_s_setprio(0); } while (0)
; #define PG8_WAIT_V(n) asm volatile("s_waitcnt vmcnt(" #n ")" ::: "memory")
; #define PG8_WAIT_L(n) asm volatile("s_waitcnt lgkmcnt(" #n ")" ::: "memory")
; #define PG8_BAR __builtin_amdgcn_s_barrier()
; #define PG8_SCHED __builtin_amdgcn_sched_barrier(0)
; template <class Epi>
; __device__ __forceinline__ void gemm_phase(LAS unsigned char* lds, const Gemm g, const StaticOrder& S, const Epi& E) {
;     ...
;             PG8_LDB(B0, 1, 0); PG8_SCHED; PG8_LDA(At, 1, 0); PG8_STAGE(PG8_SA(0, 1), a2 + hstep, voffA);
;             PG8_WAIT_L(8); PG8_BAR; PG8_WAIT_L(0); PG8_MMA(0, 0, At, B0); PG8_BAR; PG8_SCHED;
;             PG8_LDB(B1, 1, 1); PG8_STAGE(PG8_SB(1, 0), b3, voffB);
;             PG8_BAR; PG8_WAIT_L(0); PG8_MMA(0, 1, At, B1); PG8_BAR;
;             PG8_LDA(At, 1, 1); PG8_STAGE(PG8_SA(1, 0), a3, voffA);
;             PG8_BAR; PG8_WAIT_L(0); PG8_MMA(1, 0, At, B0); PG8_BAR; PG8_SCHED;
;             PG8_STAGE(PG8_SB(1, 1), b3 + hstep, voffB);
;             PG8_WAIT_V(6); PG8_BAR; PG8_MMA(1, 1, At, B1); PG8_BAR;
	s_setprio 0
	s_add_i32 s21, s68, s31
	v_lshl_add_u64 v[228:229], v[228:229], 0, s[4:5]
	s_mov_b32 m0, s21
	s_nop 0
	global_load_lds_dwordx4 v[228:229], off
	v_lshl_add_u64 v[228:229], v[230:231], 0, s[4:5]
	s_add_i32 m0, s21, 0x2000
	s_nop 0
	global_load_lds_dwordx4 v[228:229], off
	s_mov_b32 m0, s56
	v_lshl_add_u64 v[228:229], v[232:233], 0, s[4:5]
	ds_read_b128 v[180:183], v149 offset:49152
	ds_read_b128 v[184:187], v149 offset:50176
	ds_read_b128 v[188:191], v149 offset:51200
	ds_read_b128 v[192:195], v149 offset:52224
	ds_read_b128 v[196:199], v149 offset:53248
	ds_read_b128 v[200:203], v149 offset:54272
	ds_read_b128 v[204:207], v149 offset:55296
	ds_read_b128 v[208:211], v149 offset:56320
	global_load_lds_dwordx4 v[228:229], off
	v_lshl_add_u64 v[228:229], v[234:235], 0, s[4:5]
	s_mov_b32 m0, s57
	s_nop 0
	global_load_lds_dwordx4 v[228:229], off
	s_add_u32 s18, s18, 0x80080
	s_addc_u32 s19, s19, 0
	s_add_i32 s20, s20, s31
	v_lshl_add_u64 v[252:253], s[18:19], 0, v[132:133]
	s_mov_b32 m0, s20
	s_nop 0
	global_load_lds_dwordx4 v[252:253], off
	v_lshl_add_u64 v[252:253], s[18:19], 0, v[128:129]
	s_add_i32 m0, s20, 0x2000
	s_nop 0
	global_load_lds_dwordx4 v[252:253], off
	s_waitcnt lgkmcnt(0)
	s_waitcnt vmcnt(8)
	s_setprio 1
	s_barrier
	v_mfma_f32_16x16x32_bf16 v[60:63], v[160:163], v[180:183], v[60:63]
	v_mfma_f32_16x16x32_bf16 v[52:55], v[170:173], v[180:183], v[52:55]
	v_mfma_f32_16x16x32_bf16 v[44:47], v[160:163], v[188:191], v[44:47]
	v_mfma_f32_16x16x32_bf16 v[36:39], v[170:173], v[188:191], v[36:39]
	v_mfma_f32_16x16x32_bf16 v[28:31], v[160:163], v[196:199], v[28:31]
	v_mfma_f32_16x16x32_bf16 v[20:23], v[170:173], v[196:199], v[20:23]
	v_mfma_f32_16x16x32_bf16 v[12:15], v[160:163], v[204:207], v[12:15]
	v_mfma_f32_16x16x32_bf16 v[4:7], v[170:173], v[204:207], v[4:7]
	v_mfma_f32_16x16x32_bf16 v[60:63], v[166:169], v[184:187], v[60:63]
	v_mfma_f32_16x16x32_bf16 v[52:55], v[174:177], v[184:187], v[52:55]
	v_mfma_f32_16x16x32_bf16 v[44:47], v[166:169], v[192:195], v[44:47]
	v_mfma_f32_16x16x32_bf16 v[36:39], v[174:177], v[192:195], v[36:39]
	v_mfma_f32_16x16x32_bf16 v[28:31], v[166:169], v[200:203], v[28:31]
	v_mfma_f32_16x16x32_bf16 v[20:23], v[174:177], v[200:203], v[20:23]
	v_mfma_f32_16x16x32_bf16 v[12:15], v[166:169], v[208:211], v[12:15]
	v_mfma_f32_16x16x32_bf16 v[4:7], v[174:177], v[208:211], v[4:7]
	v_mfma_f32_16x16x32_bf16 v[56:59], v[212:215], v[180:183], v[56:59]
	v_mfma_f32_16x16x32_bf16 v[48:51], v[220:223], v[180:183], v[48:51]
	v_mfma_f32_16x16x32_bf16 v[40:43], v[212:215], v[188:191], v[40:43]
	v_mfma_f32_16x16x32_bf16 v[32:35], v[220:223], v[188:191], v[32:35]
	v_mfma_f32_16x16x32_bf16 v[24:27], v[212:215], v[196:199], v[24:27]
	v_mfma_f32_16x16x32_bf16 v[16:19], v[220:223], v[196:199], v[16:19]
	v_mfma_f32_16x16x32_bf16 v[8:11], v[212:215], v[204:207], v[8:11]
	v_mfma_f32_16x16x32_bf16 v[0:3], v[220:223], v[204:207], v[0:3]
	v_mfma_f32_16x16x32_bf16 v[56:59], v[216:219], v[184:187], v[56:59]
	v_mfma_f32_16x16x32_bf16 v[48:51], v[224:227], v[184:187], v[48:51]
	v_mfma_f32_16x16x32_bf16 v[40:43], v[216:219], v[192:195], v[40:43]
	v_mfma_f32_16x16x32_bf16 v[32:35], v[224:227], v[192:195], v[32:35]
	v_mfma_f32_16x16x32_bf16 v[24:27], v[216:219], v[200:203], v[24:27]
	v_mfma_f32_16x16x32_bf16 v[16:19], v[224:227], v[200:203], v[16:19]
	v_mfma_f32_16x16x32_bf16 v[8:11], v[216:219], v[208:211], v[8:11]
	v_mfma_f32_16x16x32_bf16 v[0:3], v[224:227], v[208:211], v[0:3]
	s_barrier
	s_setprio 0
	s_add_i32 s67, s67, 2
	s_add_u32 s16, s16, 0x100
	s_addc_u32 s17, s17, 0
	s_add_u32 s65, s65, 0x100
	s_addc_u32 s66, s66, 0
	s_cmp_gt_u32 s67, 29
	.p2align	6

; #define PG8_STAGE(bufoff, gbase, voff) do { _Pragma("unroll") for (int _i = 0; _i < 2; ++_i) \
;         __builtin_amdgcn_global_load_lds((const unsigned*)((const char*)(gbase) + (voff)[_i]), (LAS unsigned*)(lds + (bufoff) + ldsw + _i * 8192), 16, 0, 0); } while (0)
; #define PG8_LDA(dst, b, h) do { _Pragma("unroll") for (int m = 0; m < 4; ++m) _Pragma("unroll") for (int k = 0; k < 2; ++k) dst[m][k] = *(const LAS bf16x8*)(lds + PG8_SA(b, h) + aoff + m * 2048 + k * 1024); } while (0)
; #define PG8_LDB(dst, b, h) do { _Pragma("unroll") for (int n = 0; n < 2; ++n) _Pragma("unroll") for (int k = 0; k < 2; ++k) dst[n][k] = *(const LAS bf16x8*)(lds + PG8_SB(b, h) + boff + n * 2048 + k * 1024); } while (0)
; template <class Epi>
; __device__ __forceinline__ void gemm_phase(LAS unsigned char* lds, const Gemm g, const StaticOrder& S, const Epi& E) {
;     ...
;     for (;;) {
;         const bool has_next = S.next(ui + 1, nxt);
;         const char* nA = has_next ? (const char*)g.A + (size_t)nxt.pm * tstep : cA; const char* nB = has_next ? (const char*)g.Bt + (size_t)nxt.pn * tstep : cB;
;         for (int t = 0; t < nt; t += 2) {
;             const bool last = (t == nt - 2);
;             const char* a1 = cA + (size_t)(t + 1) * kstep;
;             const char* a2 = last ? nA : cA + (size_t)(t + 2) * kstep; const char* b2 = last ? nB : cB + (size_t)(t + 2) * kstep;
;             const char* a3 = a2 + kstep; const char* b3 = b2 + kstep;
;             PG8_LDB(B0, 0, 0); PG8_SCHED; PG8_LDA(At, 0, 0); PG8_STAGE(PG8_SA(1, 1), a1 + hstep, voffA);
;             PG8_WAIT_L(8); PG8_BAR; PG8_WAIT_L(0); PG8_MMA(0, 0, At, B0); PG8_BAR; PG8_SCHED;
;             PG8_LDB(B1, 0, 1); PG8_STAGE(PG8_SB(0, 0), b2, voffB);
;             PG8_BAR; PG8_WAIT_L(0); PG8_MMA(0, 1, At, B1); PG8_BAR;
;             PG8_LDA(At, 0, 1); PG8_STAGE(PG8_SA(0, 0), a2, voffA);
;             PG8_BAR; PG8_WAIT_L(0); PG8_MMA(1, 0, At, B0); PG8_BAR; PG8_SCHED;
;             PG8_STAGE(PG8_SB(0, 1), b2 + hstep, voffB);
;             PG8_WAIT_V(6); PG8_BAR; PG8_MMA(1, 1, At, B1); PG8_BAR;
;     ...
; #pragma unroll
;         for (int a = 0; a < 2; ++a)
; #pragma unroll
;             for (int b = 0; b < 2; ++b)
; #pragma unroll
;                 for (int m = 0; m < 4; ++m)
; #pragma unroll
;                     for (int n = 0; n < 2; ++n) acc[a][b][m][n] = (f32x4){0.f, 0.f, 0.f, 0.f};
.LBB0_363:
	s_add_u32 s14, s14, 0x158080
	s_addc_u32 s15, s15, 0
	s_add_u32 s63, s16, 0x100
	s_addc_u32 s64, s17, 0
	s_mov_b32 s65, -2
	s_waitcnt lgkmcnt(0)
	ds_read_b128 v[128:131], v161
	ds_read_b128 v[132:135], v161 offset:1024
	ds_read_b128 v[152:155], v161 offset:2048
	ds_read_b128 v[166:169], v161 offset:3072
	s_add_u32 s16, s14, 0xffea8080
	s_addc_u32 s17, s15, -1
	s_cmpk_eq_i32 s65, 0x52
	s_cselect_b32 s19, s1, s17
	s_cselect_b32 s18, s0, s16
	s_cselect_b32 s17, s7, s64
	s_cselect_b32 s16, s6, s63
	v_lshl_add_u64 v[156:157], s[14:15], 0, v[144:145]
	s_add_i32 m0, s30, 0xc000
	ds_read_b128 v[170:173], v162
	ds_read_b128 v[174:177], v162 offset:1024
	ds_read_b128 v[180:183], v162 offset:2048
	ds_read_b128 v[184:187], v162 offset:3072
	ds_read_b128 v[188:191], v162 offset:4096
	ds_read_b128 v[192:195], v162 offset:5120
	ds_read_b128 v[196:199], v162 offset:6144
	ds_read_b128 v[200:203], v162 offset:7168
	global_load_lds_dwordx4 v[156:157], off
	v_lshl_add_u64 v[156:157], s[14:15], 0, v[146:147]
	s_add_i32 m0, s30, 0xe000
	s_nop 0
	global_load_lds_dwordx4 v[156:157], off
	ds_read_b128 v[204:207], v163
	ds_read_b128 v[208:211], v163 offset:1024
	ds_read_b128 v[212:215], v163 offset:2048
	ds_read_b128 v[216:219], v163 offset:3072
	s_waitcnt lgkmcnt(0)
	s_waitcnt vmcnt(8)
	s_setprio 1
	s_barrier
	v_mfma_f32_16x16x32_bf16 v[124:127], v[128:131], v[170:173], 0
	v_mfma_f32_16x16x32_bf16 v[120:123], v[152:155], v[170:173], 0
	v_mfma_f32_16x16x32_bf16 v[108:111], v[128:131], v[180:183], 0
	v_mfma_f32_16x16x32_bf16 v[104:107], v[152:155], v[180:183], 0
	v_mfma_f32_16x16x32_bf16 v[92:95], v[128:131], v[188:191], 0
	v_mfma_f32_16x16x32_bf16 v[88:91], v[152:155], v[188:191], 0
	v_mfma_f32_16x16x32_bf16 v[76:79], v[128:131], v[196:199], 0
	v_mfma_f32_16x16x32_bf16 v[72:75], v[152:155], v[196:199], 0
	v_mfma_f32_16x16x32_bf16 v[124:127], v[132:135], v[174:177], v[124:127]
	v_mfma_f32_16x16x32_bf16 v[120:123], v[166:169], v[174:177], v[120:123]
	v_mfma_f32_16x16x32_bf16 v[108:111], v[132:135], v[184:187], v[108:111]
	v_mfma_f32_16x16x32_bf16 v[104:107], v[166:169], v[184:187], v[104:107]
	v_mfma_f32_16x16x32_bf16 v[92:95], v[132:135], v[192:195], v[92:95]
	v_mfma_f32_16x16x32_bf16 v[88:91], v[166:169], v[192:195], v[88:91]
	v_mfma_f32_16x16x32_bf16 v[76:79], v[132:135], v[200:203], v[76:79]
	v_mfma_f32_16x16x32_bf16 v[72:75], v[166:169], v[200:203], v[72:75]
	v_mfma_f32_16x16x32_bf16 v[116:119], v[204:207], v[170:173], 0
	v_mfma_f32_16x16x32_bf16 v[112:115], v[212:215], v[170:173], 0
	v_mfma_f32_16x16x32_bf16 v[100:103], v[204:207], v[180:183], 0
	v_mfma_f32_16x16x32_bf16 v[96:99], v[212:215], v[180:183], 0
	v_mfma_f32_16x16x32_bf16 v[84:87], v[204:207], v[188:191], 0
	v_mfma_f32_16x16x32_bf16 v[80:83], v[212:215], v[188:191], 0
	v_mfma_f32_16x16x32_bf16 v[68:71], v[204:207], v[196:199], 0
	v_mfma_f32_16x16x32_bf16 v[64:67], v[212:215], v[196:199], 0
	v_mfma_f32_16x16x32_bf16 v[116:119], v[208:211], v[174:177], v[116:119]
	v_mfma_f32_16x16x32_bf16 v[112:115], v[216:219], v[174:177], v[112:115]
	v_mfma_f32_16x16x32_bf16 v[100:103], v[208:211], v[184:187], v[100:103]
	v_mfma_f32_16x16x32_bf16 v[96:99], v[216:219], v[184:187], v[96:99]
	v_mfma_f32_16x16x32_bf16 v[84:87], v[208:211], v[192:195], v[84:87]
	v_mfma_f32_16x16x32_bf16 v[80:83], v[216:219], v[192:195], v[80:83]
	v_mfma_f32_16x16x32_bf16 v[68:71], v[208:211], v[200:203], v[68:71]
	v_mfma_f32_16x16x32_bf16 v[64:67], v[216:219], v[200:203], v[64:67]
	s_barrier
	s_setprio 0
	s_add_i32 s66, s57, s21
	v_lshl_add_u64 v[156:157], s[16:17], 0, v[138:139]
	s_mov_b32 m0, s66
	s_nop 0
	global_load_lds_dwordx4 v[156:157], off
	v_lshl_add_u64 v[220:221], s[16:17], 0, v[142:143]
	s_add_i32 m0, s66, 0x2000
	s_nop 0
	global_load_lds_dwordx4 v[220:221], off
	s_mov_b32 m0, s30
	v_lshl_add_u64 v[222:223], s[18:19], 0, v[136:137]
	ds_read_b128 v[170:173], v162 offset:16384
	ds_read_b128 v[174:177], v162 offset:17408
	ds_read_b128 v[180:183], v162 offset:18432
	ds_read_b128 v[184:187], v162 offset:19456
	ds_read_b128 v[188:191], v162 offset:20480
	ds_read_b128 v[192:195], v162 offset:21504
	ds_read_b128 v[196:199], v162 offset:22528
	ds_read_b128 v[200:203], v162 offset:23552
	global_load_lds_dwordx4 v[222:223], off
	v_lshl_add_u64 v[224:225], s[18:19], 0, v[140:141]
	s_mov_b32 m0, s31
	s_nop 0
	global_load_lds_dwordx4 v[224:225], off
	s_add_u32 s66, s16, 0x158000
	s_addc_u32 s67, s17, 0
	s_add_i32 s68, s58, s21
	v_lshl_add_u64 v[252:253], s[66:67], 0, v[138:139]
	s_mov_b32 m0, s68
	s_nop 0
	global_load_lds_dwordx4 v[252:253], off
	v_lshl_add_u64 v[252:253], s[66:67], 0, v[142:143]
	s_add_i32 m0, s68, 0x2000
	s_nop 0
	global_load_lds_dwordx4 v[252:253], off
	s_waitcnt lgkmcnt(0)
	s_waitcnt vmcnt(8)
	s_setprio 1
	s_barrier
; #define PG8_STAGE(bufoff, gbase, voff) do { _Pragma("unroll") for (int _i = 0; _i < 2; ++_i) \
;         __builtin_amdgcn_global_load_lds((const unsigned*)((const char*)(gbase) + (voff)[_i]), (LAS unsigned*)(lds + (bufoff) + ldsw + _i * 8192), 16, 0, 0); } while (0)
; #define PG8_LDA(dst, b, h) do { _Pragma("unroll") for (int m = 0; m < 4; ++m) _Pragma("unroll") for (int k = 0; k < 2; ++k) dst[m][k] = *(const LAS bf16x8*)(lds + PG8_SA(b, h) + aoff + m * 2048 + k * 1024); } while (0)
; #define PG8_LDB(dst, b, h) do { _Pragma("unroll") for (int n = 0; n < 2; ++n) _Pragma("unroll") for (int k = 0; k < 2; ++k) dst[n][k] = *(const LAS bf16x8*)(lds + PG8_SB(b, h) + boff + n * 2048 + k * 1024); } while (0)
; #define PG8_WAIT_V(n) asm volatile("s_waitcnt vmcnt(" #n ")" ::: "memory")
; #define PG8_WAIT_L(n) asm volatile("s_waitcnt lgkmcnt(" #n ")" ::: "memory")
; #define PG8_BAR __builtin_amdgcn_s_barrier()
; #define PG8_SCHED __builtin_amdgcn_sched_barrier(0)
; template <class Epi>
; __device__ __forceinline__ void gemm_phase(LAS unsigned char* lds, const Gemm g, const StaticOrder& S, const Epi& E) {
;     ...
;             PG8_LDB(B0, 0, 0); PG8_SCHED; PG8_LDA(At, 0, 0); PG8_STAGE(PG8_SA(1, 1), a1 + hstep, voffA);
;             PG8_WAIT_L(8); PG8_BAR; PG8_WAIT_L(0); PG8_MMA(0, 0, At, B0); PG8_BAR; PG8_SCHED;
;             PG8_LDB(B1, 0, 1); PG8_STAGE(PG8_SB(0, 0), b2, voffB);
;             PG8_BAR; PG8_WAIT_L(0); PG8_MMA(0, 1, At, B1); PG8_BAR;
;             PG8_LDA(At, 0, 1); PG8_STAGE(PG8_SA(0, 0), a2, voffA);
;             PG8_BAR; PG8_WAIT_L(0); PG8_MMA(1, 0, At, B0); PG8_BAR; PG8_SCHED;
;             PG8_STAGE(PG8_SB(0, 1), b2 + hstep, voffB);
;             PG8_WAIT_V(6); PG8_BAR; PG8_MMA(1, 1, At, B1); PG8_BAR;
;             PG8_LDB(B0, 1, 0); PG8_SCHED; PG8_LDA(At, 1, 0); PG8_STAGE(PG8_SA(0, 1), a2 + hstep, voffA);
;             PG8_WAIT_L(8); PG8_BAR; PG8_WAIT_L(0); PG8_MMA(0, 0, At, B0); PG8_BAR; PG8_SCHED;
;             PG8_LDB(B1, 1, 1); PG8_STAGE(PG8_SB(1, 0), b3, voffB);
;             PG8_BAR; PG8_WAIT_L(0); PG8_MMA(0, 1, At, B1); PG8_BAR;
;             PG8_LDA(At, 1, 1); PG8_STAGE(PG8_SA(1, 0), a3, voffA);
;             PG8_BAR; PG8_WAIT_L(0); PG8_MMA(1, 0, At, B0); PG8_BAR; PG8_SCHED;
;             PG8_STAGE(PG8_SB(1, 1), b3 + hstep, voffB);
;             PG8_WAIT_V(6); PG8_BAR; PG8_MMA(1, 1, At, B1); PG8_BAR;
	v_mfma_f32_16x16x32_bf16 v[60:63], v[128:131], v[170:173], 0
	v_mfma_f32_16x16x32_bf16 v[56:59], v[152:155], v[170:173], 0
	v_mfma_f32_16x16x32_bf16 v[44:47], v[128:131], v[180:183], 0
	v_mfma_f32_16x16x32_bf16 v[40:43], v[152:155], v[180:183], 0
	v_mfma_f32_16x16x32_bf16 v[28:31], v[128:131], v[188:191], 0
	v_mfma_f32_16x16x32_bf16 v[24:27], v[152:155], v[188:191], 0
	v_mfma_f32_16x16x32_bf16 v[12:15], v[128:131], v[196:199], 0
	v_mfma_f32_16x16x32_bf16 v[8:11], v[152:155], v[196:199], 0
	v_mfma_f32_16x16x32_bf16 v[60:63], v[132:135], v[174:177], v[60:63]
	v_mfma_f32_16x16x32_bf16 v[56:59], v[166:169], v[174:177], v[56:59]
	v_mfma_f32_16x16x32_bf16 v[44:47], v[132:135], v[184:187], v[44:47]
	v_mfma_f32_16x16x32_bf16 v[40:43], v[166:169], v[184:187], v[40:43]
	v_mfma_f32_16x16x32_bf16 v[28:31], v[132:135], v[192:195], v[28:31]
	v_mfma_f32_16x16x32_bf16 v[24:27], v[166:169], v[192:195], v[24:27]
	v_mfma_f32_16x16x32_bf16 v[12:15], v[132:135], v[200:203], v[12:15]
	v_mfma_f32_16x16x32_bf16 v[8:11], v[166:169], v[200:203], v[8:11]
	v_mfma_f32_16x16x32_bf16 v[52:55], v[204:207], v[170:173], 0
	v_mfma_f32_16x16x32_bf16 v[48:51], v[212:215], v[170:173], 0
	v_mfma_f32_16x16x32_bf16 v[36:39], v[204:207], v[180:183], 0
	v_mfma_f32_16x16x32_bf16 v[32:35], v[212:215], v[180:183], 0
	v_mfma_f32_16x16x32_bf16 v[20:23], v[204:207], v[188:191], 0
	v_mfma_f32_16x16x32_bf16 v[16:19], v[212:215], v[188:191], 0
	v_mfma_f32_16x16x32_bf16 v[4:7], v[204:207], v[196:199], 0
	v_mfma_f32_16x16x32_bf16 v[0:3], v[212:215], v[196:199], 0
	v_mfma_f32_16x16x32_bf16 v[52:55], v[208:211], v[174:177], v[52:55]
	v_mfma_f32_16x16x32_bf16 v[48:51], v[216:219], v[174:177], v[48:51]
	v_mfma_f32_16x16x32_bf16 v[36:39], v[208:211], v[184:187], v[36:39]
	v_mfma_f32_16x16x32_bf16 v[32:35], v[216:219], v[184:187], v[32:35]
	v_mfma_f32_16x16x32_bf16 v[20:23], v[208:211], v[192:195], v[20:23]
	v_mfma_f32_16x16x32_bf16 v[16:19], v[216:219], v[192:195], v[16:19]
	v_mfma_f32_16x16x32_bf16 v[4:7], v[208:211], v[200:203], v[4:7]
	v_mfma_f32_16x16x32_bf16 v[0:3], v[216:219], v[200:203], v[0:3]
	s_barrier
	s_setprio 0
	s_add_i32 s66, 0, 0x18000
	v_add_u32_e32 v166, s66, v158
	ds_read_b128 v[128:131], v166
	ds_read_b128 v[132:135], v166 offset:1024
	ds_read_b128 v[152:155], v166 offset:2048
	ds_read_b128 v[166:169], v166 offset:3072
	s_add_u32 s18, s18, 0x158000
	s_addc_u32 s19, s19, 0
	s_mov_b32 m0, s33
	v_lshl_add_u64 v[204:205], s[18:19], 0, v[136:137]
	ds_read_b128 v[170:173], v162 offset:32768
	ds_read_b128 v[174:177], v162 offset:33792
	ds_read_b128 v[180:183], v162 offset:34816
	ds_read_b128 v[184:187], v162 offset:35840
	ds_read_b128 v[188:191], v162 offset:36864
	ds_read_b128 v[192:195], v162 offset:37888
	ds_read_b128 v[196:199], v162 offset:38912
	ds_read_b128 v[200:203], v162 offset:39936
	global_load_lds_dwordx4 v[204:205], off
	v_lshl_add_u64 v[204:205], s[18:19], 0, v[140:141]
	s_mov_b32 m0, s34
	s_nop 0
	global_load_lds_dwordx4 v[204:205], off
	s_add_i32 s18, 0, 0x1c000
	v_add_u32_e32 v179, s18, v158
	ds_read_b128 v[204:207], v179
	ds_read_b128 v[208:211], v179 offset:1024
	ds_read_b128 v[212:215], v179 offset:2048
	ds_read_b128 v[216:219], v179 offset:3072
	s_waitcnt lgkmcnt(0)
	s_waitcnt vmcnt(8)
	s_setprio 1
	s_barrier
	v_mfma_f32_16x16x32_bf16 v[124:127], v[128:131], v[170:173], v[124:127]
	v_mfma_f32_16x16x32_bf16 v[120:123], v[152:155], v[170:173], v[120:123]
	v_mfma_f32_16x16x32_bf16 v[108:111], v[128:131], v[180:183], v[108:111]
	v_mfma_f32_16x16x32_bf16 v[104:107], v[152:155], v[180:183], v[104:107]
	v_mfma_f32_16x16x32_bf16 v[92:95], v[128:131], v[188:191], v[92:95]
	v_mfma_f32_16x16x32_bf16 v[88:91], v[152:155], v[188:191], v[88:91]
	v_mfma_f32_16x16x32_bf16 v[76:79], v[128:131], v[196:199], v[76:79]
	v_mfma_f32_16x16x32_bf16 v[72:75], v[152:155], v[196:199], v[72:75]
	v_mfma_f32_16x16x32_bf16 v[124:127], v[132:135], v[174:177], v[124:127]
	v_mfma_f32_16x16x32_bf16 v[120:123], v[166:169], v[174:177], v[120:123]
	v_mfma_f32_16x16x32_bf16 v[108:111], v[132:135], v[184:187], v[108:111]
	v_mfma_f32_16x16x32_bf16 v[104:107], v[166:169], v[184:187], v[104:107]
	v_mfma_f32_16x16x32_bf16 v[92:95], v[132:135], v[192:195], v[92:95]
	v_mfma_f32_16x16x32_bf16 v[88:91], v[166:169], v[192:195], v[88:91]
	v_mfma_f32_16x16x32_bf16 v[76:79], v[132:135], v[200:203], v[76:79]
	v_mfma_f32_16x16x32_bf16 v[72:75], v[166:169], v[200:203], v[72:75]
	v_mfma_f32_16x16x32_bf16 v[116:119], v[204:207], v[170:173], v[116:119]
	v_mfma_f32_16x16x32_bf16 v[112:115], v[212:215], v[170:173], v[112:115]
	v_mfma_f32_16x16x32_bf16 v[100:103], v[204:207], v[180:183], v[100:103]
	v_mfma_f32_16x16x32_bf16 v[96:99], v[212:215], v[180:183], v[96:99]
	v_mfma_f32_16x16x32_bf16 v[84:87], v[204:207], v[188:191], v[84:87]
	v_mfma_f32_16x16x32_bf16 v[80:83], v[212:215], v[188:191], v[80:83]
	v_mfma_f32_16x16x32_bf16 v[68:71], v[204:207], v[196:199], v[68:71]
	v_mfma_f32_16x16x32_bf16 v[64:67], v[212:215], v[196:199], v[64:67]
	v_mfma_f32_16x16x32_bf16 v[116:119], v[208:211], v[174:177], v[116:119]
	v_mfma_f32_16x16x32_bf16 v[112:115], v[216:219], v[174:177], v[112:115]
	v_mfma_f32_16x16x32_bf16 v[100:103], v[208:211], v[184:187], v[100:103]
	v_mfma_f32_16x16x32_bf16 v[96:99], v[216:219], v[184:187], v[96:99]
	v_mfma_f32_16x16x32_bf16 v[84:87], v[208:211], v[192:195], v[84:87]
	v_mfma_f32_16x16x32_bf16 v[80:83], v[216:219], v[192:195], v[80:83]
	v_mfma_f32_16x16x32_bf16 v[68:71], v[208:211], v[200:203], v[68:71]
	v_mfma_f32_16x16x32_bf16 v[64:67], v[216:219], v[200:203], v[64:67]
	s_barrier
; #define PG8_STAGE(bufoff, gbase, voff) do { _Pragma("unroll") for (int _i = 0; _i < 2; ++_i) \
;         __builtin_amdgcn_global_load_lds((const unsigned*)((const char*)(gbase) + (voff)[_i]), (LAS unsigned*)(lds + (bufoff) + ldsw + _i * 8192), 16, 0, 0); } while (0)
; #define PG8_LDA(dst, b, h) do { _Pragma("unroll") for (int m = 0; m < 4; ++m) _Pragma("unroll") for (int k = 0; k < 2; ++k) dst[m][k] = *(const LAS bf16x8*)(lds + PG8_SA(b, h) + aoff + m * 2048 + k * 1024); } while (0)
; #define PG8_LDB(dst, b, h) do { _Pragma("unroll") for (int n = 0; n < 2; ++n) _Pragma("unroll") for (int k = 0; k < 2; ++k) dst[n][k] = *(const LAS bf16x8*)(lds + PG8_SB(b, h) + boff + n * 2048 + k * 1024); } while (0)
; #define PG8_MMA(ai, bj, At, Bt) do { __builtin_amdgcn_s_setprio(1); _Pragma("unroll") for (int m = 0; m < 4; ++m) _Pragma("unroll") for (int n = 0; n < 2; ++n) _Pragma("unroll") for (int k = 0; k < 2; ++k) \
;         acc[ai][bj][m][n] = __builtin_amdgcn_mfma_f32_16x16x32_bf16(Bt[n][k], At[m][k], acc[ai][bj][m][n], 0, 0, 0); __builtin_amdgcn_s_setprio(0); } while (0)
; #define PG8_WAIT_V(n) asm volatile("s_waitcnt vmcnt(" #n ")" ::: "memory")
; #define PG8_WAIT_L(n) asm volatile("s_waitcnt lgkmcnt(" #n ")" ::: "memory")
; #define PG8_BAR __builtin_amdgcn_s_barrier()
; #define PG8_SCHED __builtin_amdgcn_sched_barrier(0)
; template <class Epi>
; __device__ __forceinline__ void gemm_phase(LAS unsigned char* lds, const Gemm g, const StaticOrder& S, const Epi& E) {
;     ...
;             PG8_LDB(B0, 1, 0); PG8_SCHED; PG8_LDA(At, 1, 0); PG8_STAGE(PG8_SA(0, 1), a2 + hstep, voffA);
;             PG8_WAIT_L(8); PG8_BAR; PG8_WAIT_L(0); PG8_MMA(0, 0, At, B0); PG8_BAR; PG8_SCHED;
;             PG8_LDB(B1, 1, 1); PG8_STAGE(PG8_SB(1, 0), b3, voffB);
;             PG8_BAR; PG8_WAIT_L(0); PG8_MMA(0, 1, At, B1); PG8_BAR;
;             PG8_LDA(At, 1, 1); PG8_STAGE(PG8_SA(1, 0), a3, voffA);
;             PG8_BAR; PG8_WAIT_L(0); PG8_MMA(1, 0, At, B0); PG8_BAR; PG8_SCHED;
;             PG8_STAGE(PG8_SB(1, 1), b3 + hstep, voffB);
;             PG8_WAIT_V(6); PG8_BAR; PG8_MMA(1, 1, At, B1); PG8_BAR;
	s_setprio 0
	s_add_i32 s19, s66, s21
	v_lshl_add_u64 v[156:157], v[156:157], 0, s[12:13]
	s_mov_b32 m0, s19
	s_nop 0
	global_load_lds_dwordx4 v[156:157], off
	v_lshl_add_u64 v[156:157], v[220:221], 0, s[12:13]
	s_add_i32 m0, s19, 0x2000
	s_nop 0
	global_load_lds_dwordx4 v[156:157], off
	s_mov_b32 m0, s38
	v_lshl_add_u64 v[156:157], v[222:223], 0, s[12:13]
	ds_read_b128 v[170:173], v162 offset:49152
	ds_read_b128 v[174:177], v162 offset:50176
	ds_read_b128 v[180:183], v162 offset:51200
	ds_read_b128 v[184:187], v162 offset:52224
	ds_read_b128 v[188:191], v162 offset:53248
	ds_read_b128 v[192:195], v162 offset:54272
	ds_read_b128 v[196:199], v162 offset:55296
	ds_read_b128 v[200:203], v162 offset:56320
	global_load_lds_dwordx4 v[156:157], off
	v_lshl_add_u64 v[156:157], v[224:225], 0, s[12:13]
	s_mov_b32 m0, s39
	s_nop 0
	global_load_lds_dwordx4 v[156:157], off
	s_add_u32 s16, s16, 0x158080
	s_addc_u32 s17, s17, 0
	s_add_i32 s18, s18, s21
	v_lshl_add_u64 v[252:253], s[16:17], 0, v[138:139]
	s_mov_b32 m0, s18
	s_nop 0
	global_load_lds_dwordx4 v[252:253], off
	v_lshl_add_u64 v[252:253], s[16:17], 0, v[142:143]
	s_add_i32 m0, s18, 0x2000
	s_nop 0
	global_load_lds_dwordx4 v[252:253], off
	s_waitcnt lgkmcnt(0)
	s_waitcnt vmcnt(8)
	s_setprio 1
	s_barrier
	v_mfma_f32_16x16x32_bf16 v[60:63], v[128:131], v[170:173], v[60:63]
	v_mfma_f32_16x16x32_bf16 v[56:59], v[152:155], v[170:173], v[56:59]
	v_mfma_f32_16x16x32_bf16 v[44:47], v[128:131], v[180:183], v[44:47]
	v_mfma_f32_16x16x32_bf16 v[40:43], v[152:155], v[180:183], v[40:43]
	v_mfma_f32_16x16x32_bf16 v[28:31], v[128:131], v[188:191], v[28:31]
	v_mfma_f32_16x16x32_bf16 v[24:27], v[152:155], v[188:191], v[24:27]
	v_mfma_f32_16x16x32_bf16 v[12:15], v[128:131], v[196:199], v[12:15]
	v_mfma_f32_16x16x32_bf16 v[8:11], v[152:155], v[196:199], v[8:11]
	v_mfma_f32_16x16x32_bf16 v[60:63], v[132:135], v[174:177], v[60:63]
	v_mfma_f32_16x16x32_bf16 v[56:59], v[166:169], v[174:177], v[56:59]
	v_mfma_f32_16x16x32_bf16 v[44:47], v[132:135], v[184:187], v[44:47]
	v_mfma_f32_16x16x32_bf16 v[40:43], v[166:169], v[184:187], v[40:43]
	v_mfma_f32_16x16x32_bf16 v[28:31], v[132:135], v[192:195], v[28:31]
	v_mfma_f32_16x16x32_bf16 v[24:27], v[166:169], v[192:195], v[24:27]
	v_mfma_f32_16x16x32_bf16 v[12:15], v[132:135], v[200:203], v[12:15]
	v_mfma_f32_16x16x32_bf16 v[8:11], v[166:169], v[200:203], v[8:11]
	v_mfma_f32_16x16x32_bf16 v[52:55], v[204:207], v[170:173], v[52:55]
	v_mfma_f32_16x16x32_bf16 v[48:51], v[212:215], v[170:173], v[48:51]
	v_mfma_f32_16x16x32_bf16 v[36:39], v[204:207], v[180:183], v[36:39]
	v_mfma_f32_16x16x32_bf16 v[32:35], v[212:215], v[180:183], v[32:35]
	v_mfma_f32_16x16x32_bf16 v[20:23], v[204:207], v[188:191], v[20:23]
	v_mfma_f32_16x16x32_bf16 v[16:19], v[212:215], v[188:191], v[16:19]
	v_mfma_f32_16x16x32_bf16 v[4:7], v[204:207], v[196:199], v[4:7]
	v_mfma_f32_16x16x32_bf16 v[0:3], v[212:215], v[196:199], v[0:3]
	v_mfma_f32_16x16x32_bf16 v[52:55], v[208:211], v[174:177], v[52:55]
	v_mfma_f32_16x16x32_bf16 v[48:51], v[216:219], v[174:177], v[48:51]
	v_mfma_f32_16x16x32_bf16 v[36:39], v[208:211], v[184:187], v[36:39]
	v_mfma_f32_16x16x32_bf16 v[32:35], v[216:219], v[184:187], v[32:35]
	v_mfma_f32_16x16x32_bf16 v[20:23], v[208:211], v[192:195], v[20:23]
	v_mfma_f32_16x16x32_bf16 v[16:19], v[216:219], v[192:195], v[16:19]
	v_mfma_f32_16x16x32_bf16 v[4:7], v[208:211], v[200:203], v[4:7]
	v_mfma_f32_16x16x32_bf16 v[0:3], v[216:219], v[200:203], v[0:3]
	s_barrier
	s_setprio 0
	s_add_i32 s65, s65, 2
	s_add_u32 s14, s14, 0x100
	s_addc_u32 s15, s15, 0
	s_add_u32 s63, s63, 0x100
	s_addc_u32 s64, s64, 0
	s_cmpk_gt_u32 s65, 0x53
	.p2align	6

; #define PG8_STAGE(bufoff, gbase, voff) do { _Pragma("unroll") for (int _i = 0; _i < 2; ++_i) \
;         __builtin_amdgcn_global_load_lds((const unsigned*)((const char*)(gbase) + (voff)[_i]), (LAS unsigned*)(lds + (bufoff) + ldsw + _i * 8192), 16, 0, 0); } while (0)
; #define PG8_LDA(dst, b, h) do { _Pragma("unroll") for (int m = 0; m < 4; ++m) _Pragma("unroll") for (int k = 0; k < 2; ++k) dst[m][k] = *(const LAS bf16x8*)(lds + PG8_SA(b, h) + aoff + m * 2048 + k * 1024); } while (0)
; #define PG8_LDB(dst, b, h) do { _Pragma("unroll") for (int n = 0; n < 2; ++n) _Pragma("unroll") for (int k = 0; k < 2; ++k) dst[n][k] = *(const LAS bf16x8*)(lds + PG8_SB(b, h) + boff + n * 2048 + k * 1024); } while (0)
; template <class Epi>
; __device__ __forceinline__ void gemm_phase(LAS unsigned char* lds, const Gemm g, const StaticOrder& S, const Epi& E) {
;     ...
;     for (;;) {
;         const bool has_next = S.next(ui + 1, nxt);
;         const char* nA = has_next ? (const char*)g.A + (size_t)nxt.pm * tstep : cA; const char* nB = has_next ? (const char*)g.Bt + (size_t)nxt.pn * tstep : cB;
;         for (int t = 0; t < nt; t += 2) {
;             const bool last = (t == nt - 2);
;             const char* a1 = cA + (size_t)(t + 1) * kstep;
;             const char* a2 = last ? nA : cA + (size_t)(t + 2) * kstep; const char* b2 = last ? nB : cB + (size_t)(t + 2) * kstep;
;             const char* a3 = a2 + kstep; const char* b3 = b2 + kstep;
;             PG8_LDB(B0, 0, 0); PG8_SCHED; PG8_LDA(At, 0, 0); PG8_STAGE(PG8_SA(1, 1), a1 + hstep, voffA);
;             PG8_WAIT_L(8); PG8_BAR; PG8_WAIT_L(0); PG8_MMA(0, 0, At, B0); PG8_BAR; PG8_SCHED;
;             PG8_LDB(B1, 0, 1); PG8_STAGE(PG8_SB(0, 0), b2, voffB);
;             PG8_BAR; PG8_WAIT_L(0); PG8_MMA(0, 1, At, B1); PG8_BAR;
;             PG8_LDA(At, 0, 1); PG8_STAGE(PG8_SA(0, 0), a2, voffA);
;             PG8_BAR; PG8_WAIT_L(0); PG8_MMA(1, 0, At, B0); PG8_BAR; PG8_SCHED;
;             PG8_STAGE(PG8_SB(0, 1), b2 + hstep, voffB);
;             PG8_WAIT_V(6); PG8_BAR; PG8_MMA(1, 1, At, B1); PG8_BAR;
;     ...
; #pragma unroll
;         for (int a = 0; a < 2; ++a)
; #pragma unroll
;             for (int b = 0; b < 2; ++b)
; #pragma unroll
;                 for (int m = 0; m < 4; ++m)
; #pragma unroll
;                     for (int n = 0; n < 2; ++n) acc[a][b][m][n] = (f32x4){0.f, 0.f, 0.f, 0.f};
.LBB0_690:
	s_ashr_i32 s63, s62, 31
	s_lshl_b64 s[10:11], s[62:63], 20
	s_add_u32 s64, s70, s10
	v_cmp_lt_i64_e64 s[2:3], s[2:3], v[144:145]
	s_addc_u32 s65, s71, s11
	s_and_b64 s[10:11], s[2:3], exec
	s_cselect_b32 s1, s65, s7
	s_cselect_b32 s5, s64, s6
	s_ashr_i32 s61, s60, 31
	s_lshl_b64 s[10:11], s[60:61], 20
	s_add_u32 s66, s72, s10
	s_addc_u32 s67, s73, s11
	s_and_b64 s[10:11], s[2:3], exec
	s_cselect_b32 s12, s67, s9
	s_cselect_b32 s13, s66, s8
	s_add_u32 s6, s6, 0x80080
	s_addc_u32 s7, s7, 0
	s_add_u32 s33, s8, 0x100
	s_addc_u32 s61, s9, 0
	s_mov_b32 s63, -2
	s_waitcnt vmcnt(0)
	ds_read_b128 v[150:153], v167
	ds_read_b128 v[154:157], v167 offset:1024
	ds_read_b128 v[158:161], v167 offset:2048
	ds_read_b128 v[180:183], v167 offset:3072
	s_add_u32 s8, s6, 0xfff80080
	s_addc_u32 s9, s7, -1
	s_cmp_eq_u32 s63, 28
	s_cselect_b32 s11, s1, s9
	s_cselect_b32 s10, s5, s8
	s_cselect_b32 s9, s12, s61
	s_cselect_b32 s8, s13, s33
	v_lshl_add_u64 v[162:163], s[6:7], 0, v[140:141]
	s_add_i32 m0, s74, 0xc000
	ds_read_b128 v[184:187], v168
	ds_read_b128 v[188:191], v168 offset:1024
	ds_read_b128 v[192:195], v168 offset:2048
	ds_read_b128 v[196:199], v168 offset:3072
	ds_read_b128 v[200:203], v168 offset:4096
	ds_read_b128 v[204:207], v168 offset:5120
	ds_read_b128 v[208:211], v168 offset:6144
	ds_read_b128 v[212:215], v168 offset:7168
	global_load_lds_dwordx4 v[162:163], off
	v_lshl_add_u64 v[162:163], s[6:7], 0, v[142:143]
	s_add_i32 m0, s74, 0xe000
	s_nop 0
	global_load_lds_dwordx4 v[162:163], off
	ds_read_b128 v[216:219], v169
	ds_read_b128 v[220:223], v169 offset:1024
	ds_read_b128 v[224:227], v169 offset:2048
	ds_read_b128 v[228:231], v169 offset:3072
	s_waitcnt lgkmcnt(0)
	s_waitcnt vmcnt(8)
	s_setprio 1
	s_barrier
	v_mfma_f32_16x16x32_bf16 v[124:127], v[150:153], v[184:187], 0
	v_mfma_f32_16x16x32_bf16 v[120:123], v[158:161], v[184:187], 0
	v_mfma_f32_16x16x32_bf16 v[108:111], v[150:153], v[192:195], 0
	v_mfma_f32_16x16x32_bf16 v[104:107], v[158:161], v[192:195], 0
	v_mfma_f32_16x16x32_bf16 v[92:95], v[150:153], v[200:203], 0
	v_mfma_f32_16x16x32_bf16 v[88:91], v[158:161], v[200:203], 0
	v_mfma_f32_16x16x32_bf16 v[76:79], v[150:153], v[208:211], 0
	v_mfma_f32_16x16x32_bf16 v[72:75], v[158:161], v[208:211], 0
	v_mfma_f32_16x16x32_bf16 v[124:127], v[154:157], v[188:191], v[124:127]
	v_mfma_f32_16x16x32_bf16 v[120:123], v[180:183], v[188:191], v[120:123]
	v_mfma_f32_16x16x32_bf16 v[108:111], v[154:157], v[196:199], v[108:111]
	v_mfma_f32_16x16x32_bf16 v[104:107], v[180:183], v[196:199], v[104:107]
	v_mfma_f32_16x16x32_bf16 v[92:95], v[154:157], v[204:207], v[92:95]
	v_mfma_f32_16x16x32_bf16 v[88:91], v[180:183], v[204:207], v[88:91]
	v_mfma_f32_16x16x32_bf16 v[76:79], v[154:157], v[212:215], v[76:79]
	v_mfma_f32_16x16x32_bf16 v[72:75], v[180:183], v[212:215], v[72:75]
	v_mfma_f32_16x16x32_bf16 v[116:119], v[216:219], v[184:187], 0
	v_mfma_f32_16x16x32_bf16 v[112:115], v[224:227], v[184:187], 0
	v_mfma_f32_16x16x32_bf16 v[100:103], v[216:219], v[192:195], 0
	v_mfma_f32_16x16x32_bf16 v[96:99], v[224:227], v[192:195], 0
	v_mfma_f32_16x16x32_bf16 v[84:87], v[216:219], v[200:203], 0
	v_mfma_f32_16x16x32_bf16 v[80:83], v[224:227], v[200:203], 0
	v_mfma_f32_16x16x32_bf16 v[68:71], v[216:219], v[208:211], 0
	v_mfma_f32_16x16x32_bf16 v[64:67], v[224:227], v[208:211], 0
	v_mfma_f32_16x16x32_bf16 v[116:119], v[220:223], v[188:191], v[116:119]
	v_mfma_f32_16x16x32_bf16 v[112:115], v[228:231], v[188:191], v[112:115]
	v_mfma_f32_16x16x32_bf16 v[100:103], v[220:223], v[196:199], v[100:103]
	v_mfma_f32_16x16x32_bf16 v[96:99], v[228:231], v[196:199], v[96:99]
	v_mfma_f32_16x16x32_bf16 v[84:87], v[220:223], v[204:207], v[84:87]
	v_mfma_f32_16x16x32_bf16 v[80:83], v[228:231], v[204:207], v[80:83]
	v_mfma_f32_16x16x32_bf16 v[68:71], v[220:223], v[212:215], v[68:71]
	v_mfma_f32_16x16x32_bf16 v[64:67], v[228:231], v[212:215], v[64:67]
	s_barrier
	s_setprio 0
	s_add_i32 s89, s84, s69
	v_lshl_add_u64 v[162:163], s[8:9], 0, v[130:131]
	s_mov_b32 m0, s89
	s_nop 0
	global_load_lds_dwordx4 v[162:163], off
	v_lshl_add_u64 v[232:233], s[8:9], 0, v[134:135]
	s_add_i32 m0, s89, 0x2000
	s_nop 0
	global_load_lds_dwordx4 v[232:233], off
	s_mov_b32 m0, s74
	v_lshl_add_u64 v[234:235], s[10:11], 0, v[128:129]
	ds_read_b128 v[184:187], v168 offset:16384
	ds_read_b128 v[188:191], v168 offset:17408
	ds_read_b128 v[192:195], v168 offset:18432
	ds_read_b128 v[196:199], v168 offset:19456
	ds_read_b128 v[200:203], v168 offset:20480
	ds_read_b128 v[204:207], v168 offset:21504
	ds_read_b128 v[208:211], v168 offset:22528
	ds_read_b128 v[212:215], v168 offset:23552
	global_load_lds_dwordx4 v[234:235], off
	v_lshl_add_u64 v[236:237], s[10:11], 0, v[132:133]
	s_mov_b32 m0, s75
	s_nop 0
	global_load_lds_dwordx4 v[236:237], off
	s_add_u32 s90, s8, 0x80000
	s_addc_u32 s91, s9, 0
	s_add_i32 s89, s85, s69
	v_lshl_add_u64 v[252:253], s[90:91], 0, v[130:131]
	s_mov_b32 m0, s89
	s_nop 0
	global_load_lds_dwordx4 v[252:253], off
	v_lshl_add_u64 v[252:253], s[90:91], 0, v[134:135]
	s_add_i32 m0, s89, 0x2000
	s_nop 0
	global_load_lds_dwordx4 v[252:253], off
	s_waitcnt lgkmcnt(0)
	s_waitcnt vmcnt(8)
	s_setprio 1
	s_barrier
; #define PG8_STAGE(bufoff, gbase, voff) do { _Pragma("unroll") for (int _i = 0; _i < 2; ++_i) \
;         __builtin_amdgcn_global_load_lds((const unsigned*)((const char*)(gbase) + (voff)[_i]), (LAS unsigned*)(lds + (bufoff) + ldsw + _i * 8192), 16, 0, 0); } while (0)
; #define PG8_LDA(dst, b, h) do { _Pragma("unroll") for (int m = 0; m < 4; ++m) _Pragma("unroll") for (int k = 0; k < 2; ++k) dst[m][k] = *(const LAS bf16x8*)(lds + PG8_SA(b, h) + aoff + m * 2048 + k * 1024); } while (0)
; #define PG8_LDB(dst, b, h) do { _Pragma("unroll") for (int n = 0; n < 2; ++n) _Pragma("unroll") for (int k = 0; k < 2; ++k) dst[n][k] = *(const LAS bf16x8*)(lds + PG8_SB(b, h) + boff + n * 2048 + k * 1024); } while (0)
; #define PG8_WAIT_V(n) asm volatile("s_waitcnt vmcnt(" #n ")" ::: "memory")
; #define PG8_WAIT_L(n) asm volatile("s_waitcnt lgkmcnt(" #n ")" ::: "memory")
; #define PG8_BAR __builtin_amdgcn_s_barrier()
; #define PG8_SCHED __builtin_amdgcn_sched_barrier(0)
; template <class Epi>
; __device__ __forceinline__ void gemm_phase(LAS unsigned char* lds, const Gemm g, const StaticOrder& S, const Epi& E) {
;     ...
;             PG8_LDB(B0, 0, 0); PG8_SCHED; PG8_LDA(At, 0, 0); PG8_STAGE(PG8_SA(1, 1), a1 + hstep, voffA);
;             PG8_WAIT_L(8); PG8_BAR; PG8_WAIT_L(0); PG8_MMA(0, 0, At, B0); PG8_BAR; PG8_SCHED;
;             PG8_LDB(B1, 0, 1); PG8_STAGE(PG8_SB(0, 0), b2, voffB);
;             PG8_BAR; PG8_WAIT_L(0); PG8_MMA(0, 1, At, B1); PG8_BAR;
;             PG8_LDA(At, 0, 1); PG8_STAGE(PG8_SA(0, 0), a2, voffA);
;             PG8_BAR; PG8_WAIT_L(0); PG8_MMA(1, 0, At, B0); PG8_BAR; PG8_SCHED;
;             PG8_STAGE(PG8_SB(0, 1), b2 + hstep, voffB);
;             PG8_WAIT_V(6); PG8_BAR; PG8_MMA(1, 1, At, B1); PG8_BAR;
;             PG8_LDB(B0, 1, 0); PG8_SCHED; PG8_LDA(At, 1, 0); PG8_STAGE(PG8_SA(0, 1), a2 + hstep, voffA);
;             PG8_WAIT_L(8); PG8_BAR; PG8_WAIT_L(0); PG8_MMA(0, 0, At, B0); PG8_BAR; PG8_SCHED;
;             PG8_LDB(B1, 1, 1); PG8_STAGE(PG8_SB(1, 0), b3, voffB);
;             PG8_BAR; PG8_WAIT_L(0); PG8_MMA(0, 1, At, B1); PG8_BAR;
;             PG8_LDA(At, 1, 1); PG8_STAGE(PG8_SA(1, 0), a3, voffA);
;             PG8_BAR; PG8_WAIT_L(0); PG8_MMA(1, 0, At, B0); PG8_BAR; PG8_SCHED;
;             PG8_STAGE(PG8_SB(1, 1), b3 + hstep, voffB);
;             PG8_WAIT_V(6); PG8_BAR; PG8_MMA(1, 1, At, B1); PG8_BAR;
	v_mfma_f32_16x16x32_bf16 v[60:63], v[150:153], v[184:187], 0
	v_mfma_f32_16x16x32_bf16 v[56:59], v[158:161], v[184:187], 0
	v_mfma_f32_16x16x32_bf16 v[44:47], v[150:153], v[192:195], 0
	v_mfma_f32_16x16x32_bf16 v[40:43], v[158:161], v[192:195], 0
	v_mfma_f32_16x16x32_bf16 v[28:31], v[150:153], v[200:203], 0
	v_mfma_f32_16x16x32_bf16 v[24:27], v[158:161], v[200:203], 0
	v_mfma_f32_16x16x32_bf16 v[12:15], v[150:153], v[208:211], 0
	v_mfma_f32_16x16x32_bf16 v[8:11], v[158:161], v[208:211], 0
	v_mfma_f32_16x16x32_bf16 v[60:63], v[154:157], v[188:191], v[60:63]
	v_mfma_f32_16x16x32_bf16 v[56:59], v[180:183], v[188:191], v[56:59]
	v_mfma_f32_16x16x32_bf16 v[44:47], v[154:157], v[196:199], v[44:47]
	v_mfma_f32_16x16x32_bf16 v[40:43], v[180:183], v[196:199], v[40:43]
	v_mfma_f32_16x16x32_bf16 v[28:31], v[154:157], v[204:207], v[28:31]
	v_mfma_f32_16x16x32_bf16 v[24:27], v[180:183], v[204:207], v[24:27]
	v_mfma_f32_16x16x32_bf16 v[12:15], v[154:157], v[212:215], v[12:15]
	v_mfma_f32_16x16x32_bf16 v[8:11], v[180:183], v[212:215], v[8:11]
	v_mfma_f32_16x16x32_bf16 v[52:55], v[216:219], v[184:187], 0
	v_mfma_f32_16x16x32_bf16 v[48:51], v[224:227], v[184:187], 0
	v_mfma_f32_16x16x32_bf16 v[36:39], v[216:219], v[192:195], 0
	v_mfma_f32_16x16x32_bf16 v[32:35], v[224:227], v[192:195], 0
	v_mfma_f32_16x16x32_bf16 v[20:23], v[216:219], v[200:203], 0
	v_mfma_f32_16x16x32_bf16 v[16:19], v[224:227], v[200:203], 0
	v_mfma_f32_16x16x32_bf16 v[4:7], v[216:219], v[208:211], 0
	v_mfma_f32_16x16x32_bf16 v[0:3], v[224:227], v[208:211], 0
	v_mfma_f32_16x16x32_bf16 v[52:55], v[220:223], v[188:191], v[52:55]
	v_mfma_f32_16x16x32_bf16 v[48:51], v[228:231], v[188:191], v[48:51]
	v_mfma_f32_16x16x32_bf16 v[36:39], v[220:223], v[196:199], v[36:39]
	v_mfma_f32_16x16x32_bf16 v[32:35], v[228:231], v[196:199], v[32:35]
	v_mfma_f32_16x16x32_bf16 v[20:23], v[220:223], v[204:207], v[20:23]
	v_mfma_f32_16x16x32_bf16 v[16:19], v[228:231], v[204:207], v[16:19]
	v_mfma_f32_16x16x32_bf16 v[4:7], v[220:223], v[212:215], v[4:7]
	v_mfma_f32_16x16x32_bf16 v[0:3], v[228:231], v[212:215], v[0:3]
	s_barrier
	s_setprio 0
	s_add_i32 s89, 0, 0x18000
	v_add_u32_e32 v138, s89, v165
	ds_read_b128 v[150:153], v138
	ds_read_b128 v[154:157], v138 offset:1024
	ds_read_b128 v[158:161], v138 offset:2048
	ds_read_b128 v[180:183], v138 offset:3072
	s_add_u32 s10, s10, 0x80000
	s_addc_u32 s11, s11, 0
	s_mov_b32 m0, s76
	v_lshl_add_u64 v[216:217], s[10:11], 0, v[128:129]
	ds_read_b128 v[184:187], v168 offset:32768
	ds_read_b128 v[188:191], v168 offset:33792
	ds_read_b128 v[192:195], v168 offset:34816
	ds_read_b128 v[196:199], v168 offset:35840
	ds_read_b128 v[200:203], v168 offset:36864
	ds_read_b128 v[204:207], v168 offset:37888
	ds_read_b128 v[208:211], v168 offset:38912
	ds_read_b128 v[212:215], v168 offset:39936
	global_load_lds_dwordx4 v[216:217], off
	v_lshl_add_u64 v[216:217], s[10:11], 0, v[132:133]
	s_mov_b32 m0, s77
	s_nop 0
	global_load_lds_dwordx4 v[216:217], off
	s_add_i32 s10, 0, 0x1c000
	v_add_u32_e32 v138, s10, v165
	ds_read_b128 v[216:219], v138
	ds_read_b128 v[220:223], v138 offset:1024
	ds_read_b128 v[224:227], v138 offset:2048
	ds_read_b128 v[228:231], v138 offset:3072
	s_waitcnt lgkmcnt(0)
	s_waitcnt vmcnt(8)
	s_setprio 1
	s_barrier
	v_mfma_f32_16x16x32_bf16 v[124:127], v[150:153], v[184:187], v[124:127]
	v_mfma_f32_16x16x32_bf16 v[120:123], v[158:161], v[184:187], v[120:123]
	v_mfma_f32_16x16x32_bf16 v[108:111], v[150:153], v[192:195], v[108:111]
	v_mfma_f32_16x16x32_bf16 v[104:107], v[158:161], v[192:195], v[104:107]
	v_mfma_f32_16x16x32_bf16 v[92:95], v[150:153], v[200:203], v[92:95]
	v_mfma_f32_16x16x32_bf16 v[88:91], v[158:161], v[200:203], v[88:91]
	v_mfma_f32_16x16x32_bf16 v[76:79], v[150:153], v[208:211], v[76:79]
	v_mfma_f32_16x16x32_bf16 v[72:75], v[158:161], v[208:211], v[72:75]
	v_mfma_f32_16x16x32_bf16 v[124:127], v[154:157], v[188:191], v[124:127]
	v_mfma_f32_16x16x32_bf16 v[120:123], v[180:183], v[188:191], v[120:123]
	v_mfma_f32_16x16x32_bf16 v[108:111], v[154:157], v[196:199], v[108:111]
	v_mfma_f32_16x16x32_bf16 v[104:107], v[180:183], v[196:199], v[104:107]
	v_mfma_f32_16x16x32_bf16 v[92:95], v[154:157], v[204:207], v[92:95]
	v_mfma_f32_16x16x32_bf16 v[88:91], v[180:183], v[204:207], v[88:91]
	v_mfma_f32_16x16x32_bf16 v[76:79], v[154:157], v[212:215], v[76:79]
	v_mfma_f32_16x16x32_bf16 v[72:75], v[180:183], v[212:215], v[72:75]
	v_mfma_f32_16x16x32_bf16 v[116:119], v[216:219], v[184:187], v[116:119]
	v_mfma_f32_16x16x32_bf16 v[112:115], v[224:227], v[184:187], v[112:115]
	v_mfma_f32_16x16x32_bf16 v[100:103], v[216:219], v[192:195], v[100:103]
	v_mfma_f32_16x16x32_bf16 v[96:99], v[224:227], v[192:195], v[96:99]
	v_mfma_f32_16x16x32_bf16 v[84:87], v[216:219], v[200:203], v[84:87]
	v_mfma_f32_16x16x32_bf16 v[80:83], v[224:227], v[200:203], v[80:83]
	v_mfma_f32_16x16x32_bf16 v[68:71], v[216:219], v[208:211], v[68:71]
	v_mfma_f32_16x16x32_bf16 v[64:67], v[224:227], v[208:211], v[64:67]
	v_mfma_f32_16x16x32_bf16 v[116:119], v[220:223], v[188:191], v[116:119]
	v_mfma_f32_16x16x32_bf16 v[112:115], v[228:231], v[188:191], v[112:115]
	v_mfma_f32_16x16x32_bf16 v[100:103], v[220:223], v[196:199], v[100:103]
	v_mfma_f32_16x16x32_bf16 v[96:99], v[228:231], v[196:199], v[96:99]
	v_mfma_f32_16x16x32_bf16 v[84:87], v[220:223], v[204:207], v[84:87]
	v_mfma_f32_16x16x32_bf16 v[80:83], v[228:231], v[204:207], v[80:83]
	v_mfma_f32_16x16x32_bf16 v[68:71], v[220:223], v[212:215], v[68:71]
	v_mfma_f32_16x16x32_bf16 v[64:67], v[228:231], v[212:215], v[64:67]
	s_barrier
; #define PG8_STAGE(bufoff, gbase, voff) do { _Pragma("unroll") for (int _i = 0; _i < 2; ++_i) \
;         __builtin_amdgcn_global_load_lds((const unsigned*)((const char*)(gbase) + (voff)[_i]), (LAS unsigned*)(lds + (bufoff) + ldsw + _i * 8192), 16, 0, 0); } while (0)
; #define PG8_LDA(dst, b, h) do { _Pragma("unroll") for (int m = 0; m < 4; ++m) _Pragma("unroll") for (int k = 0; k < 2; ++k) dst[m][k] = *(const LAS bf16x8*)(lds + PG8_SA(b, h) + aoff + m * 2048 + k * 1024); } while (0)
; #define PG8_LDB(dst, b, h) do { _Pragma("unroll") for (int n = 0; n < 2; ++n) _Pragma("unroll") for (int k = 0; k < 2; ++k) dst[n][k] = *(const LAS bf16x8*)(lds + PG8_SB(b, h) + boff + n * 2048 + k * 1024); } while (0)
; #define PG8_MMA(ai, bj, At, Bt) do { __builtin_amdgcn_s_setprio(1); _Pragma("unroll") for (int m = 0; m < 4; ++m) _Pragma("unroll") for (int n = 0; n < 2; ++n) _Pragma("unroll") for (int k = 0; k < 2; ++k) \
;         acc[ai][bj][m][n] = __builtin_amdgcn_mfma_f32_16x16x32_bf16(Bt[n][k], At[m][k], acc[ai][bj][m][n], 0, 0, 0); __builtin_amdgcn_s_setprio(0); } while (0)
; #define PG8_WAIT_V(n) asm volatile("s_waitcnt vmcnt(" #n ")" ::: "memory")
; #define PG8_WAIT_L(n) asm volatile("s_waitcnt lgkmcnt(" #n ")" ::: "memory")
; #define PG8_BAR __builtin_amdgcn_s_barrier()
; #define PG8_SCHED __builtin_amdgcn_sched_barrier(0)
; template <class Epi>
; __device__ __forceinline__ void gemm_phase(LAS unsigned char* lds, const Gemm g, const StaticOrder& S, const Epi& E) {
;     ...
;             PG8_LDB(B0, 1, 0); PG8_SCHED; PG8_LDA(At, 1, 0); PG8_STAGE(PG8_SA(0, 1), a2 + hstep, voffA);
;             PG8_WAIT_L(8); PG8_BAR; PG8_WAIT_L(0); PG8_MMA(0, 0, At, B0); PG8_BAR; PG8_SCHED;
;             PG8_LDB(B1, 1, 1); PG8_STAGE(PG8_SB(1, 0), b3, voffB);
;             PG8_BAR; PG8_WAIT_L(0); PG8_MMA(0, 1, At, B1); PG8_BAR;
;             PG8_LDA(At, 1, 1); PG8_STAGE(PG8_SA(1, 0), a3, voffA);
;             PG8_BAR; PG8_WAIT_L(0); PG8_MMA(1, 0, At, B0); PG8_BAR; PG8_SCHED;
;             PG8_STAGE(PG8_SB(1, 1), b3 + hstep, voffB);
;             PG8_WAIT_V(6); PG8_BAR; PG8_MMA(1, 1, At, B1); PG8_BAR;
	s_setprio 0
	s_add_i32 s11, s89, s69
	v_lshl_add_u64 v[162:163], v[162:163], 0, s[34:35]
	s_mov_b32 m0, s11
	s_nop 0
	global_load_lds_dwordx4 v[162:163], off
	v_lshl_add_u64 v[162:163], v[232:233], 0, s[34:35]
	s_add_i32 m0, s11, 0x2000
	s_nop 0
	global_load_lds_dwordx4 v[162:163], off
	s_mov_b32 m0, s79
	v_lshl_add_u64 v[162:163], v[234:235], 0, s[34:35]
	ds_read_b128 v[184:187], v168 offset:49152
	ds_read_b128 v[188:191], v168 offset:50176
	ds_read_b128 v[192:195], v168 offset:51200
	ds_read_b128 v[196:199], v168 offset:52224
	ds_read_b128 v[200:203], v168 offset:53248
	ds_read_b128 v[204:207], v168 offset:54272
	ds_read_b128 v[208:211], v168 offset:55296
	ds_read_b128 v[212:215], v168 offset:56320
	global_load_lds_dwordx4 v[162:163], off
	v_lshl_add_u64 v[162:163], v[236:237], 0, s[34:35]
	s_mov_b32 m0, s80
	s_nop 0
	global_load_lds_dwordx4 v[162:163], off
	s_add_u32 s8, s8, 0x80080
	s_addc_u32 s9, s9, 0
	s_add_i32 s10, s10, s69
	v_lshl_add_u64 v[252:253], s[8:9], 0, v[130:131]
	s_mov_b32 m0, s10
	s_nop 0
	global_load_lds_dwordx4 v[252:253], off
	v_lshl_add_u64 v[252:253], s[8:9], 0, v[134:135]
	s_add_i32 m0, s10, 0x2000
	s_nop 0
	global_load_lds_dwordx4 v[252:253], off
	s_waitcnt lgkmcnt(0)
	s_waitcnt vmcnt(8)
	s_setprio 1
	s_barrier
	v_mfma_f32_16x16x32_bf16 v[60:63], v[150:153], v[184:187], v[60:63]
	v_mfma_f32_16x16x32_bf16 v[56:59], v[158:161], v[184:187], v[56:59]
	v_mfma_f32_16x16x32_bf16 v[44:47], v[150:153], v[192:195], v[44:47]
	v_mfma_f32_16x16x32_bf16 v[40:43], v[158:161], v[192:195], v[40:43]
	v_mfma_f32_16x16x32_bf16 v[28:31], v[150:153], v[200:203], v[28:31]
	v_mfma_f32_16x16x32_bf16 v[24:27], v[158:161], v[200:203], v[24:27]
	v_mfma_f32_16x16x32_bf16 v[12:15], v[150:153], v[208:211], v[12:15]
	v_mfma_f32_16x16x32_bf16 v[8:11], v[158:161], v[208:211], v[8:11]
	v_mfma_f32_16x16x32_bf16 v[60:63], v[154:157], v[188:191], v[60:63]
	v_mfma_f32_16x16x32_bf16 v[56:59], v[180:183], v[188:191], v[56:59]
	v_mfma_f32_16x16x32_bf16 v[44:47], v[154:157], v[196:199], v[44:47]
	v_mfma_f32_16x16x32_bf16 v[40:43], v[180:183], v[196:199], v[40:43]
	v_mfma_f32_16x16x32_bf16 v[28:31], v[154:157], v[204:207], v[28:31]
	v_mfma_f32_16x16x32_bf16 v[24:27], v[180:183], v[204:207], v[24:27]
	v_mfma_f32_16x16x32_bf16 v[12:15], v[154:157], v[212:215], v[12:15]
	v_mfma_f32_16x16x32_bf16 v[8:11], v[180:183], v[212:215], v[8:11]
	v_mfma_f32_16x16x32_bf16 v[52:55], v[216:219], v[184:187], v[52:55]
	v_mfma_f32_16x16x32_bf16 v[48:51], v[224:227], v[184:187], v[48:51]
	v_mfma_f32_16x16x32_bf16 v[36:39], v[216:219], v[192:195], v[36:39]
	v_mfma_f32_16x16x32_bf16 v[32:35], v[224:227], v[192:195], v[32:35]
	v_mfma_f32_16x16x32_bf16 v[20:23], v[216:219], v[200:203], v[20:23]
	v_mfma_f32_16x16x32_bf16 v[16:19], v[224:227], v[200:203], v[16:19]
	v_mfma_f32_16x16x32_bf16 v[4:7], v[216:219], v[208:211], v[4:7]
	v_mfma_f32_16x16x32_bf16 v[0:3], v[224:227], v[208:211], v[0:3]
	v_mfma_f32_16x16x32_bf16 v[52:55], v[220:223], v[188:191], v[52:55]
	v_mfma_f32_16x16x32_bf16 v[48:51], v[228:231], v[188:191], v[48:51]
	v_mfma_f32_16x16x32_bf16 v[36:39], v[220:223], v[196:199], v[36:39]
	v_mfma_f32_16x16x32_bf16 v[32:35], v[228:231], v[196:199], v[32:35]
	v_mfma_f32_16x16x32_bf16 v[20:23], v[220:223], v[204:207], v[20:23]
	v_mfma_f32_16x16x32_bf16 v[16:19], v[228:231], v[204:207], v[16:19]
	v_mfma_f32_16x16x32_bf16 v[4:7], v[220:223], v[212:215], v[4:7]
	v_mfma_f32_16x16x32_bf16 v[0:3], v[228:231], v[212:215], v[0:3]
	s_barrier
	s_setprio 0
	s_add_i32 s63, s63, 2
	s_add_u32 s6, s6, 0x100
	s_addc_u32 s7, s7, 0
	s_add_u32 s33, s33, 0x100
	s_addc_u32 s61, s61, 0
	s_cmp_gt_u32 s63, 29
	.p2align	6

; #define PG8_STAGE(bufoff, gbase, voff) do { _Pragma("unroll") for (int _i = 0; _i < 2; ++_i) \
;         __builtin_amdgcn_global_load_lds((const unsigned*)((const char*)(gbase) + (voff)[_i]), (LAS unsigned*)(lds + (bufoff) + ldsw + _i * 8192), 16, 0, 0); } while (0)
; #define PG8_LDA(dst, b, h) do { _Pragma("unroll") for (int m = 0; m < 4; ++m) _Pragma("unroll") for (int k = 0; k < 2; ++k) dst[m][k] = *(const LAS bf16x8*)(lds + PG8_SA(b, h) + aoff + m * 2048 + k * 1024); } while (0)
; #define PG8_LDB(dst, b, h) do { _Pragma("unroll") for (int n = 0; n < 2; ++n) _Pragma("unroll") for (int k = 0; k < 2; ++k) dst[n][k] = *(const LAS bf16x8*)(lds + PG8_SB(b, h) + boff + n * 2048 + k * 1024); } while (0)
; template <class Epi>
; __device__ __forceinline__ void gemm_phase(LAS unsigned char* lds, const Gemm g, const StaticOrder& S, const Epi& E) {
;     ...
;     for (;;) {
;         const bool has_next = S.next(ui + 1, nxt);
;         const char* nA = has_next ? (const char*)g.A + (size_t)nxt.pm * tstep : cA; const char* nB = has_next ? (const char*)g.Bt + (size_t)nxt.pn * tstep : cB;
;         for (int t = 0; t < nt; t += 2) {
;             const bool last = (t == nt - 2);
;             const char* a1 = cA + (size_t)(t + 1) * kstep;
;             const char* a2 = last ? nA : cA + (size_t)(t + 2) * kstep; const char* b2 = last ? nB : cB + (size_t)(t + 2) * kstep;
;             const char* a3 = a2 + kstep; const char* b3 = b2 + kstep;
;             PG8_LDB(B0, 0, 0); PG8_SCHED; PG8_LDA(At, 0, 0); PG8_STAGE(PG8_SA(1, 1), a1 + hstep, voffA);
;             PG8_WAIT_L(8); PG8_BAR; PG8_WAIT_L(0); PG8_MMA(0, 0, At, B0); PG8_BAR; PG8_SCHED;
;             PG8_LDB(B1, 0, 1); PG8_STAGE(PG8_SB(0, 0), b2, voffB);
;             PG8_BAR; PG8_WAIT_L(0); PG8_MMA(0, 1, At, B1); PG8_BAR;
;             PG8_LDA(At, 0, 1); PG8_STAGE(PG8_SA(0, 0), a2, voffA);
;             PG8_BAR; PG8_WAIT_L(0); PG8_MMA(1, 0, At, B0); PG8_BAR; PG8_SCHED;
;             PG8_STAGE(PG8_SB(0, 1), b2 + hstep, voffB);
;             PG8_WAIT_V(6); PG8_BAR; PG8_MMA(1, 1, At, B1); PG8_BAR;
;     ...
; #pragma unroll
;         for (int a = 0; a < 2; ++a)
; #pragma unroll
;             for (int b = 0; b < 2; ++b)
; #pragma unroll
;                 for (int m = 0; m < 4; ++m)
; #pragma unroll
;                     for (int n = 0; n < 2; ++n) acc[a][b][m][n] = (f32x4){0.f, 0.f, 0.f, 0.f};
.LBB0_1219:
	s_ashr_i32 s13, s12, 31
	v_cmp_lt_i64_e32 vcc, s[14:15], v[150:151]
	s_lshl_b64 s[14:15], s[12:13], 20
	s_add_u32 s14, s34, s14
	s_addc_u32 s15, s35, s15
	s_and_b64 s[16:17], vcc, exec
	s_cselect_b32 s13, s15, s23
	s_cselect_b32 s19, s14, s22
	s_ashr_i32 s11, s10, 31
	s_lshl_b64 s[16:17], s[10:11], 20
	s_add_u32 s16, s37, s16
	s_addc_u32 s17, s38, s17
	s_and_b64 s[30:31], vcc, exec
	s_cselect_b32 s11, s17, s25
	s_cselect_b32 s64, s16, s24
	s_add_u32 s22, s22, 0x80080
	s_addc_u32 s23, s23, 0
	s_add_u32 s65, s24, 0x100
	s_addc_u32 s66, s25, 0
	s_mov_b32 s67, -2
	s_waitcnt lgkmcnt(0)
	ds_read_b128 v[128:131], v162
	ds_read_b128 v[132:135], v162 offset:1024
	ds_read_b128 v[154:157], v162 offset:2048
	ds_read_b128 v[168:171], v162 offset:3072
	s_add_u32 s24, s22, 0xfff80080
	s_addc_u32 s25, s23, -1
	s_cmp_eq_u32 s67, 28
	s_cselect_b32 s31, s13, s25
	s_cselect_b32 s30, s19, s24
	s_cselect_b32 s25, s11, s66
	s_cselect_b32 s24, s64, s65
	v_lshl_add_u64 v[158:159], s[22:23], 0, v[146:147]
	s_add_i32 m0, s21, 0xc000
	ds_read_b128 v[172:175], v163
	ds_read_b128 v[180:183], v163 offset:1024
	ds_read_b128 v[184:187], v163 offset:2048
	ds_read_b128 v[188:191], v163 offset:3072
	ds_read_b128 v[192:195], v163 offset:4096
	ds_read_b128 v[196:199], v163 offset:5120
	ds_read_b128 v[200:203], v163 offset:6144
	ds_read_b128 v[204:207], v163 offset:7168
	global_load_lds_dwordx4 v[158:159], off
	v_lshl_add_u64 v[158:159], s[22:23], 0, v[148:149]
	s_add_i32 m0, s21, 0xe000
	s_nop 0
	global_load_lds_dwordx4 v[158:159], off
	ds_read_b128 v[208:211], v165
	ds_read_b128 v[212:215], v165 offset:1024
	ds_read_b128 v[216:219], v165 offset:2048
	ds_read_b128 v[220:223], v165 offset:3072
	s_waitcnt lgkmcnt(0)
	s_waitcnt vmcnt(8)
	s_setprio 1
	s_barrier
	v_mfma_f32_16x16x32_bf16 v[124:127], v[128:131], v[172:175], 0
	v_mfma_f32_16x16x32_bf16 v[120:123], v[154:157], v[172:175], 0
	v_mfma_f32_16x16x32_bf16 v[108:111], v[128:131], v[184:187], 0
	v_mfma_f32_16x16x32_bf16 v[104:107], v[154:157], v[184:187], 0
	v_mfma_f32_16x16x32_bf16 v[92:95], v[128:131], v[192:195], 0
	v_mfma_f32_16x16x32_bf16 v[88:91], v[154:157], v[192:195], 0
	v_mfma_f32_16x16x32_bf16 v[76:79], v[128:131], v[200:203], 0
	v_mfma_f32_16x16x32_bf16 v[72:75], v[154:157], v[200:203], 0
	v_mfma_f32_16x16x32_bf16 v[124:127], v[132:135], v[180:183], v[124:127]
	v_mfma_f32_16x16x32_bf16 v[120:123], v[168:171], v[180:183], v[120:123]
	v_mfma_f32_16x16x32_bf16 v[108:111], v[132:135], v[188:191], v[108:111]
	v_mfma_f32_16x16x32_bf16 v[104:107], v[168:171], v[188:191], v[104:107]
	v_mfma_f32_16x16x32_bf16 v[92:95], v[132:135], v[196:199], v[92:95]
	v_mfma_f32_16x16x32_bf16 v[88:91], v[168:171], v[196:199], v[88:91]
	v_mfma_f32_16x16x32_bf16 v[76:79], v[132:135], v[204:207], v[76:79]
	v_mfma_f32_16x16x32_bf16 v[72:75], v[168:171], v[204:207], v[72:75]
	v_mfma_f32_16x16x32_bf16 v[116:119], v[208:211], v[172:175], 0
	v_mfma_f32_16x16x32_bf16 v[112:115], v[216:219], v[172:175], 0
	v_mfma_f32_16x16x32_bf16 v[100:103], v[208:211], v[184:187], 0
	v_mfma_f32_16x16x32_bf16 v[96:99], v[216:219], v[184:187], 0
	v_mfma_f32_16x16x32_bf16 v[84:87], v[208:211], v[192:195], 0
	v_mfma_f32_16x16x32_bf16 v[80:83], v[216:219], v[192:195], 0
	v_mfma_f32_16x16x32_bf16 v[68:71], v[208:211], v[200:203], 0
	v_mfma_f32_16x16x32_bf16 v[64:67], v[216:219], v[200:203], 0
	v_mfma_f32_16x16x32_bf16 v[116:119], v[212:215], v[180:183], v[116:119]
	v_mfma_f32_16x16x32_bf16 v[112:115], v[220:223], v[180:183], v[112:115]
	v_mfma_f32_16x16x32_bf16 v[100:103], v[212:215], v[188:191], v[100:103]
	v_mfma_f32_16x16x32_bf16 v[96:99], v[220:223], v[188:191], v[96:99]
	v_mfma_f32_16x16x32_bf16 v[84:87], v[212:215], v[196:199], v[84:87]
	v_mfma_f32_16x16x32_bf16 v[80:83], v[220:223], v[196:199], v[80:83]
	v_mfma_f32_16x16x32_bf16 v[68:71], v[212:215], v[204:207], v[68:71]
	v_mfma_f32_16x16x32_bf16 v[64:67], v[220:223], v[204:207], v[64:67]
	s_barrier
	s_setprio 0
	s_add_i32 s68, s62, s36
	v_lshl_add_u64 v[158:159], s[24:25], 0, v[140:141]
	s_mov_b32 m0, s68
	s_nop 0
	global_load_lds_dwordx4 v[158:159], off
	v_lshl_add_u64 v[176:177], s[24:25], 0, v[144:145]
	s_add_i32 m0, s68, 0x2000
	s_nop 0
	global_load_lds_dwordx4 v[176:177], off
	s_mov_b32 m0, s21
	v_lshl_add_u64 v[224:225], s[30:31], 0, v[138:139]
	ds_read_b128 v[172:175], v163 offset:16384
	ds_read_b128 v[180:183], v163 offset:17408
	ds_read_b128 v[184:187], v163 offset:18432
	ds_read_b128 v[188:191], v163 offset:19456
	ds_read_b128 v[192:195], v163 offset:20480
	ds_read_b128 v[196:199], v163 offset:21504
	ds_read_b128 v[200:203], v163 offset:22528
	ds_read_b128 v[204:207], v163 offset:23552
	global_load_lds_dwordx4 v[224:225], off
	v_lshl_add_u64 v[226:227], s[30:31], 0, v[142:143]
	s_mov_b32 m0, s39
	s_nop 0
	global_load_lds_dwordx4 v[226:227], off
	s_add_u32 s68, s24, 0x80000
	s_addc_u32 s69, s25, 0
	s_add_i32 s70, s63, s36
	v_lshl_add_u64 v[252:253], s[68:69], 0, v[140:141]
	s_mov_b32 m0, s70
	s_nop 0
	global_load_lds_dwordx4 v[252:253], off
	v_lshl_add_u64 v[252:253], s[68:69], 0, v[144:145]
	s_add_i32 m0, s70, 0x2000
	s_nop 0
	global_load_lds_dwordx4 v[252:253], off
	s_waitcnt lgkmcnt(0)
	s_waitcnt vmcnt(8)
	s_setprio 1
	s_barrier
; #define PG8_STAGE(bufoff, gbase, voff) do { _Pragma("unroll") for (int _i = 0; _i < 2; ++_i) \
;         __builtin_amdgcn_global_load_lds((const unsigned*)((const char*)(gbase) + (voff)[_i]), (LAS unsigned*)(lds + (bufoff) + ldsw + _i * 8192), 16, 0, 0); } while (0)
; #define PG8_LDA(dst, b, h) do { _Pragma("unroll") for (int m = 0; m < 4; ++m) _Pragma("unroll") for (int k = 0; k < 2; ++k) dst[m][k] = *(const LAS bf16x8*)(lds + PG8_SA(b, h) + aoff + m * 2048 + k * 1024); } while (0)
; #define PG8_LDB(dst, b, h) do { _Pragma("unroll") for (int n = 0; n < 2; ++n) _Pragma("unroll") for (int k = 0; k < 2; ++k) dst[n][k] = *(const LAS bf16x8*)(lds + PG8_SB(b, h) + boff + n * 2048 + k * 1024); } while (0)
; #define PG8_WAIT_V(n) asm volatile("s_waitcnt vmcnt(" #n ")" ::: "memory")
; #define PG8_WAIT_L(n) asm volatile("s_waitcnt lgkmcnt(" #n ")" ::: "memory")
; #define PG8_BAR __builtin_amdgcn_s_barrier()
; #define PG8_SCHED __builtin_amdgcn_sched_barrier(0)
; template <class Epi>
; __device__ __forceinline__ void gemm_phase(LAS unsigned char* lds, const Gemm g, const StaticOrder& S, const Epi& E) {
;     ...
;             PG8_LDB(B0, 0, 0); PG8_SCHED; PG8_LDA(At, 0, 0); PG8_STAGE(PG8_SA(1, 1), a1 + hstep, voffA);
;             PG8_WAIT_L(8); PG8_BAR; PG8_WAIT_L(0); PG8_MMA(0, 0, At, B0); PG8_BAR; PG8_SCHED;
;             PG8_LDB(B1, 0, 1); PG8_STAGE(PG8_SB(0, 0), b2, voffB);
;             PG8_BAR; PG8_WAIT_L(0); PG8_MMA(0, 1, At, B1); PG8_BAR;
;             PG8_LDA(At, 0, 1); PG8_STAGE(PG8_SA(0, 0), a2, voffA);
;             PG8_BAR; PG8_WAIT_L(0); PG8_MMA(1, 0, At, B0); PG8_BAR; PG8_SCHED;
;             PG8_STAGE(PG8_SB(0, 1), b2 + hstep, voffB);
;             PG8_WAIT_V(6); PG8_BAR; PG8_MMA(1, 1, At, B1); PG8_BAR;
;             PG8_LDB(B0, 1, 0); PG8_SCHED; PG8_LDA(At, 1, 0); PG8_STAGE(PG8_SA(0, 1), a2 + hstep, voffA);
;             PG8_WAIT_L(8); PG8_BAR; PG8_WAIT_L(0); PG8_MMA(0, 0, At, B0); PG8_BAR; PG8_SCHED;
;             PG8_LDB(B1, 1, 1); PG8_STAGE(PG8_SB(1, 0), b3, voffB);
;             PG8_BAR; PG8_WAIT_L(0); PG8_MMA(0, 1, At, B1); PG8_BAR;
;             PG8_LDA(At, 1, 1); PG8_STAGE(PG8_SA(1, 0), a3, voffA);
;             PG8_BAR; PG8_WAIT_L(0); PG8_MMA(1, 0, At, B0); PG8_BAR; PG8_SCHED;
;             PG8_STAGE(PG8_SB(1, 1), b3 + hstep, voffB);
;             PG8_WAIT_V(6); PG8_BAR; PG8_MMA(1, 1, At, B1); PG8_BAR;
	v_mfma_f32_16x16x32_bf16 v[60:63], v[128:131], v[172:175], 0
	v_mfma_f32_16x16x32_bf16 v[56:59], v[154:157], v[172:175], 0
	v_mfma_f32_16x16x32_bf16 v[44:47], v[128:131], v[184:187], 0
	v_mfma_f32_16x16x32_bf16 v[40:43], v[154:157], v[184:187], 0
	v_mfma_f32_16x16x32_bf16 v[28:31], v[128:131], v[192:195], 0
	v_mfma_f32_16x16x32_bf16 v[24:27], v[154:157], v[192:195], 0
	v_mfma_f32_16x16x32_bf16 v[12:15], v[128:131], v[200:203], 0
	v_mfma_f32_16x16x32_bf16 v[8:11], v[154:157], v[200:203], 0
	v_mfma_f32_16x16x32_bf16 v[60:63], v[132:135], v[180:183], v[60:63]
	v_mfma_f32_16x16x32_bf16 v[56:59], v[168:171], v[180:183], v[56:59]
	v_mfma_f32_16x16x32_bf16 v[44:47], v[132:135], v[188:191], v[44:47]
	v_mfma_f32_16x16x32_bf16 v[40:43], v[168:171], v[188:191], v[40:43]
	v_mfma_f32_16x16x32_bf16 v[28:31], v[132:135], v[196:199], v[28:31]
	v_mfma_f32_16x16x32_bf16 v[24:27], v[168:171], v[196:199], v[24:27]
	v_mfma_f32_16x16x32_bf16 v[12:15], v[132:135], v[204:207], v[12:15]
	v_mfma_f32_16x16x32_bf16 v[8:11], v[168:171], v[204:207], v[8:11]
	v_mfma_f32_16x16x32_bf16 v[52:55], v[208:211], v[172:175], 0
	v_mfma_f32_16x16x32_bf16 v[48:51], v[216:219], v[172:175], 0
	v_mfma_f32_16x16x32_bf16 v[36:39], v[208:211], v[184:187], 0
	v_mfma_f32_16x16x32_bf16 v[32:35], v[216:219], v[184:187], 0
	v_mfma_f32_16x16x32_bf16 v[20:23], v[208:211], v[192:195], 0
	v_mfma_f32_16x16x32_bf16 v[16:19], v[216:219], v[192:195], 0
	v_mfma_f32_16x16x32_bf16 v[4:7], v[208:211], v[200:203], 0
	v_mfma_f32_16x16x32_bf16 v[0:3], v[216:219], v[200:203], 0
	v_mfma_f32_16x16x32_bf16 v[52:55], v[212:215], v[180:183], v[52:55]
	v_mfma_f32_16x16x32_bf16 v[48:51], v[220:223], v[180:183], v[48:51]
	v_mfma_f32_16x16x32_bf16 v[36:39], v[212:215], v[188:191], v[36:39]
	v_mfma_f32_16x16x32_bf16 v[32:35], v[220:223], v[188:191], v[32:35]
	v_mfma_f32_16x16x32_bf16 v[20:23], v[212:215], v[196:199], v[20:23]
	v_mfma_f32_16x16x32_bf16 v[16:19], v[220:223], v[196:199], v[16:19]
	v_mfma_f32_16x16x32_bf16 v[4:7], v[212:215], v[204:207], v[4:7]
	v_mfma_f32_16x16x32_bf16 v[0:3], v[220:223], v[204:207], v[0:3]
	s_barrier
	s_setprio 0
	s_add_i32 s68, 0, 0x18000
	v_add_u32_e32 v167, s68, v137
	ds_read_b128 v[128:131], v167
	ds_read_b128 v[132:135], v167 offset:1024
	ds_read_b128 v[154:157], v167 offset:2048
	ds_read_b128 v[168:171], v167 offset:3072
	s_add_u32 s30, s30, 0x80000
	s_addc_u32 s31, s31, 0
	s_mov_b32 m0, s42
	v_lshl_add_u64 v[208:209], s[30:31], 0, v[138:139]
	ds_read_b128 v[172:175], v163 offset:32768
	ds_read_b128 v[180:183], v163 offset:33792
	ds_read_b128 v[184:187], v163 offset:34816
	ds_read_b128 v[188:191], v163 offset:35840
	ds_read_b128 v[192:195], v163 offset:36864
	ds_read_b128 v[196:199], v163 offset:37888
	ds_read_b128 v[200:203], v163 offset:38912
	ds_read_b128 v[204:207], v163 offset:39936
	global_load_lds_dwordx4 v[208:209], off
	v_lshl_add_u64 v[208:209], s[30:31], 0, v[142:143]
	s_mov_b32 m0, s43
	s_nop 0
	global_load_lds_dwordx4 v[208:209], off
	s_add_i32 s30, 0, 0x1c000
	v_add_u32_e32 v167, s30, v137
	ds_read_b128 v[208:211], v167
	ds_read_b128 v[212:215], v167 offset:1024
	ds_read_b128 v[216:219], v167 offset:2048
	ds_read_b128 v[220:223], v167 offset:3072
	s_waitcnt lgkmcnt(0)
	s_waitcnt vmcnt(8)
	s_setprio 1
	s_barrier
	v_mfma_f32_16x16x32_bf16 v[124:127], v[128:131], v[172:175], v[124:127]
	v_mfma_f32_16x16x32_bf16 v[120:123], v[154:157], v[172:175], v[120:123]
	v_mfma_f32_16x16x32_bf16 v[108:111], v[128:131], v[184:187], v[108:111]
	v_mfma_f32_16x16x32_bf16 v[104:107], v[154:157], v[184:187], v[104:107]
	v_mfma_f32_16x16x32_bf16 v[92:95], v[128:131], v[192:195], v[92:95]
	v_mfma_f32_16x16x32_bf16 v[88:91], v[154:157], v[192:195], v[88:91]
	v_mfma_f32_16x16x32_bf16 v[76:79], v[128:131], v[200:203], v[76:79]
	v_mfma_f32_16x16x32_bf16 v[72:75], v[154:157], v[200:203], v[72:75]
	v_mfma_f32_16x16x32_bf16 v[124:127], v[132:135], v[180:183], v[124:127]
	v_mfma_f32_16x16x32_bf16 v[120:123], v[168:171], v[180:183], v[120:123]
	v_mfma_f32_16x16x32_bf16 v[108:111], v[132:135], v[188:191], v[108:111]
	v_mfma_f32_16x16x32_bf16 v[104:107], v[168:171], v[188:191], v[104:107]
	v_mfma_f32_16x16x32_bf16 v[92:95], v[132:135], v[196:199], v[92:95]
	v_mfma_f32_16x16x32_bf16 v[88:91], v[168:171], v[196:199], v[88:91]
	v_mfma_f32_16x16x32_bf16 v[76:79], v[132:135], v[204:207], v[76:79]
	v_mfma_f32_16x16x32_bf16 v[72:75], v[168:171], v[204:207], v[72:75]
	v_mfma_f32_16x16x32_bf16 v[116:119], v[208:211], v[172:175], v[116:119]
	v_mfma_f32_16x16x32_bf16 v[112:115], v[216:219], v[172:175], v[112:115]
	v_mfma_f32_16x16x32_bf16 v[100:103], v[208:211], v[184:187], v[100:103]
	v_mfma_f32_16x16x32_bf16 v[96:99], v[216:219], v[184:187], v[96:99]
	v_mfma_f32_16x16x32_bf16 v[84:87], v[208:211], v[192:195], v[84:87]
	v_mfma_f32_16x16x32_bf16 v[80:83], v[216:219], v[192:195], v[80:83]
	v_mfma_f32_16x16x32_bf16 v[68:71], v[208:211], v[200:203], v[68:71]
	v_mfma_f32_16x16x32_bf16 v[64:67], v[216:219], v[200:203], v[64:67]
	v_mfma_f32_16x16x32_bf16 v[116:119], v[212:215], v[180:183], v[116:119]
	v_mfma_f32_16x16x32_bf16 v[112:115], v[220:223], v[180:183], v[112:115]
	v_mfma_f32_16x16x32_bf16 v[100:103], v[212:215], v[188:191], v[100:103]
	v_mfma_f32_16x16x32_bf16 v[96:99], v[220:223], v[188:191], v[96:99]
	v_mfma_f32_16x16x32_bf16 v[84:87], v[212:215], v[196:199], v[84:87]
	v_mfma_f32_16x16x32_bf16 v[80:83], v[220:223], v[196:199], v[80:83]
	v_mfma_f32_16x16x32_bf16 v[68:71], v[212:215], v[204:207], v[68:71]
	v_mfma_f32_16x16x32_bf16 v[64:67], v[220:223], v[204:207], v[64:67]
	s_barrier
; #define PG8_STAGE(bufoff, gbase, voff) do { _Pragma("unroll") for (int _i = 0; _i < 2; ++_i) \
;         __builtin_amdgcn_global_load_lds((const unsigned*)((const char*)(gbase) + (voff)[_i]), (LAS unsigned*)(lds + (bufoff) + ldsw + _i * 8192), 16, 0, 0); } while (0)
; #define PG8_LDA(dst, b, h) do { _Pragma("unroll") for (int m = 0; m < 4; ++m) _Pragma("unroll") for (int k = 0; k < 2; ++k) dst[m][k] = *(const LAS bf16x8*)(lds + PG8_SA(b, h) + aoff + m * 2048 + k * 1024); } while (0)
; #define PG8_LDB(dst, b, h) do { _Pragma("unroll") for (int n = 0; n < 2; ++n) _Pragma("unroll") for (int k = 0; k < 2; ++k) dst[n][k] = *(const LAS bf16x8*)(lds + PG8_SB(b, h) + boff + n * 2048 + k * 1024); } while (0)
; #define PG8_MMA(ai, bj, At, Bt) do { __builtin_amdgcn_s_setprio(1); _Pragma("unroll") for (int m = 0; m < 4; ++m) _Pragma("unroll") for (int n = 0; n < 2; ++n) _Pragma("unroll") for (int k = 0; k < 2; ++k) \
;         acc[ai][bj][m][n] = __builtin_amdgcn_mfma_f32_16x16x32_bf16(Bt[n][k], At[m][k], acc[ai][bj][m][n], 0, 0, 0); __builtin_amdgcn_s_setprio(0); } while (0)
; #define PG8_WAIT_V(n) asm volatile("s_waitcnt vmcnt(" #n ")" ::: "memory")
; #define PG8_WAIT_L(n) asm volatile("s_waitcnt lgkmcnt(" #n ")" ::: "memory")
; #define PG8_BAR __builtin_amdgcn_s_barrier()
; #define PG8_SCHED __builtin_amdgcn_sched_barrier(0)
; template <class Epi>
; __device__ __forceinline__ void gemm_phase(LAS unsigned char* lds, const Gemm g, const StaticOrder& S, const Epi& E) {
;     ...
;             PG8_LDB(B0, 1, 0); PG8_SCHED; PG8_LDA(At, 1, 0); PG8_STAGE(PG8_SA(0, 1), a2 + hstep, voffA);
;             PG8_WAIT_L(8); PG8_BAR; PG8_WAIT_L(0); PG8_MMA(0, 0, At, B0); PG8_BAR; PG8_SCHED;
;             PG8_LDB(B1, 1, 1); PG8_STAGE(PG8_SB(1, 0), b3, voffB);
;             PG8_BAR; PG8_WAIT_L(0); PG8_MMA(0, 1, At, B1); PG8_BAR;
;             PG8_LDA(At, 1, 1); PG8_STAGE(PG8_SA(1, 0), a3, voffA);
;             PG8_BAR; PG8_WAIT_L(0); PG8_MMA(1, 0, At, B0); PG8_BAR; PG8_SCHED;
;             PG8_STAGE(PG8_SB(1, 1), b3 + hstep, voffB);
;             PG8_WAIT_V(6); PG8_BAR; PG8_MMA(1, 1, At, B1); PG8_BAR;
	s_setprio 0
	s_add_i32 s31, s68, s36
	v_lshl_add_u64 v[158:159], v[158:159], 0, s[8:9]
	s_mov_b32 m0, s31
	s_nop 0
	global_load_lds_dwordx4 v[158:159], off
	v_lshl_add_u64 v[158:159], v[176:177], 0, s[8:9]
	s_add_i32 m0, s31, 0x2000
	s_nop 0
	global_load_lds_dwordx4 v[158:159], off
	s_mov_b32 m0, s57
	v_lshl_add_u64 v[158:159], v[224:225], 0, s[8:9]
	ds_read_b128 v[172:175], v163 offset:49152
	ds_read_b128 v[180:183], v163 offset:50176
	ds_read_b128 v[184:187], v163 offset:51200
	ds_read_b128 v[188:191], v163 offset:52224
	ds_read_b128 v[192:195], v163 offset:53248
	ds_read_b128 v[196:199], v163 offset:54272
	ds_read_b128 v[200:203], v163 offset:55296
	ds_read_b128 v[204:207], v163 offset:56320
	global_load_lds_dwordx4 v[158:159], off
	v_lshl_add_u64 v[158:159], v[226:227], 0, s[8:9]
	s_mov_b32 m0, s58
	s_nop 0
	global_load_lds_dwordx4 v[158:159], off
	s_add_u32 s24, s24, 0x80080
	s_addc_u32 s25, s25, 0
	s_add_i32 s30, s30, s36
	v_lshl_add_u64 v[252:253], s[24:25], 0, v[140:141]
	s_mov_b32 m0, s30
	s_nop 0
	global_load_lds_dwordx4 v[252:253], off
	v_lshl_add_u64 v[252:253], s[24:25], 0, v[144:145]
	s_add_i32 m0, s30, 0x2000
	s_nop 0
	global_load_lds_dwordx4 v[252:253], off
	s_waitcnt lgkmcnt(0)
	s_waitcnt vmcnt(8)
	s_setprio 1
	s_barrier
	v_mfma_f32_16x16x32_bf16 v[60:63], v[128:131], v[172:175], v[60:63]
	v_mfma_f32_16x16x32_bf16 v[56:59], v[154:157], v[172:175], v[56:59]
	v_mfma_f32_16x16x32_bf16 v[44:47], v[128:131], v[184:187], v[44:47]
	v_mfma_f32_16x16x32_bf16 v[40:43], v[154:157], v[184:187], v[40:43]
	v_mfma_f32_16x16x32_bf16 v[28:31], v[128:131], v[192:195], v[28:31]
	v_mfma_f32_16x16x32_bf16 v[24:27], v[154:157], v[192:195], v[24:27]
	v_mfma_f32_16x16x32_bf16 v[12:15], v[128:131], v[200:203], v[12:15]
	v_mfma_f32_16x16x32_bf16 v[8:11], v[154:157], v[200:203], v[8:11]
	v_mfma_f32_16x16x32_bf16 v[60:63], v[132:135], v[180:183], v[60:63]
	v_mfma_f32_16x16x32_bf16 v[56:59], v[168:171], v[180:183], v[56:59]
	v_mfma_f32_16x16x32_bf16 v[44:47], v[132:135], v[188:191], v[44:47]
	v_mfma_f32_16x16x32_bf16 v[40:43], v[168:171], v[188:191], v[40:43]
	v_mfma_f32_16x16x32_bf16 v[28:31], v[132:135], v[196:199], v[28:31]
	v_mfma_f32_16x16x32_bf16 v[24:27], v[168:171], v[196:199], v[24:27]
	v_mfma_f32_16x16x32_bf16 v[12:15], v[132:135], v[204:207], v[12:15]
	v_mfma_f32_16x16x32_bf16 v[8:11], v[168:171], v[204:207], v[8:11]
	v_mfma_f32_16x16x32_bf16 v[52:55], v[208:211], v[172:175], v[52:55]
	v_mfma_f32_16x16x32_bf16 v[48:51], v[216:219], v[172:175], v[48:51]
	v_mfma_f32_16x16x32_bf16 v[36:39], v[208:211], v[184:187], v[36:39]
	v_mfma_f32_16x16x32_bf16 v[32:35], v[216:219], v[184:187], v[32:35]
	v_mfma_f32_16x16x32_bf16 v[20:23], v[208:211], v[192:195], v[20:23]
	v_mfma_f32_16x16x32_bf16 v[16:19], v[216:219], v[192:195], v[16:19]
	v_mfma_f32_16x16x32_bf16 v[4:7], v[208:211], v[200:203], v[4:7]
	v_mfma_f32_16x16x32_bf16 v[0:3], v[216:219], v[200:203], v[0:3]
	v_mfma_f32_16x16x32_bf16 v[52:55], v[212:215], v[180:183], v[52:55]
	v_mfma_f32_16x16x32_bf16 v[48:51], v[220:223], v[180:183], v[48:51]
	v_mfma_f32_16x16x32_bf16 v[36:39], v[212:215], v[188:191], v[36:39]
	v_mfma_f32_16x16x32_bf16 v[32:35], v[220:223], v[188:191], v[32:35]
	v_mfma_f32_16x16x32_bf16 v[20:23], v[212:215], v[196:199], v[20:23]
	v_mfma_f32_16x16x32_bf16 v[16:19], v[220:223], v[196:199], v[16:19]
	v_mfma_f32_16x16x32_bf16 v[4:7], v[212:215], v[204:207], v[4:7]
	v_mfma_f32_16x16x32_bf16 v[0:3], v[220:223], v[204:207], v[0:3]
	s_barrier
	s_setprio 0
	s_add_i32 s67, s67, 2
	s_add_u32 s22, s22, 0x100
	s_addc_u32 s23, s23, 0
	s_add_u32 s65, s65, 0x100
	s_addc_u32 s66, s66, 0
	s_cmp_gt_u32 s67, 29
	.p2align	6

; #define PG8_STAGE(bufoff, gbase, voff) do { _Pragma("unroll") for (int _i = 0; _i < 2; ++_i) \
;         __builtin_amdgcn_global_load_lds((const unsigned*)((const char*)(gbase) + (voff)[_i]), (LAS unsigned*)(lds + (bufoff) + ldsw + _i * 8192), 16, 0, 0); } while (0)
; #define PG8_LDA(dst, b, h) do { _Pragma("unroll") for (int m = 0; m < 4; ++m) _Pragma("unroll") for (int k = 0; k < 2; ++k) dst[m][k] = *(const LAS bf16x8*)(lds + PG8_SA(b, h) + aoff + m * 2048 + k * 1024); } while (0)
; #define PG8_LDB(dst, b, h) do { _Pragma("unroll") for (int n = 0; n < 2; ++n) _Pragma("unroll") for (int k = 0; k < 2; ++k) dst[n][k] = *(const LAS bf16x8*)(lds + PG8_SB(b, h) + boff + n * 2048 + k * 1024); } while (0)
; template <class Epi>
; __device__ __forceinline__ void gemm_phase(LAS unsigned char* lds, const Gemm g, const StaticOrder& S, const Epi& E) {
;     ...
;     for (;;) {
;         const bool has_next = S.next(ui + 1, nxt);
;         const char* nA = has_next ? (const char*)g.A + (size_t)nxt.pm * tstep : cA; const char* nB = has_next ? (const char*)g.Bt + (size_t)nxt.pn * tstep : cB;
;         for (int t = 0; t < nt; t += 2) {
;             const bool last = (t == nt - 2);
;             const char* a1 = cA + (size_t)(t + 1) * kstep;
;             const char* a2 = last ? nA : cA + (size_t)(t + 2) * kstep; const char* b2 = last ? nB : cB + (size_t)(t + 2) * kstep;
;             const char* a3 = a2 + kstep; const char* b3 = b2 + kstep;
;             PG8_LDB(B0, 0, 0); PG8_SCHED; PG8_LDA(At, 0, 0); PG8_STAGE(PG8_SA(1, 1), a1 + hstep, voffA);
;             PG8_WAIT_L(8); PG8_BAR; PG8_WAIT_L(0); PG8_MMA(0, 0, At, B0); PG8_BAR; PG8_SCHED;
;             PG8_LDB(B1, 0, 1); PG8_STAGE(PG8_SB(0, 0), b2, voffB);
;             PG8_BAR; PG8_WAIT_L(0); PG8_MMA(0, 1, At, B1); PG8_BAR;
;             PG8_LDA(At, 0, 1); PG8_STAGE(PG8_SA(0, 0), a2, voffA);
;             PG8_BAR; PG8_WAIT_L(0); PG8_MMA(1, 0, At, B0); PG8_BAR; PG8_SCHED;
;             PG8_STAGE(PG8_SB(0, 1), b2 + hstep, voffB);
;             PG8_WAIT_V(6); PG8_BAR; PG8_MMA(1, 1, At, B1); PG8_BAR;
;     ...
; #pragma unroll
;         for (int a = 0; a < 2; ++a)
; #pragma unroll
;             for (int b = 0; b < 2; ++b)
; #pragma unroll
;                 for (int m = 0; m < 4; ++m)
; #pragma unroll
;                     for (int n = 0; n < 2; ++n) acc[a][b][m][n] = (f32x4){0.f, 0.f, 0.f, 0.f};
.LBB0_1305:
	s_ashr_i32 s9, s8, 31
	v_cmp_lt_i64_e32 vcc, s[10:11], v[142:143]
	s_lshl_b64 s[10:11], s[8:9], 20
	s_add_u32 s10, s23, s10
	s_addc_u32 s11, s24, s11
	s_and_b64 s[12:13], vcc, exec
	s_cselect_b32 s9, s11, s17
	s_cselect_b32 s61, s10, s16
	s_ashr_i32 s7, s6, 31
	s_lshl_b64 s[12:13], s[6:7], 20
	s_add_u32 s12, s25, s12
	s_addc_u32 s13, s30, s13
	s_and_b64 s[20:21], vcc, exec
	s_cselect_b32 s7, s13, s19
	s_cselect_b32 s62, s12, s18
	s_add_u32 s16, s16, 0x80080
	s_addc_u32 s17, s17, 0
	s_add_u32 s63, s18, 0x100
	s_addc_u32 s64, s19, 0
	s_mov_b32 s65, -2
	ds_read_b128 v[166:169], v149
	ds_read_b128 v[170:173], v149 offset:1024
	ds_read_b128 v[174:177], v149 offset:2048
	ds_read_b128 v[180:183], v149 offset:3072
	s_add_u32 s18, s16, 0xfff80080
	s_addc_u32 s19, s17, -1
	s_cmp_eq_u32 s65, 28
	s_cselect_b32 s21, s9, s19
	s_cselect_b32 s20, s61, s18
	s_cselect_b32 s19, s7, s64
	s_cselect_b32 s18, s62, s63
	v_lshl_add_u64 v[162:163], s[16:17], 0, v[138:139]
	s_add_i32 m0, s35, 0xc000
	ds_read_b128 v[184:187], v150
	ds_read_b128 v[188:191], v150 offset:1024
	ds_read_b128 v[192:195], v150 offset:2048
	ds_read_b128 v[196:199], v150 offset:3072
	ds_read_b128 v[200:203], v150 offset:4096
	ds_read_b128 v[204:207], v150 offset:5120
	ds_read_b128 v[208:211], v150 offset:6144
	ds_read_b128 v[212:215], v150 offset:7168
	global_load_lds_dwordx4 v[162:163], off
	v_lshl_add_u64 v[162:163], s[16:17], 0, v[140:141]
	s_add_i32 m0, s35, 0xe000
	s_nop 0
	global_load_lds_dwordx4 v[162:163], off
	ds_read_b128 v[216:219], v152
	ds_read_b128 v[220:223], v152 offset:1024
	ds_read_b128 v[224:227], v152 offset:2048
	ds_read_b128 v[228:231], v152 offset:3072
	s_waitcnt lgkmcnt(0)
	s_waitcnt vmcnt(8)
	s_setprio 1
	s_barrier
	v_mfma_f32_16x16x32_bf16 v[124:127], v[166:169], v[184:187], 0
	v_mfma_f32_16x16x32_bf16 v[116:119], v[174:177], v[184:187], 0
	v_mfma_f32_16x16x32_bf16 v[108:111], v[166:169], v[192:195], 0
	v_mfma_f32_16x16x32_bf16 v[100:103], v[174:177], v[192:195], 0
	v_mfma_f32_16x16x32_bf16 v[92:95], v[166:169], v[200:203], 0
	v_mfma_f32_16x16x32_bf16 v[84:87], v[174:177], v[200:203], 0
	v_mfma_f32_16x16x32_bf16 v[76:79], v[166:169], v[208:211], 0
	v_mfma_f32_16x16x32_bf16 v[68:71], v[174:177], v[208:211], 0
	v_mfma_f32_16x16x32_bf16 v[124:127], v[170:173], v[188:191], v[124:127]
	v_mfma_f32_16x16x32_bf16 v[116:119], v[180:183], v[188:191], v[116:119]
	v_mfma_f32_16x16x32_bf16 v[108:111], v[170:173], v[196:199], v[108:111]
	v_mfma_f32_16x16x32_bf16 v[100:103], v[180:183], v[196:199], v[100:103]
	v_mfma_f32_16x16x32_bf16 v[92:95], v[170:173], v[204:207], v[92:95]
	v_mfma_f32_16x16x32_bf16 v[84:87], v[180:183], v[204:207], v[84:87]
	v_mfma_f32_16x16x32_bf16 v[76:79], v[170:173], v[212:215], v[76:79]
	v_mfma_f32_16x16x32_bf16 v[68:71], v[180:183], v[212:215], v[68:71]
	v_mfma_f32_16x16x32_bf16 v[120:123], v[216:219], v[184:187], 0
	v_mfma_f32_16x16x32_bf16 v[112:115], v[224:227], v[184:187], 0
	v_mfma_f32_16x16x32_bf16 v[104:107], v[216:219], v[192:195], 0
	v_mfma_f32_16x16x32_bf16 v[96:99], v[224:227], v[192:195], 0
	v_mfma_f32_16x16x32_bf16 v[88:91], v[216:219], v[200:203], 0
	v_mfma_f32_16x16x32_bf16 v[80:83], v[224:227], v[200:203], 0
	v_mfma_f32_16x16x32_bf16 v[72:75], v[216:219], v[208:211], 0
	v_mfma_f32_16x16x32_bf16 v[64:67], v[224:227], v[208:211], 0
	v_mfma_f32_16x16x32_bf16 v[120:123], v[220:223], v[188:191], v[120:123]
	v_mfma_f32_16x16x32_bf16 v[112:115], v[228:231], v[188:191], v[112:115]
	v_mfma_f32_16x16x32_bf16 v[104:107], v[220:223], v[196:199], v[104:107]
	v_mfma_f32_16x16x32_bf16 v[96:99], v[228:231], v[196:199], v[96:99]
	v_mfma_f32_16x16x32_bf16 v[88:91], v[220:223], v[204:207], v[88:91]
	v_mfma_f32_16x16x32_bf16 v[80:83], v[228:231], v[204:207], v[80:83]
	v_mfma_f32_16x16x32_bf16 v[72:75], v[220:223], v[212:215], v[72:75]
	v_mfma_f32_16x16x32_bf16 v[64:67], v[228:231], v[212:215], v[64:67]
	s_barrier
	s_setprio 0
	s_add_i32 s66, s58, s31
	v_lshl_add_u64 v[162:163], s[18:19], 0, v[132:133]
	s_mov_b32 m0, s66
	s_nop 0
	global_load_lds_dwordx4 v[162:163], off
	v_lshl_add_u64 v[232:233], s[18:19], 0, v[128:129]
	s_add_i32 m0, s66, 0x2000
	s_nop 0
	global_load_lds_dwordx4 v[232:233], off
	s_mov_b32 m0, s35
	v_lshl_add_u64 v[234:235], s[20:21], 0, v[134:135]
	ds_read_b128 v[184:187], v150 offset:16384
	ds_read_b128 v[188:191], v150 offset:17408
	ds_read_b128 v[192:195], v150 offset:18432
	ds_read_b128 v[196:199], v150 offset:19456
	ds_read_b128 v[200:203], v150 offset:20480
	ds_read_b128 v[204:207], v150 offset:21504
	ds_read_b128 v[208:211], v150 offset:22528
	ds_read_b128 v[212:215], v150 offset:23552
	global_load_lds_dwordx4 v[234:235], off
	v_lshl_add_u64 v[236:237], s[20:21], 0, v[130:131]
	s_mov_b32 m0, s36
	s_nop 0
	global_load_lds_dwordx4 v[236:237], off
	s_add_u32 s66, s18, 0x80000
	s_addc_u32 s67, s19, 0
	s_add_i32 s68, s59, s31
	v_lshl_add_u64 v[252:253], s[66:67], 0, v[132:133]
	s_mov_b32 m0, s68
	s_nop 0
	global_load_lds_dwordx4 v[252:253], off
	v_lshl_add_u64 v[252:253], s[66:67], 0, v[128:129]
	s_add_i32 m0, s68, 0x2000
	s_nop 0
	global_load_lds_dwordx4 v[252:253], off
	s_waitcnt lgkmcnt(0)
	s_waitcnt vmcnt(8)
	s_setprio 1
	s_barrier
; #define PG8_STAGE(bufoff, gbase, voff) do { _Pragma("unroll") for (int _i = 0; _i < 2; ++_i) \
;         __builtin_amdgcn_global_load_lds((const unsigned*)((const char*)(gbase) + (voff)[_i]), (LAS unsigned*)(lds + (bufoff) + ldsw + _i * 8192), 16, 0, 0); } while (0)
; #define PG8_LDA(dst, b, h) do { _Pragma("unroll") for (int m = 0; m < 4; ++m) _Pragma("unroll") for (int k = 0; k < 2; ++k) dst[m][k] = *(const LAS bf16x8*)(lds + PG8_SA(b, h) + aoff + m * 2048 + k * 1024); } while (0)
; #define PG8_LDB(dst, b, h) do { _Pragma("unroll") for (int n = 0; n < 2; ++n) _Pragma("unroll") for (int k = 0; k < 2; ++k) dst[n][k] = *(const LAS bf16x8*)(lds + PG8_SB(b, h) + boff + n * 2048 + k * 1024); } while (0)
; #define PG8_WAIT_V(n) asm volatile("s_waitcnt vmcnt(" #n ")" ::: "memory")
; #define PG8_WAIT_L(n) asm volatile("s_waitcnt lgkmcnt(" #n ")" ::: "memory")
; #define PG8_BAR __builtin_amdgcn_s_barrier()
; #define PG8_SCHED __builtin_amdgcn_sched_barrier(0)
; template <class Epi>
; __device__ __forceinline__ void gemm_phase(LAS unsigned char* lds, const Gemm g, const StaticOrder& S, const Epi& E) {
;     ...
;             PG8_LDB(B0, 0, 0); PG8_SCHED; PG8_LDA(At, 0, 0); PG8_STAGE(PG8_SA(1, 1), a1 + hstep, voffA);
;             PG8_WAIT_L(8); PG8_BAR; PG8_WAIT_L(0); PG8_MMA(0, 0, At, B0); PG8_BAR; PG8_SCHED;
;             PG8_LDB(B1, 0, 1); PG8_STAGE(PG8_SB(0, 0), b2, voffB);
;             PG8_BAR; PG8_WAIT_L(0); PG8_MMA(0, 1, At, B1); PG8_BAR;
;             PG8_LDA(At, 0, 1); PG8_STAGE(PG8_SA(0, 0), a2, voffA);
;             PG8_BAR; PG8_WAIT_L(0); PG8_MMA(1, 0, At, B0); PG8_BAR; PG8_SCHED;
;             PG8_STAGE(PG8_SB(0, 1), b2 + hstep, voffB);
;             PG8_WAIT_V(6); PG8_BAR; PG8_MMA(1, 1, At, B1); PG8_BAR;
;             PG8_LDB(B0, 1, 0); PG8_SCHED; PG8_LDA(At, 1, 0); PG8_STAGE(PG8_SA(0, 1), a2 + hstep, voffA);
;             PG8_WAIT_L(8); PG8_BAR; PG8_WAIT_L(0); PG8_MMA(0, 0, At, B0); PG8_BAR; PG8_SCHED;
;             PG8_LDB(B1, 1, 1); PG8_STAGE(PG8_SB(1, 0), b3, voffB);
;             PG8_BAR; PG8_WAIT_L(0); PG8_MMA(0, 1, At, B1); PG8_BAR;
;             PG8_LDA(At, 1, 1); PG8_STAGE(PG8_SA(1, 0), a3, voffA);
;             PG8_BAR; PG8_WAIT_L(0); PG8_MMA(1, 0, At, B0); PG8_BAR; PG8_SCHED;
;             PG8_STAGE(PG8_SB(1, 1), b3 + hstep, voffB);
;             PG8_WAIT_V(6); PG8_BAR; PG8_MMA(1, 1, At, B1); PG8_BAR;
	v_mfma_f32_16x16x32_bf16 v[60:63], v[166:169], v[184:187], 0
	v_mfma_f32_16x16x32_bf16 v[52:55], v[174:177], v[184:187], 0
	v_mfma_f32_16x16x32_bf16 v[44:47], v[166:169], v[192:195], 0
	v_mfma_f32_16x16x32_bf16 v[36:39], v[174:177], v[192:195], 0
	v_mfma_f32_16x16x32_bf16 v[28:31], v[166:169], v[200:203], 0
	v_mfma_f32_16x16x32_bf16 v[20:23], v[174:177], v[200:203], 0
	v_mfma_f32_16x16x32_bf16 v[12:15], v[166:169], v[208:211], 0
	v_mfma_f32_16x16x32_bf16 v[4:7], v[174:177], v[208:211], 0
	v_mfma_f32_16x16x32_bf16 v[60:63], v[170:173], v[188:191], v[60:63]
	v_mfma_f32_16x16x32_bf16 v[52:55], v[180:183], v[188:191], v[52:55]
	v_mfma_f32_16x16x32_bf16 v[44:47], v[170:173], v[196:199], v[44:47]
	v_mfma_f32_16x16x32_bf16 v[36:39], v[180:183], v[196:199], v[36:39]
	v_mfma_f32_16x16x32_bf16 v[28:31], v[170:173], v[204:207], v[28:31]
	v_mfma_f32_16x16x32_bf16 v[20:23], v[180:183], v[204:207], v[20:23]
	v_mfma_f32_16x16x32_bf16 v[12:15], v[170:173], v[212:215], v[12:15]
	v_mfma_f32_16x16x32_bf16 v[4:7], v[180:183], v[212:215], v[4:7]
	v_mfma_f32_16x16x32_bf16 v[56:59], v[216:219], v[184:187], 0
	v_mfma_f32_16x16x32_bf16 v[48:51], v[224:227], v[184:187], 0
	v_mfma_f32_16x16x32_bf16 v[40:43], v[216:219], v[192:195], 0
	v_mfma_f32_16x16x32_bf16 v[32:35], v[224:227], v[192:195], 0
	v_mfma_f32_16x16x32_bf16 v[24:27], v[216:219], v[200:203], 0
	v_mfma_f32_16x16x32_bf16 v[16:19], v[224:227], v[200:203], 0
	v_mfma_f32_16x16x32_bf16 v[8:11], v[216:219], v[208:211], 0
	v_mfma_f32_16x16x32_bf16 v[0:3], v[224:227], v[208:211], 0
	v_mfma_f32_16x16x32_bf16 v[56:59], v[220:223], v[188:191], v[56:59]
	v_mfma_f32_16x16x32_bf16 v[48:51], v[228:231], v[188:191], v[48:51]
	v_mfma_f32_16x16x32_bf16 v[40:43], v[220:223], v[196:199], v[40:43]
	v_mfma_f32_16x16x32_bf16 v[32:35], v[228:231], v[196:199], v[32:35]
	v_mfma_f32_16x16x32_bf16 v[24:27], v[220:223], v[204:207], v[24:27]
	v_mfma_f32_16x16x32_bf16 v[16:19], v[228:231], v[204:207], v[16:19]
	v_mfma_f32_16x16x32_bf16 v[8:11], v[220:223], v[212:215], v[8:11]
	v_mfma_f32_16x16x32_bf16 v[0:3], v[228:231], v[212:215], v[0:3]
	s_barrier
	s_setprio 0
	s_add_i32 s66, 0, 0x18000
	v_add_u32_e32 v161, s66, v147
	ds_read_b128 v[166:169], v161
	ds_read_b128 v[170:173], v161 offset:1024
	ds_read_b128 v[174:177], v161 offset:2048
	ds_read_b128 v[180:183], v161 offset:3072
	s_add_u32 s20, s20, 0x80000
	s_addc_u32 s21, s21, 0
	s_mov_b32 m0, s37
	v_lshl_add_u64 v[216:217], s[20:21], 0, v[134:135]
	ds_read_b128 v[184:187], v150 offset:32768
	ds_read_b128 v[188:191], v150 offset:33792
	ds_read_b128 v[192:195], v150 offset:34816
	ds_read_b128 v[196:199], v150 offset:35840
	ds_read_b128 v[200:203], v150 offset:36864
	ds_read_b128 v[204:207], v150 offset:37888
	ds_read_b128 v[208:211], v150 offset:38912
	ds_read_b128 v[212:215], v150 offset:39936
	global_load_lds_dwordx4 v[216:217], off
	v_lshl_add_u64 v[216:217], s[20:21], 0, v[130:131]
	s_mov_b32 m0, s38
	s_nop 0
	global_load_lds_dwordx4 v[216:217], off
	s_add_i32 s20, 0, 0x1c000
	v_add_u32_e32 v161, s20, v147
	ds_read_b128 v[216:219], v161
	ds_read_b128 v[220:223], v161 offset:1024
	ds_read_b128 v[224:227], v161 offset:2048
	ds_read_b128 v[228:231], v161 offset:3072
	s_waitcnt lgkmcnt(0)
	s_waitcnt vmcnt(8)
	s_setprio 1
	s_barrier
	v_mfma_f32_16x16x32_bf16 v[124:127], v[166:169], v[184:187], v[124:127]
	v_mfma_f32_16x16x32_bf16 v[116:119], v[174:177], v[184:187], v[116:119]
	v_mfma_f32_16x16x32_bf16 v[108:111], v[166:169], v[192:195], v[108:111]
	v_mfma_f32_16x16x32_bf16 v[100:103], v[174:177], v[192:195], v[100:103]
	v_mfma_f32_16x16x32_bf16 v[92:95], v[166:169], v[200:203], v[92:95]
	v_mfma_f32_16x16x32_bf16 v[84:87], v[174:177], v[200:203], v[84:87]
	v_mfma_f32_16x16x32_bf16 v[76:79], v[166:169], v[208:211], v[76:79]
	v_mfma_f32_16x16x32_bf16 v[68:71], v[174:177], v[208:211], v[68:71]
	v_mfma_f32_16x16x32_bf16 v[124:127], v[170:173], v[188:191], v[124:127]
	v_mfma_f32_16x16x32_bf16 v[116:119], v[180:183], v[188:191], v[116:119]
	v_mfma_f32_16x16x32_bf16 v[108:111], v[170:173], v[196:199], v[108:111]
	v_mfma_f32_16x16x32_bf16 v[100:103], v[180:183], v[196:199], v[100:103]
	v_mfma_f32_16x16x32_bf16 v[92:95], v[170:173], v[204:207], v[92:95]
	v_mfma_f32_16x16x32_bf16 v[84:87], v[180:183], v[204:207], v[84:87]
	v_mfma_f32_16x16x32_bf16 v[76:79], v[170:173], v[212:215], v[76:79]
	v_mfma_f32_16x16x32_bf16 v[68:71], v[180:183], v[212:215], v[68:71]
	v_mfma_f32_16x16x32_bf16 v[120:123], v[216:219], v[184:187], v[120:123]
	v_mfma_f32_16x16x32_bf16 v[112:115], v[224:227], v[184:187], v[112:115]
	v_mfma_f32_16x16x32_bf16 v[104:107], v[216:219], v[192:195], v[104:107]
	v_mfma_f32_16x16x32_bf16 v[96:99], v[224:227], v[192:195], v[96:99]
	v_mfma_f32_16x16x32_bf16 v[88:91], v[216:219], v[200:203], v[88:91]
	v_mfma_f32_16x16x32_bf16 v[80:83], v[224:227], v[200:203], v[80:83]
	v_mfma_f32_16x16x32_bf16 v[72:75], v[216:219], v[208:211], v[72:75]
	v_mfma_f32_16x16x32_bf16 v[64:67], v[224:227], v[208:211], v[64:67]
	v_mfma_f32_16x16x32_bf16 v[120:123], v[220:223], v[188:191], v[120:123]
	v_mfma_f32_16x16x32_bf16 v[112:115], v[228:231], v[188:191], v[112:115]
	v_mfma_f32_16x16x32_bf16 v[104:107], v[220:223], v[196:199], v[104:107]
	v_mfma_f32_16x16x32_bf16 v[96:99], v[228:231], v[196:199], v[96:99]
	v_mfma_f32_16x16x32_bf16 v[88:91], v[220:223], v[204:207], v[88:91]
	v_mfma_f32_16x16x32_bf16 v[80:83], v[228:231], v[204:207], v[80:83]
	v_mfma_f32_16x16x32_bf16 v[72:75], v[220:223], v[212:215], v[72:75]
	v_mfma_f32_16x16x32_bf16 v[64:67], v[228:231], v[212:215], v[64:67]
	s_barrier
; #define PG8_STAGE(bufoff, gbase, voff) do { _Pragma("unroll") for (int _i = 0; _i < 2; ++_i) \
;         __builtin_amdgcn_global_load_lds((const unsigned*)((const char*)(gbase) + (voff)[_i]), (LAS unsigned*)(lds + (bufoff) + ldsw + _i * 8192), 16, 0, 0); } while (0)
; #define PG8_LDA(dst, b, h) do { _Pragma("unroll") for (int m = 0; m < 4; ++m) _Pragma("unroll") for (int k = 0; k < 2; ++k) dst[m][k] = *(const LAS bf16x8*)(lds + PG8_SA(b, h) + aoff + m * 2048 + k * 1024); } while (0)
; #define PG8_LDB(dst, b, h) do { _Pragma("unroll") for (int n = 0; n < 2; ++n) _Pragma("unroll") for (int k = 0; k < 2; ++k) dst[n][k] = *(const LAS bf16x8*)(lds + PG8_SB(b, h) + boff + n * 2048 + k * 1024); } while (0)
; #define PG8_MMA(ai, bj, At, Bt) do { __builtin_amdgcn_s_setprio(1); _Pragma("unroll") for (int m = 0; m < 4; ++m) _Pragma("unroll") for (int n = 0; n < 2; ++n) _Pragma("unroll") for (int k = 0; k < 2; ++k) \
;         acc[ai][bj][m][n] = __builtin_amdgcn_mfma_f32_16x16x32_bf16(Bt[n][k], At[m][k], acc[ai][bj][m][n], 0, 0, 0); __builtin_amdgcn_s_setprio(0); } while (0)
; #define PG8_WAIT_V(n) asm volatile("s_waitcnt vmcnt(" #n ")" ::: "memory")
; #define PG8_WAIT_L(n) asm volatile("s_waitcnt lgkmcnt(" #n ")" ::: "memory")
; #define PG8_BAR __builtin_amdgcn_s_barrier()
; #define PG8_SCHED __builtin_amdgcn_sched_barrier(0)
; template <class Epi>
; __device__ __forceinline__ void gemm_phase(LAS unsigned char* lds, const Gemm g, const StaticOrder& S, const Epi& E) {
;     ...
;             PG8_LDB(B0, 1, 0); PG8_SCHED; PG8_LDA(At, 1, 0); PG8_STAGE(PG8_SA(0, 1), a2 + hstep, voffA);
;             PG8_WAIT_L(8); PG8_BAR; PG8_WAIT_L(0); PG8_MMA(0, 0, At, B0); PG8_BAR; PG8_SCHED;
;             PG8_LDB(B1, 1, 1); PG8_STAGE(PG8_SB(1, 0), b3, voffB);
;             PG8_BAR; PG8_WAIT_L(0); PG8_MMA(0, 1, At, B1); PG8_BAR;
;             PG8_LDA(At, 1, 1); PG8_STAGE(PG8_SA(1, 0), a3, voffA);
;             PG8_BAR; PG8_WAIT_L(0); PG8_MMA(1, 0, At, B0); PG8_BAR; PG8_SCHED;
;             PG8_STAGE(PG8_SB(1, 1), b3 + hstep, voffB);
;             PG8_WAIT_V(6); PG8_BAR; PG8_MMA(1, 1, At, B1); PG8_BAR;
	s_setprio 0
	s_add_i32 s21, s66, s31
	v_lshl_add_u64 v[162:163], v[162:163], 0, s[4:5]
	s_mov_b32 m0, s21
	s_nop 0
	global_load_lds_dwordx4 v[162:163], off
	v_lshl_add_u64 v[162:163], v[232:233], 0, s[4:5]
	s_add_i32 m0, s21, 0x2000
	s_nop 0
	global_load_lds_dwordx4 v[162:163], off
	s_mov_b32 m0, s42
	v_lshl_add_u64 v[162:163], v[234:235], 0, s[4:5]
	ds_read_b128 v[184:187], v150 offset:49152
	ds_read_b128 v[188:191], v150 offset:50176
	ds_read_b128 v[192:195], v150 offset:51200
	ds_read_b128 v[196:199], v150 offset:52224
	ds_read_b128 v[200:203], v150 offset:53248
	ds_read_b128 v[204:207], v150 offset:54272
	ds_read_b128 v[208:211], v150 offset:55296
	ds_read_b128 v[212:215], v150 offset:56320
	global_load_lds_dwordx4 v[162:163], off
	v_lshl_add_u64 v[162:163], v[236:237], 0, s[4:5]
	s_mov_b32 m0, s43
	s_nop 0
	global_load_lds_dwordx4 v[162:163], off
	s_add_u32 s18, s18, 0x80080
	s_addc_u32 s19, s19, 0
	s_add_i32 s20, s20, s31
	v_lshl_add_u64 v[162:163], s[18:19], 0, v[132:133]
	s_mov_b32 m0, s20
	s_nop 0
	global_load_lds_dwordx4 v[162:163], off
	v_lshl_add_u64 v[162:163], s[18:19], 0, v[128:129]
	s_add_i32 m0, s20, 0x2000
	s_nop 0
	global_load_lds_dwordx4 v[162:163], off
	s_waitcnt lgkmcnt(0)
	s_waitcnt vmcnt(8)
	s_setprio 1
	s_barrier
	v_mfma_f32_16x16x32_bf16 v[60:63], v[166:169], v[184:187], v[60:63]
	v_mfma_f32_16x16x32_bf16 v[52:55], v[174:177], v[184:187], v[52:55]
	v_mfma_f32_16x16x32_bf16 v[44:47], v[166:169], v[192:195], v[44:47]
	v_mfma_f32_16x16x32_bf16 v[36:39], v[174:177], v[192:195], v[36:39]
	v_mfma_f32_16x16x32_bf16 v[28:31], v[166:169], v[200:203], v[28:31]
	v_mfma_f32_16x16x32_bf16 v[20:23], v[174:177], v[200:203], v[20:23]
	v_mfma_f32_16x16x32_bf16 v[12:15], v[166:169], v[208:211], v[12:15]
	v_mfma_f32_16x16x32_bf16 v[4:7], v[174:177], v[208:211], v[4:7]
	v_mfma_f32_16x16x32_bf16 v[60:63], v[170:173], v[188:191], v[60:63]
	v_mfma_f32_16x16x32_bf16 v[52:55], v[180:183], v[188:191], v[52:55]
	v_mfma_f32_16x16x32_bf16 v[44:47], v[170:173], v[196:199], v[44:47]
	v_mfma_f32_16x16x32_bf16 v[36:39], v[180:183], v[196:199], v[36:39]
	v_mfma_f32_16x16x32_bf16 v[28:31], v[170:173], v[204:207], v[28:31]
	v_mfma_f32_16x16x32_bf16 v[20:23], v[180:183], v[204:207], v[20:23]
	v_mfma_f32_16x16x32_bf16 v[12:15], v[170:173], v[212:215], v[12:15]
	v_mfma_f32_16x16x32_bf16 v[4:7], v[180:183], v[212:215], v[4:7]
	v_mfma_f32_16x16x32_bf16 v[56:59], v[216:219], v[184:187], v[56:59]
	v_mfma_f32_16x16x32_bf16 v[48:51], v[224:227], v[184:187], v[48:51]
	v_mfma_f32_16x16x32_bf16 v[40:43], v[216:219], v[192:195], v[40:43]
	v_mfma_f32_16x16x32_bf16 v[32:35], v[224:227], v[192:195], v[32:35]
	v_mfma_f32_16x16x32_bf16 v[24:27], v[216:219], v[200:203], v[24:27]
	v_mfma_f32_16x16x32_bf16 v[16:19], v[224:227], v[200:203], v[16:19]
	v_mfma_f32_16x16x32_bf16 v[8:11], v[216:219], v[208:211], v[8:11]
	v_mfma_f32_16x16x32_bf16 v[0:3], v[224:227], v[208:211], v[0:3]
	v_mfma_f32_16x16x32_bf16 v[56:59], v[220:223], v[188:191], v[56:59]
	v_mfma_f32_16x16x32_bf16 v[48:51], v[228:231], v[188:191], v[48:51]
	v_mfma_f32_16x16x32_bf16 v[40:43], v[220:223], v[196:199], v[40:43]
	v_mfma_f32_16x16x32_bf16 v[32:35], v[228:231], v[196:199], v[32:35]
	v_mfma_f32_16x16x32_bf16 v[24:27], v[220:223], v[204:207], v[24:27]
	v_mfma_f32_16x16x32_bf16 v[16:19], v[228:231], v[204:207], v[16:19]
	v_mfma_f32_16x16x32_bf16 v[8:11], v[220:223], v[212:215], v[8:11]
	v_mfma_f32_16x16x32_bf16 v[0:3], v[228:231], v[212:215], v[0:3]
	s_barrier
	s_setprio 0
	s_add_i32 s65, s65, 2
	s_add_u32 s16, s16, 0x100
	s_addc_u32 s17, s17, 0
	s_add_u32 s63, s63, 0x100
	s_addc_u32 s64, s64, 0
	s_cmp_gt_u32 s65, 29
	.p2align	6

; #define PG8_STAGE(bufoff, gbase, voff) do { _Pragma("unroll") for (int _i = 0; _i < 2; ++_i) \
;         __builtin_amdgcn_global_load_lds((const unsigned*)((const char*)(gbase) + (voff)[_i]), (LAS unsigned*)(lds + (bufoff) + ldsw + _i * 8192), 16, 0, 0); } while (0)
; #define PG8_LDA(dst, b, h) do { _Pragma("unroll") for (int m = 0; m < 4; ++m) _Pragma("unroll") for (int k = 0; k < 2; ++k) dst[m][k] = *(const LAS bf16x8*)(lds + PG8_SA(b, h) + aoff + m * 2048 + k * 1024); } while (0)
; #define PG8_LDB(dst, b, h) do { _Pragma("unroll") for (int n = 0; n < 2; ++n) _Pragma("unroll") for (int k = 0; k < 2; ++k) dst[n][k] = *(const LAS bf16x8*)(lds + PG8_SB(b, h) + boff + n * 2048 + k * 1024); } while (0)
; template <class Epi>
; __device__ __forceinline__ void gemm_phase(LAS unsigned char* lds, const Gemm g, const StaticOrder& S, const Epi& E) {
;     ...
;     for (;;) {
;         const bool has_next = S.next(ui + 1, nxt);
;         const char* nA = has_next ? (const char*)g.A + (size_t)nxt.pm * tstep : cA; const char* nB = has_next ? (const char*)g.Bt + (size_t)nxt.pn * tstep : cB;
;         for (int t = 0; t < nt; t += 2) {
;             const bool last = (t == nt - 2);
;             const char* a1 = cA + (size_t)(t + 1) * kstep;
;             const char* a2 = last ? nA : cA + (size_t)(t + 2) * kstep; const char* b2 = last ? nB : cB + (size_t)(t + 2) * kstep;
;             const char* a3 = a2 + kstep; const char* b3 = b2 + kstep;
;             PG8_LDB(B0, 0, 0); PG8_SCHED; PG8_LDA(At, 0, 0); PG8_STAGE(PG8_SA(1, 1), a1 + hstep, voffA);
;             PG8_WAIT_L(8); PG8_BAR; PG8_WAIT_L(0); PG8_MMA(0, 0, At, B0); PG8_BAR; PG8_SCHED;
;             PG8_LDB(B1, 0, 1); PG8_STAGE(PG8_SB(0, 0), b2, voffB);
;             PG8_BAR; PG8_WAIT_L(0); PG8_MMA(0, 1, At, B1); PG8_BAR;
;             PG8_LDA(At, 0, 1); PG8_STAGE(PG8_SA(0, 0), a2, voffA);
;             PG8_BAR; PG8_WAIT_L(0); PG8_MMA(1, 0, At, B0); PG8_BAR; PG8_SCHED;
;             PG8_STAGE(PG8_SB(0, 1), b2 + hstep, voffB);
;             PG8_WAIT_V(6); PG8_BAR; PG8_MMA(1, 1, At, B1); PG8_BAR;
;     ...
; #pragma unroll
;         for (int a = 0; a < 2; ++a)
; #pragma unroll
;             for (int b = 0; b < 2; ++b)
; #pragma unroll
;                 for (int m = 0; m < 4; ++m)
; #pragma unroll
;                     for (int n = 0; n < 2; ++n) acc[a][b][m][n] = (f32x4){0.f, 0.f, 0.f, 0.f};
.LBB0_1410:
	s_add_u32 s14, s14, 0x158080
	s_addc_u32 s15, s15, 0
	s_add_u32 s61, s16, 0x100
	s_addc_u32 s62, s17, 0
	s_mov_b32 s63, -2
	s_waitcnt lgkmcnt(0)
	ds_read_b128 v[128:131], v162
	ds_read_b128 v[132:135], v162 offset:1024
	ds_read_b128 v[154:157], v162 offset:2048
	ds_read_b128 v[168:171], v162 offset:3072
	s_add_u32 s16, s14, 0xffea8080
	s_addc_u32 s17, s15, -1
	s_cmpk_eq_i32 s63, 0x52
	s_cselect_b32 s19, s1, s17
	s_cselect_b32 s18, s0, s16
	s_cselect_b32 s17, s7, s62
	s_cselect_b32 s16, s6, s61
	v_lshl_add_u64 v[158:159], s[14:15], 0, v[146:147]
	s_add_i32 m0, s30, 0xc000
	ds_read_b128 v[172:175], v163
	ds_read_b128 v[180:183], v163 offset:1024
	ds_read_b128 v[184:187], v163 offset:2048
	ds_read_b128 v[188:191], v163 offset:3072
	ds_read_b128 v[192:195], v163 offset:4096
	ds_read_b128 v[196:199], v163 offset:5120
	ds_read_b128 v[200:203], v163 offset:6144
	ds_read_b128 v[204:207], v163 offset:7168
	global_load_lds_dwordx4 v[158:159], off
	v_lshl_add_u64 v[158:159], s[14:15], 0, v[148:149]
	s_add_i32 m0, s30, 0xe000
	s_nop 0
	global_load_lds_dwordx4 v[158:159], off
	ds_read_b128 v[208:211], v165
	ds_read_b128 v[212:215], v165 offset:1024
	ds_read_b128 v[216:219], v165 offset:2048
	ds_read_b128 v[220:223], v165 offset:3072
	s_waitcnt lgkmcnt(0)
	s_waitcnt vmcnt(8)
	s_setprio 1
	s_barrier
	v_mfma_f32_16x16x32_bf16 v[124:127], v[128:131], v[172:175], 0
	v_mfma_f32_16x16x32_bf16 v[120:123], v[154:157], v[172:175], 0
	v_mfma_f32_16x16x32_bf16 v[108:111], v[128:131], v[184:187], 0
	v_mfma_f32_16x16x32_bf16 v[104:107], v[154:157], v[184:187], 0
	v_mfma_f32_16x16x32_bf16 v[92:95], v[128:131], v[192:195], 0
	v_mfma_f32_16x16x32_bf16 v[88:91], v[154:157], v[192:195], 0
	v_mfma_f32_16x16x32_bf16 v[76:79], v[128:131], v[200:203], 0
	v_mfma_f32_16x16x32_bf16 v[72:75], v[154:157], v[200:203], 0
	v_mfma_f32_16x16x32_bf16 v[124:127], v[132:135], v[180:183], v[124:127]
	v_mfma_f32_16x16x32_bf16 v[120:123], v[168:171], v[180:183], v[120:123]
	v_mfma_f32_16x16x32_bf16 v[108:111], v[132:135], v[188:191], v[108:111]
	v_mfma_f32_16x16x32_bf16 v[104:107], v[168:171], v[188:191], v[104:107]
	v_mfma_f32_16x16x32_bf16 v[92:95], v[132:135], v[196:199], v[92:95]
	v_mfma_f32_16x16x32_bf16 v[88:91], v[168:171], v[196:199], v[88:91]
	v_mfma_f32_16x16x32_bf16 v[76:79], v[132:135], v[204:207], v[76:79]
	v_mfma_f32_16x16x32_bf16 v[72:75], v[168:171], v[204:207], v[72:75]
	v_mfma_f32_16x16x32_bf16 v[116:119], v[208:211], v[172:175], 0
	v_mfma_f32_16x16x32_bf16 v[112:115], v[216:219], v[172:175], 0
	v_mfma_f32_16x16x32_bf16 v[100:103], v[208:211], v[184:187], 0
	v_mfma_f32_16x16x32_bf16 v[96:99], v[216:219], v[184:187], 0
	v_mfma_f32_16x16x32_bf16 v[84:87], v[208:211], v[192:195], 0
	v_mfma_f32_16x16x32_bf16 v[80:83], v[216:219], v[192:195], 0
	v_mfma_f32_16x16x32_bf16 v[68:71], v[208:211], v[200:203], 0
	v_mfma_f32_16x16x32_bf16 v[64:67], v[216:219], v[200:203], 0
	v_mfma_f32_16x16x32_bf16 v[116:119], v[212:215], v[180:183], v[116:119]
	v_mfma_f32_16x16x32_bf16 v[112:115], v[220:223], v[180:183], v[112:115]
	v_mfma_f32_16x16x32_bf16 v[100:103], v[212:215], v[188:191], v[100:103]
	v_mfma_f32_16x16x32_bf16 v[96:99], v[220:223], v[188:191], v[96:99]
	v_mfma_f32_16x16x32_bf16 v[84:87], v[212:215], v[196:199], v[84:87]
	v_mfma_f32_16x16x32_bf16 v[80:83], v[220:223], v[196:199], v[80:83]
	v_mfma_f32_16x16x32_bf16 v[68:71], v[212:215], v[204:207], v[68:71]
	v_mfma_f32_16x16x32_bf16 v[64:67], v[220:223], v[204:207], v[64:67]
	s_barrier
	s_setprio 0
	s_add_i32 s64, s43, s21
	v_lshl_add_u64 v[158:159], s[16:17], 0, v[140:141]
	s_mov_b32 m0, s64
	s_nop 0
	global_load_lds_dwordx4 v[158:159], off
	v_lshl_add_u64 v[176:177], s[16:17], 0, v[144:145]
	s_add_i32 m0, s64, 0x2000
	s_nop 0
	global_load_lds_dwordx4 v[176:177], off
	s_mov_b32 m0, s30
	v_lshl_add_u64 v[224:225], s[18:19], 0, v[138:139]
	ds_read_b128 v[172:175], v163 offset:16384
	ds_read_b128 v[180:183], v163 offset:17408
	ds_read_b128 v[184:187], v163 offset:18432
	ds_read_b128 v[188:191], v163 offset:19456
	ds_read_b128 v[192:195], v163 offset:20480
	ds_read_b128 v[196:199], v163 offset:21504
	ds_read_b128 v[200:203], v163 offset:22528
	ds_read_b128 v[204:207], v163 offset:23552
	global_load_lds_dwordx4 v[224:225], off
	v_lshl_add_u64 v[226:227], s[18:19], 0, v[142:143]
	s_mov_b32 m0, s31
	s_nop 0
	global_load_lds_dwordx4 v[226:227], off
	s_add_u32 s64, s16, 0x158000
	s_addc_u32 s65, s17, 0
	s_add_i32 s66, s56, s21
	v_lshl_add_u64 v[252:253], s[64:65], 0, v[140:141]
	s_mov_b32 m0, s66
	s_nop 0
	global_load_lds_dwordx4 v[252:253], off
	v_lshl_add_u64 v[252:253], s[64:65], 0, v[144:145]
	s_add_i32 m0, s66, 0x2000
	s_nop 0
	global_load_lds_dwordx4 v[252:253], off
	s_waitcnt lgkmcnt(0)
	s_waitcnt vmcnt(8)
	s_setprio 1
	s_barrier
; #define PG8_STAGE(bufoff, gbase, voff) do { _Pragma("unroll") for (int _i = 0; _i < 2; ++_i) \
;         __builtin_amdgcn_global_load_lds((const unsigned*)((const char*)(gbase) + (voff)[_i]), (LAS unsigned*)(lds + (bufoff) + ldsw + _i * 8192), 16, 0, 0); } while (0)
; #define PG8_LDA(dst, b, h) do { _Pragma("unroll") for (int m = 0; m < 4; ++m) _Pragma("unroll") for (int k = 0; k < 2; ++k) dst[m][k] = *(const LAS bf16x8*)(lds + PG8_SA(b, h) + aoff + m * 2048 + k * 1024); } while (0)
; #define PG8_LDB(dst, b, h) do { _Pragma("unroll") for (int n = 0; n < 2; ++n) _Pragma("unroll") for (int k = 0; k < 2; ++k) dst[n][k] = *(const LAS bf16x8*)(lds + PG8_SB(b, h) + boff + n * 2048 + k * 1024); } while (0)
; #define PG8_WAIT_V(n) asm volatile("s_waitcnt vmcnt(" #n ")" ::: "memory")
; #define PG8_WAIT_L(n) asm volatile("s_waitcnt lgkmcnt(" #n ")" ::: "memory")
; #define PG8_BAR __builtin_amdgcn_s_barrier()
; #define PG8_SCHED __builtin_amdgcn_sched_barrier(0)
; template <class Epi>
; __device__ __forceinline__ void gemm_phase(LAS unsigned char* lds, const Gemm g, const StaticOrder& S, const Epi& E) {
;     ...
;             PG8_LDB(B0, 0, 0); PG8_SCHED; PG8_LDA(At, 0, 0); PG8_STAGE(PG8_SA(1, 1), a1 + hstep, voffA);
;             PG8_WAIT_L(8); PG8_BAR; PG8_WAIT_L(0); PG8_MMA(0, 0, At, B0); PG8_BAR; PG8_SCHED;
;             PG8_LDB(B1, 0, 1); PG8_STAGE(PG8_SB(0, 0), b2, voffB);
;             PG8_BAR; PG8_WAIT_L(0); PG8_MMA(0, 1, At, B1); PG8_BAR;
;             PG8_LDA(At, 0, 1); PG8_STAGE(PG8_SA(0, 0), a2, voffA);
;             PG8_BAR; PG8_WAIT_L(0); PG8_MMA(1, 0, At, B0); PG8_BAR; PG8_SCHED;
;             PG8_STAGE(PG8_SB(0, 1), b2 + hstep, voffB);
;             PG8_WAIT_V(6); PG8_BAR; PG8_MMA(1, 1, At, B1); PG8_BAR;
;             PG8_LDB(B0, 1, 0); PG8_SCHED; PG8_LDA(At, 1, 0); PG8_STAGE(PG8_SA(0, 1), a2 + hstep, voffA);
;             PG8_WAIT_L(8); PG8_BAR; PG8_WAIT_L(0); PG8_MMA(0, 0, At, B0); PG8_BAR; PG8_SCHED;
;             PG8_LDB(B1, 1, 1); PG8_STAGE(PG8_SB(1, 0), b3, voffB);
;             PG8_BAR; PG8_WAIT_L(0); PG8_MMA(0, 1, At, B1); PG8_BAR;
;             PG8_LDA(At, 1, 1); PG8_STAGE(PG8_SA(1, 0), a3, voffA);
;             PG8_BAR; PG8_WAIT_L(0); PG8_MMA(1, 0, At, B0); PG8_BAR; PG8_SCHED;
;             PG8_STAGE(PG8_SB(1, 1), b3 + hstep, voffB);
;             PG8_WAIT_V(6); PG8_BAR; PG8_MMA(1, 1, At, B1); PG8_BAR;
	v_mfma_f32_16x16x32_bf16 v[60:63], v[128:131], v[172:175], 0
	v_mfma_f32_16x16x32_bf16 v[56:59], v[154:157], v[172:175], 0
	v_mfma_f32_16x16x32_bf16 v[44:47], v[128:131], v[184:187], 0
	v_mfma_f32_16x16x32_bf16 v[40:43], v[154:157], v[184:187], 0
	v_mfma_f32_16x16x32_bf16 v[28:31], v[128:131], v[192:195], 0
	v_mfma_f32_16x16x32_bf16 v[24:27], v[154:157], v[192:195], 0
	v_mfma_f32_16x16x32_bf16 v[12:15], v[128:131], v[200:203], 0
	v_mfma_f32_16x16x32_bf16 v[8:11], v[154:157], v[200:203], 0
	v_mfma_f32_16x16x32_bf16 v[60:63], v[132:135], v[180:183], v[60:63]
	v_mfma_f32_16x16x32_bf16 v[56:59], v[168:171], v[180:183], v[56:59]
	v_mfma_f32_16x16x32_bf16 v[44:47], v[132:135], v[188:191], v[44:47]
	v_mfma_f32_16x16x32_bf16 v[40:43], v[168:171], v[188:191], v[40:43]
	v_mfma_f32_16x16x32_bf16 v[28:31], v[132:135], v[196:199], v[28:31]
	v_mfma_f32_16x16x32_bf16 v[24:27], v[168:171], v[196:199], v[24:27]
	v_mfma_f32_16x16x32_bf16 v[12:15], v[132:135], v[204:207], v[12:15]
	v_mfma_f32_16x16x32_bf16 v[8:11], v[168:171], v[204:207], v[8:11]
	v_mfma_f32_16x16x32_bf16 v[52:55], v[208:211], v[172:175], 0
	v_mfma_f32_16x16x32_bf16 v[48:51], v[216:219], v[172:175], 0
	v_mfma_f32_16x16x32_bf16 v[36:39], v[208:211], v[184:187], 0
	v_mfma_f32_16x16x32_bf16 v[32:35], v[216:219], v[184:187], 0
	v_mfma_f32_16x16x32_bf16 v[20:23], v[208:211], v[192:195], 0
	v_mfma_f32_16x16x32_bf16 v[16:19], v[216:219], v[192:195], 0
	v_mfma_f32_16x16x32_bf16 v[4:7], v[208:211], v[200:203], 0
	v_mfma_f32_16x16x32_bf16 v[0:3], v[216:219], v[200:203], 0
	v_mfma_f32_16x16x32_bf16 v[52:55], v[212:215], v[180:183], v[52:55]
	v_mfma_f32_16x16x32_bf16 v[48:51], v[220:223], v[180:183], v[48:51]
	v_mfma_f32_16x16x32_bf16 v[36:39], v[212:215], v[188:191], v[36:39]
	v_mfma_f32_16x16x32_bf16 v[32:35], v[220:223], v[188:191], v[32:35]
	v_mfma_f32_16x16x32_bf16 v[20:23], v[212:215], v[196:199], v[20:23]
	v_mfma_f32_16x16x32_bf16 v[16:19], v[220:223], v[196:199], v[16:19]
	v_mfma_f32_16x16x32_bf16 v[4:7], v[212:215], v[204:207], v[4:7]
	v_mfma_f32_16x16x32_bf16 v[0:3], v[220:223], v[204:207], v[0:3]
	s_barrier
	s_setprio 0
	s_add_i32 s64, 0, 0x18000
	v_add_u32_e32 v167, s64, v137
	ds_read_b128 v[128:131], v167
	ds_read_b128 v[132:135], v167 offset:1024
	ds_read_b128 v[154:157], v167 offset:2048
	ds_read_b128 v[168:171], v167 offset:3072
	s_add_u32 s18, s18, 0x158000
	s_addc_u32 s19, s19, 0
	s_mov_b32 m0, s33
	v_lshl_add_u64 v[208:209], s[18:19], 0, v[138:139]
	ds_read_b128 v[172:175], v163 offset:32768
	ds_read_b128 v[180:183], v163 offset:33792
	ds_read_b128 v[184:187], v163 offset:34816
	ds_read_b128 v[188:191], v163 offset:35840
	ds_read_b128 v[192:195], v163 offset:36864
	ds_read_b128 v[196:199], v163 offset:37888
	ds_read_b128 v[200:203], v163 offset:38912
	ds_read_b128 v[204:207], v163 offset:39936
	global_load_lds_dwordx4 v[208:209], off
	v_lshl_add_u64 v[208:209], s[18:19], 0, v[142:143]
	s_mov_b32 m0, s34
	s_nop 0
	global_load_lds_dwordx4 v[208:209], off
	s_add_i32 s18, 0, 0x1c000
	v_add_u32_e32 v167, s18, v137
	ds_read_b128 v[208:211], v167
	ds_read_b128 v[212:215], v167 offset:1024
	ds_read_b128 v[216:219], v167 offset:2048
	ds_read_b128 v[220:223], v167 offset:3072
	s_waitcnt lgkmcnt(0)
	s_waitcnt vmcnt(8)
	s_setprio 1
	s_barrier
	v_mfma_f32_16x16x32_bf16 v[124:127], v[128:131], v[172:175], v[124:127]
	v_mfma_f32_16x16x32_bf16 v[120:123], v[154:157], v[172:175], v[120:123]
	v_mfma_f32_16x16x32_bf16 v[108:111], v[128:131], v[184:187], v[108:111]
	v_mfma_f32_16x16x32_bf16 v[104:107], v[154:157], v[184:187], v[104:107]
	v_mfma_f32_16x16x32_bf16 v[92:95], v[128:131], v[192:195], v[92:95]
	v_mfma_f32_16x16x32_bf16 v[88:91], v[154:157], v[192:195], v[88:91]
	v_mfma_f32_16x16x32_bf16 v[76:79], v[128:131], v[200:203], v[76:79]
	v_mfma_f32_16x16x32_bf16 v[72:75], v[154:157], v[200:203], v[72:75]
	v_mfma_f32_16x16x32_bf16 v[124:127], v[132:135], v[180:183], v[124:127]
	v_mfma_f32_16x16x32_bf16 v[120:123], v[168:171], v[180:183], v[120:123]
	v_mfma_f32_16x16x32_bf16 v[108:111], v[132:135], v[188:191], v[108:111]
	v_mfma_f32_16x16x32_bf16 v[104:107], v[168:171], v[188:191], v[104:107]
	v_mfma_f32_16x16x32_bf16 v[92:95], v[132:135], v[196:199], v[92:95]
	v_mfma_f32_16x16x32_bf16 v[88:91], v[168:171], v[196:199], v[88:91]
	v_mfma_f32_16x16x32_bf16 v[76:79], v[132:135], v[204:207], v[76:79]
	v_mfma_f32_16x16x32_bf16 v[72:75], v[168:171], v[204:207], v[72:75]
	v_mfma_f32_16x16x32_bf16 v[116:119], v[208:211], v[172:175], v[116:119]
	v_mfma_f32_16x16x32_bf16 v[112:115], v[216:219], v[172:175], v[112:115]
	v_mfma_f32_16x16x32_bf16 v[100:103], v[208:211], v[184:187], v[100:103]
	v_mfma_f32_16x16x32_bf16 v[96:99], v[216:219], v[184:187], v[96:99]
	v_mfma_f32_16x16x32_bf16 v[84:87], v[208:211], v[192:195], v[84:87]
	v_mfma_f32_16x16x32_bf16 v[80:83], v[216:219], v[192:195], v[80:83]
	v_mfma_f32_16x16x32_bf16 v[68:71], v[208:211], v[200:203], v[68:71]
	v_mfma_f32_16x16x32_bf16 v[64:67], v[216:219], v[200:203], v[64:67]
	v_mfma_f32_16x16x32_bf16 v[116:119], v[212:215], v[180:183], v[116:119]
	v_mfma_f32_16x16x32_bf16 v[112:115], v[220:223], v[180:183], v[112:115]
	v_mfma_f32_16x16x32_bf16 v[100:103], v[212:215], v[188:191], v[100:103]
	v_mfma_f32_16x16x32_bf16 v[96:99], v[220:223], v[188:191], v[96:99]
	v_mfma_f32_16x16x32_bf16 v[84:87], v[212:215], v[196:199], v[84:87]
	v_mfma_f32_16x16x32_bf16 v[80:83], v[220:223], v[196:199], v[80:83]
	v_mfma_f32_16x16x32_bf16 v[68:71], v[212:215], v[204:207], v[68:71]
	v_mfma_f32_16x16x32_bf16 v[64:67], v[220:223], v[204:207], v[64:67]
	s_barrier
; #define PG8_STAGE(bufoff, gbase, voff) do { _Pragma("unroll") for (int _i = 0; _i < 2; ++_i) \
;         __builtin_amdgcn_global_load_lds((const unsigned*)((const char*)(gbase) + (voff)[_i]), (LAS unsigned*)(lds + (bufoff) + ldsw + _i * 8192), 16, 0, 0); } while (0)
; #define PG8_LDA(dst, b, h) do { _Pragma("unroll") for (int m = 0; m < 4; ++m) _Pragma("unroll") for (int k = 0; k < 2; ++k) dst[m][k] = *(const LAS bf16x8*)(lds + PG8_SA(b, h) + aoff + m * 2048 + k * 1024); } while (0)
; #define PG8_LDB(dst, b, h) do { _Pragma("unroll") for (int n = 0; n < 2; ++n) _Pragma("unroll") for (int k = 0; k < 2; ++k) dst[n][k] = *(const LAS bf16x8*)(lds + PG8_SB(b, h) + boff + n * 2048 + k * 1024); } while (0)
; #define PG8_MMA(ai, bj, At, Bt) do { __builtin_amdgcn_s_setprio(1); _Pragma("unroll") for (int m = 0; m < 4; ++m) _Pragma("unroll") for (int n = 0; n < 2; ++n) _Pragma("unroll") for (int k = 0; k < 2; ++k) \
;         acc[ai][bj][m][n] = __builtin_amdgcn_mfma_f32_16x16x32_bf16(Bt[n][k], At[m][k], acc[ai][bj][m][n], 0, 0, 0); __builtin_amdgcn_s_setprio(0); } while (0)
; #define PG8_WAIT_V(n) asm volatile("s_waitcnt vmcnt(" #n ")" ::: "memory")
; #define PG8_WAIT_L(n) asm volatile("s_waitcnt lgkmcnt(" #n ")" ::: "memory")
; #define PG8_BAR __builtin_amdgcn_s_barrier()
; #define PG8_SCHED __builtin_amdgcn_sched_barrier(0)
; template <class Epi>
; __device__ __forceinline__ void gemm_phase(LAS unsigned char* lds, const Gemm g, const StaticOrder& S, const Epi& E) {
;     ...
;             PG8_LDB(B0, 1, 0); PG8_SCHED; PG8_LDA(At, 1, 0); PG8_STAGE(PG8_SA(0, 1), a2 + hstep, voffA);
;             PG8_WAIT_L(8); PG8_BAR; PG8_WAIT_L(0); PG8_MMA(0, 0, At, B0); PG8_BAR; PG8_SCHED;
;             PG8_LDB(B1, 1, 1); PG8_STAGE(PG8_SB(1, 0), b3, voffB);
;             PG8_BAR; PG8_WAIT_L(0); PG8_MMA(0, 1, At, B1); PG8_BAR;
;             PG8_LDA(At, 1, 1); PG8_STAGE(PG8_SA(1, 0), a3, voffA);
;             PG8_BAR; PG8_WAIT_L(0); PG8_MMA(1, 0, At, B0); PG8_BAR; PG8_SCHED;
;             PG8_STAGE(PG8_SB(1, 1), b3 + hstep, voffB);
;             PG8_WAIT_V(6); PG8_BAR; PG8_MMA(1, 1, At, B1); PG8_BAR;
	s_setprio 0
	s_add_i32 s19, s64, s21
	v_lshl_add_u64 v[158:159], v[158:159], 0, s[12:13]
	s_mov_b32 m0, s19
	s_nop 0
	global_load_lds_dwordx4 v[158:159], off
	v_lshl_add_u64 v[158:159], v[176:177], 0, s[12:13]
	s_add_i32 m0, s19, 0x2000
	s_nop 0
	global_load_lds_dwordx4 v[158:159], off
	s_mov_b32 m0, s36
	v_lshl_add_u64 v[158:159], v[224:225], 0, s[12:13]
	ds_read_b128 v[172:175], v163 offset:49152
	ds_read_b128 v[180:183], v163 offset:50176
	ds_read_b128 v[184:187], v163 offset:51200
	ds_read_b128 v[188:191], v163 offset:52224
	ds_read_b128 v[192:195], v163 offset:53248
	ds_read_b128 v[196:199], v163 offset:54272
	ds_read_b128 v[200:203], v163 offset:55296
	ds_read_b128 v[204:207], v163 offset:56320
	global_load_lds_dwordx4 v[158:159], off
	v_lshl_add_u64 v[158:159], v[226:227], 0, s[12:13]
	s_mov_b32 m0, s37
	s_nop 0
	global_load_lds_dwordx4 v[158:159], off
	s_add_u32 s16, s16, 0x158080
	s_addc_u32 s17, s17, 0
	s_add_i32 s18, s18, s21
	v_lshl_add_u64 v[252:253], s[16:17], 0, v[140:141]
	s_mov_b32 m0, s18
	s_nop 0
	global_load_lds_dwordx4 v[252:253], off
	v_lshl_add_u64 v[252:253], s[16:17], 0, v[144:145]
	s_add_i32 m0, s18, 0x2000
	s_nop 0
	global_load_lds_dwordx4 v[252:253], off
	s_waitcnt lgkmcnt(0)
	s_waitcnt vmcnt(8)
	s_setprio 1
	s_barrier
	v_mfma_f32_16x16x32_bf16 v[60:63], v[128:131], v[172:175], v[60:63]
	v_mfma_f32_16x16x32_bf16 v[56:59], v[154:157], v[172:175], v[56:59]
	v_mfma_f32_16x16x32_bf16 v[44:47], v[128:131], v[184:187], v[44:47]
	v_mfma_f32_16x16x32_bf16 v[40:43], v[154:157], v[184:187], v[40:43]
	v_mfma_f32_16x16x32_bf16 v[28:31], v[128:131], v[192:195], v[28:31]
	v_mfma_f32_16x16x32_bf16 v[24:27], v[154:157], v[192:195], v[24:27]
	v_mfma_f32_16x16x32_bf16 v[12:15], v[128:131], v[200:203], v[12:15]
	v_mfma_f32_16x16x32_bf16 v[8:11], v[154:157], v[200:203], v[8:11]
	v_mfma_f32_16x16x32_bf16 v[60:63], v[132:135], v[180:183], v[60:63]
	v_mfma_f32_16x16x32_bf16 v[56:59], v[168:171], v[180:183], v[56:59]
	v_mfma_f32_16x16x32_bf16 v[44:47], v[132:135], v[188:191], v[44:47]
	v_mfma_f32_16x16x32_bf16 v[40:43], v[168:171], v[188:191], v[40:43]
	v_mfma_f32_16x16x32_bf16 v[28:31], v[132:135], v[196:199], v[28:31]
	v_mfma_f32_16x16x32_bf16 v[24:27], v[168:171], v[196:199], v[24:27]
	v_mfma_f32_16x16x32_bf16 v[12:15], v[132:135], v[204:207], v[12:15]
	v_mfma_f32_16x16x32_bf16 v[8:11], v[168:171], v[204:207], v[8:11]
	v_mfma_f32_16x16x32_bf16 v[52:55], v[208:211], v[172:175], v[52:55]
	v_mfma_f32_16x16x32_bf16 v[48:51], v[216:219], v[172:175], v[48:51]
	v_mfma_f32_16x16x32_bf16 v[36:39], v[208:211], v[184:187], v[36:39]
	v_mfma_f32_16x16x32_bf16 v[32:35], v[216:219], v[184:187], v[32:35]
	v_mfma_f32_16x16x32_bf16 v[20:23], v[208:211], v[192:195], v[20:23]
	v_mfma_f32_16x16x32_bf16 v[16:19], v[216:219], v[192:195], v[16:19]
	v_mfma_f32_16x16x32_bf16 v[4:7], v[208:211], v[200:203], v[4:7]
	v_mfma_f32_16x16x32_bf16 v[0:3], v[216:219], v[200:203], v[0:3]
	v_mfma_f32_16x16x32_bf16 v[52:55], v[212:215], v[180:183], v[52:55]
	v_mfma_f32_16x16x32_bf16 v[48:51], v[220:223], v[180:183], v[48:51]
	v_mfma_f32_16x16x32_bf16 v[36:39], v[212:215], v[188:191], v[36:39]
	v_mfma_f32_16x16x32_bf16 v[32:35], v[220:223], v[188:191], v[32:35]
	v_mfma_f32_16x16x32_bf16 v[20:23], v[212:215], v[196:199], v[20:23]
	v_mfma_f32_16x16x32_bf16 v[16:19], v[220:223], v[196:199], v[16:19]
	v_mfma_f32_16x16x32_bf16 v[4:7], v[212:215], v[204:207], v[4:7]
	v_mfma_f32_16x16x32_bf16 v[0:3], v[220:223], v[204:207], v[0:3]
	s_barrier
	s_setprio 0
	s_add_i32 s63, s63, 2
	s_add_u32 s14, s14, 0x100
	s_addc_u32 s15, s15, 0
	s_add_u32 s61, s61, 0x100
	s_addc_u32 s62, s62, 0
	s_cmpk_gt_u32 s63, 0x53
	.p2align	6

; #define PG8_STAGE(bufoff, gbase, voff) do { _Pragma("unroll") for (int _i = 0; _i < 2; ++_i) \
;         __builtin_amdgcn_global_load_lds((const unsigned*)((const char*)(gbase) + (voff)[_i]), (LAS unsigned*)(lds + (bufoff) + ldsw + _i * 8192), 16, 0, 0); } while (0)
; #define PG8_LDA(dst, b, h) do { _Pragma("unroll") for (int m = 0; m < 4; ++m) _Pragma("unroll") for (int k = 0; k < 2; ++k) dst[m][k] = *(const LAS bf16x8*)(lds + PG8_SA(b, h) + aoff + m * 2048 + k * 1024); } while (0)
; #define PG8_LDB(dst, b, h) do { _Pragma("unroll") for (int n = 0; n < 2; ++n) _Pragma("unroll") for (int k = 0; k < 2; ++k) dst[n][k] = *(const LAS bf16x8*)(lds + PG8_SB(b, h) + boff + n * 2048 + k * 1024); } while (0)
; template <class Epi>
; __device__ __forceinline__ void gemm_phase(LAS unsigned char* lds, const Gemm g, const StaticOrder& S, const Epi& E) {
;     ...
;     for (;;) {
;         const bool has_next = S.next(ui + 1, nxt);
;         const char* nA = has_next ? (const char*)g.A + (size_t)nxt.pm * tstep : cA; const char* nB = has_next ? (const char*)g.Bt + (size_t)nxt.pn * tstep : cB;
;         for (int t = 0; t < nt; t += 2) {
;             const bool last = (t == nt - 2);
;             const char* a1 = cA + (size_t)(t + 1) * kstep;
;             const char* a2 = last ? nA : cA + (size_t)(t + 2) * kstep; const char* b2 = last ? nB : cB + (size_t)(t + 2) * kstep;
;             const char* a3 = a2 + kstep; const char* b3 = b2 + kstep;
;             PG8_LDB(B0, 0, 0); PG8_SCHED; PG8_LDA(At, 0, 0); PG8_STAGE(PG8_SA(1, 1), a1 + hstep, voffA);
;             PG8_WAIT_L(8); PG8_BAR; PG8_WAIT_L(0); PG8_MMA(0, 0, At, B0); PG8_BAR; PG8_SCHED;
;             PG8_LDB(B1, 0, 1); PG8_STAGE(PG8_SB(0, 0), b2, voffB);
;             PG8_BAR; PG8_WAIT_L(0); PG8_MMA(0, 1, At, B1); PG8_BAR;
;             PG8_LDA(At, 0, 1); PG8_STAGE(PG8_SA(0, 0), a2, voffA);
;             PG8_BAR; PG8_WAIT_L(0); PG8_MMA(1, 0, At, B0); PG8_BAR; PG8_SCHED;
;             PG8_STAGE(PG8_SB(0, 1), b2 + hstep, voffB);
;             PG8_WAIT_V(6); PG8_BAR; PG8_MMA(1, 1, At, B1); PG8_BAR;
;     ...
; #pragma unroll
;         for (int a = 0; a < 2; ++a)
; #pragma unroll
;             for (int b = 0; b < 2; ++b)
; #pragma unroll
;                 for (int m = 0; m < 4; ++m)
; #pragma unroll
;                     for (int n = 0; n < 2; ++n) acc[a][b][m][n] = (f32x4){0.f, 0.f, 0.f, 0.f};
.LBB0_1795:
	s_ashr_i32 s37, s36, 31
	s_lshl_b64 s[8:9], s[36:37], 20
	s_add_u32 s38, s58, s8
	v_cmp_lt_i64_e64 s[2:3], s[2:3], v[146:147]
	s_addc_u32 s39, s59, s9
	s_and_b64 s[8:9], s[2:3], exec
	s_cselect_b32 s1, s39, s7
	s_cselect_b32 s5, s38, s6
	s_ashr_i32 s35, s34, 31
	s_lshl_b64 s[8:9], s[34:35], 20
	s_add_u32 s40, s60, s8
	s_addc_u32 s41, s61, s9
	s_and_b64 s[8:9], s[2:3], exec
	s_cselect_b32 s12, s41, s11
	s_cselect_b32 s13, s40, s10
	s_add_u32 s6, s6, 0x80080
	s_addc_u32 s7, s7, 0
	s_add_u32 s33, s10, 0x100
	s_addc_u32 s35, s11, 0
	s_mov_b32 s37, -2
	ds_read_b128 v[172:175], v157
	ds_read_b128 v[180:183], v157 offset:1024
	ds_read_b128 v[184:187], v157 offset:2048
	ds_read_b128 v[188:191], v157 offset:3072
	s_add_u32 s8, s6, 0xfff80080
	s_addc_u32 s9, s7, -1
	s_cmp_eq_u32 s37, 28
	s_cselect_b32 s11, s1, s9
	s_cselect_b32 s10, s5, s8
	s_cselect_b32 s9, s12, s35
	s_cselect_b32 s8, s13, s33
	v_lshl_add_u64 v[152:153], s[6:7], 0, v[142:143]
	s_add_i32 m0, s62, 0xc000
	ds_read_b128 v[192:195], v158
	ds_read_b128 v[196:199], v158 offset:1024
	ds_read_b128 v[200:203], v158 offset:2048
	ds_read_b128 v[204:207], v158 offset:3072
	ds_read_b128 v[208:211], v158 offset:4096
	ds_read_b128 v[212:215], v158 offset:5120
	ds_read_b128 v[216:219], v158 offset:6144
	ds_read_b128 v[220:223], v158 offset:7168
	global_load_lds_dwordx4 v[152:153], off
	v_lshl_add_u64 v[152:153], s[6:7], 0, v[144:145]
	s_add_i32 m0, s62, 0xe000
	s_nop 0
	global_load_lds_dwordx4 v[152:153], off
	ds_read_b128 v[224:227], v159
	ds_read_b128 v[228:231], v159 offset:1024
	ds_read_b128 v[232:235], v159 offset:2048
	ds_read_b128 v[236:239], v159 offset:3072
	s_waitcnt lgkmcnt(0)
	s_waitcnt vmcnt(8)
	s_setprio 1
	s_barrier
	v_mfma_f32_16x16x32_bf16 v[116:119], v[172:175], v[192:195], 0
	v_mfma_f32_16x16x32_bf16 v[112:115], v[184:187], v[192:195], 0
	v_mfma_f32_16x16x32_bf16 v[100:103], v[172:175], v[200:203], 0
	v_mfma_f32_16x16x32_bf16 v[96:99], v[184:187], v[200:203], 0
	v_mfma_f32_16x16x32_bf16 v[84:87], v[172:175], v[208:211], 0
	v_mfma_f32_16x16x32_bf16 v[80:83], v[184:187], v[208:211], 0
	v_mfma_f32_16x16x32_bf16 v[68:71], v[172:175], v[216:219], 0
	v_mfma_f32_16x16x32_bf16 v[64:67], v[184:187], v[216:219], 0
	v_mfma_f32_16x16x32_bf16 v[116:119], v[180:183], v[196:199], v[116:119]
	v_mfma_f32_16x16x32_bf16 v[112:115], v[188:191], v[196:199], v[112:115]
	v_mfma_f32_16x16x32_bf16 v[100:103], v[180:183], v[204:207], v[100:103]
	v_mfma_f32_16x16x32_bf16 v[96:99], v[188:191], v[204:207], v[96:99]
	v_mfma_f32_16x16x32_bf16 v[84:87], v[180:183], v[212:215], v[84:87]
	v_mfma_f32_16x16x32_bf16 v[80:83], v[188:191], v[212:215], v[80:83]
	v_mfma_f32_16x16x32_bf16 v[68:71], v[180:183], v[220:223], v[68:71]
	v_mfma_f32_16x16x32_bf16 v[64:67], v[188:191], v[220:223], v[64:67]
	v_mfma_f32_16x16x32_bf16 v[124:127], v[224:227], v[192:195], 0
	v_mfma_f32_16x16x32_bf16 v[120:123], v[232:235], v[192:195], 0
	v_mfma_f32_16x16x32_bf16 v[108:111], v[224:227], v[200:203], 0
	v_mfma_f32_16x16x32_bf16 v[104:107], v[232:235], v[200:203], 0
	v_mfma_f32_16x16x32_bf16 v[92:95], v[224:227], v[208:211], 0
	v_mfma_f32_16x16x32_bf16 v[88:91], v[232:235], v[208:211], 0
	v_mfma_f32_16x16x32_bf16 v[76:79], v[224:227], v[216:219], 0
	v_mfma_f32_16x16x32_bf16 v[72:75], v[232:235], v[216:219], 0
	v_mfma_f32_16x16x32_bf16 v[124:127], v[228:231], v[196:199], v[124:127]
	v_mfma_f32_16x16x32_bf16 v[120:123], v[236:239], v[196:199], v[120:123]
	v_mfma_f32_16x16x32_bf16 v[108:111], v[228:231], v[204:207], v[108:111]
	v_mfma_f32_16x16x32_bf16 v[104:107], v[236:239], v[204:207], v[104:107]
	v_mfma_f32_16x16x32_bf16 v[92:95], v[228:231], v[212:215], v[92:95]
	v_mfma_f32_16x16x32_bf16 v[88:91], v[236:239], v[212:215], v[88:91]
	v_mfma_f32_16x16x32_bf16 v[76:79], v[228:231], v[220:223], v[76:79]
	v_mfma_f32_16x16x32_bf16 v[72:75], v[236:239], v[220:223], v[72:75]
	s_barrier
	s_setprio 0
	s_add_i32 s42, s72, s57
	v_lshl_add_u64 v[152:153], s[8:9], 0, v[130:131]
	s_mov_b32 m0, s42
	s_nop 0
	global_load_lds_dwordx4 v[152:153], off
	v_lshl_add_u64 v[176:177], s[8:9], 0, v[134:135]
	s_add_i32 m0, s42, 0x2000
	s_nop 0
	global_load_lds_dwordx4 v[176:177], off
	s_mov_b32 m0, s62
	v_lshl_add_u64 v[240:241], s[10:11], 0, v[128:129]
	ds_read_b128 v[192:195], v158 offset:16384
	ds_read_b128 v[196:199], v158 offset:17408
	ds_read_b128 v[200:203], v158 offset:18432
	ds_read_b128 v[204:207], v158 offset:19456
	ds_read_b128 v[208:211], v158 offset:20480
	ds_read_b128 v[212:215], v158 offset:21504
	ds_read_b128 v[216:219], v158 offset:22528
	ds_read_b128 v[220:223], v158 offset:23552
	global_load_lds_dwordx4 v[240:241], off
	v_lshl_add_u64 v[242:243], s[10:11], 0, v[132:133]
	s_mov_b32 m0, s63
	s_nop 0
	global_load_lds_dwordx4 v[242:243], off
	s_add_u32 s42, s8, 0x80000
	s_addc_u32 s43, s9, 0
	s_add_i32 s78, s73, s57
	v_lshl_add_u64 v[252:253], s[42:43], 0, v[130:131]
	s_mov_b32 m0, s78
	s_nop 0
	global_load_lds_dwordx4 v[252:253], off
	v_lshl_add_u64 v[252:253], s[42:43], 0, v[134:135]
	s_add_i32 m0, s78, 0x2000
	s_nop 0
	global_load_lds_dwordx4 v[252:253], off
	s_waitcnt lgkmcnt(0)
	s_waitcnt vmcnt(8)
	s_setprio 1
	s_barrier
; #define PG8_STAGE(bufoff, gbase, voff) do { _Pragma("unroll") for (int _i = 0; _i < 2; ++_i) \
;         __builtin_amdgcn_global_load_lds((const unsigned*)((const char*)(gbase) + (voff)[_i]), (LAS unsigned*)(lds + (bufoff) + ldsw + _i * 8192), 16, 0, 0); } while (0)
; #define PG8_LDA(dst, b, h) do { _Pragma("unroll") for (int m = 0; m < 4; ++m) _Pragma("unroll") for (int k = 0; k < 2; ++k) dst[m][k] = *(const LAS bf16x8*)(lds + PG8_SA(b, h) + aoff + m * 2048 + k * 1024); } while (0)
; #define PG8_LDB(dst, b, h) do { _Pragma("unroll") for (int n = 0; n < 2; ++n) _Pragma("unroll") for (int k = 0; k < 2; ++k) dst[n][k] = *(const LAS bf16x8*)(lds + PG8_SB(b, h) + boff + n * 2048 + k * 1024); } while (0)
; #define PG8_WAIT_V(n) asm volatile("s_waitcnt vmcnt(" #n ")" ::: "memory")
; #define PG8_WAIT_L(n) asm volatile("s_waitcnt lgkmcnt(" #n ")" ::: "memory")
; #define PG8_BAR __builtin_amdgcn_s_barrier()
; #define PG8_SCHED __builtin_amdgcn_sched_barrier(0)
; template <class Epi>
; __device__ __forceinline__ void gemm_phase(LAS unsigned char* lds, const Gemm g, const StaticOrder& S, const Epi& E) {
;     ...
;             PG8_LDB(B0, 0, 0); PG8_SCHED; PG8_LDA(At, 0, 0); PG8_STAGE(PG8_SA(1, 1), a1 + hstep, voffA);
;             PG8_WAIT_L(8); PG8_BAR; PG8_WAIT_L(0); PG8_MMA(0, 0, At, B0); PG8_BAR; PG8_SCHED;
;             PG8_LDB(B1, 0, 1); PG8_STAGE(PG8_SB(0, 0), b2, voffB);
;             PG8_BAR; PG8_WAIT_L(0); PG8_MMA(0, 1, At, B1); PG8_BAR;
;             PG8_LDA(At, 0, 1); PG8_STAGE(PG8_SA(0, 0), a2, voffA);
;             PG8_BAR; PG8_WAIT_L(0); PG8_MMA(1, 0, At, B0); PG8_BAR; PG8_SCHED;
;             PG8_STAGE(PG8_SB(0, 1), b2 + hstep, voffB);
;             PG8_WAIT_V(6); PG8_BAR; PG8_MMA(1, 1, At, B1); PG8_BAR;
;             PG8_LDB(B0, 1, 0); PG8_SCHED; PG8_LDA(At, 1, 0); PG8_STAGE(PG8_SA(0, 1), a2 + hstep, voffA);
;             PG8_WAIT_L(8); PG8_BAR; PG8_WAIT_L(0); PG8_MMA(0, 0, At, B0); PG8_BAR; PG8_SCHED;
;             PG8_LDB(B1, 1, 1); PG8_STAGE(PG8_SB(1, 0), b3, voffB);
;             PG8_BAR; PG8_WAIT_L(0); PG8_MMA(0, 1, At, B1); PG8_BAR;
;             PG8_LDA(At, 1, 1); PG8_STAGE(PG8_SA(1, 0), a3, voffA);
;             PG8_BAR; PG8_WAIT_L(0); PG8_MMA(1, 0, At, B0); PG8_BAR; PG8_SCHED;
;             PG8_STAGE(PG8_SB(1, 1), b3 + hstep, voffB);
;             PG8_WAIT_V(6); PG8_BAR; PG8_MMA(1, 1, At, B1); PG8_BAR;
	v_mfma_f32_16x16x32_bf16 v[52:55], v[172:175], v[192:195], 0
	v_mfma_f32_16x16x32_bf16 v[48:51], v[184:187], v[192:195], 0
	v_mfma_f32_16x16x32_bf16 v[36:39], v[172:175], v[200:203], 0
	v_mfma_f32_16x16x32_bf16 v[32:35], v[184:187], v[200:203], 0
	v_mfma_f32_16x16x32_bf16 v[20:23], v[172:175], v[208:211], 0
	v_mfma_f32_16x16x32_bf16 v[16:19], v[184:187], v[208:211], 0
	v_mfma_f32_16x16x32_bf16 v[4:7], v[172:175], v[216:219], 0
	v_mfma_f32_16x16x32_bf16 v[0:3], v[184:187], v[216:219], 0
	v_mfma_f32_16x16x32_bf16 v[52:55], v[180:183], v[196:199], v[52:55]
	v_mfma_f32_16x16x32_bf16 v[48:51], v[188:191], v[196:199], v[48:51]
	v_mfma_f32_16x16x32_bf16 v[36:39], v[180:183], v[204:207], v[36:39]
	v_mfma_f32_16x16x32_bf16 v[32:35], v[188:191], v[204:207], v[32:35]
	v_mfma_f32_16x16x32_bf16 v[20:23], v[180:183], v[212:215], v[20:23]
	v_mfma_f32_16x16x32_bf16 v[16:19], v[188:191], v[212:215], v[16:19]
	v_mfma_f32_16x16x32_bf16 v[4:7], v[180:183], v[220:223], v[4:7]
	v_mfma_f32_16x16x32_bf16 v[0:3], v[188:191], v[220:223], v[0:3]
	v_mfma_f32_16x16x32_bf16 v[60:63], v[224:227], v[192:195], 0
	v_mfma_f32_16x16x32_bf16 v[56:59], v[232:235], v[192:195], 0
	v_mfma_f32_16x16x32_bf16 v[44:47], v[224:227], v[200:203], 0
	v_mfma_f32_16x16x32_bf16 v[40:43], v[232:235], v[200:203], 0
	v_mfma_f32_16x16x32_bf16 v[28:31], v[224:227], v[208:211], 0
	v_mfma_f32_16x16x32_bf16 v[24:27], v[232:235], v[208:211], 0
	v_mfma_f32_16x16x32_bf16 v[12:15], v[224:227], v[216:219], 0
	v_mfma_f32_16x16x32_bf16 v[8:11], v[232:235], v[216:219], 0
	v_mfma_f32_16x16x32_bf16 v[60:63], v[228:231], v[196:199], v[60:63]
	v_mfma_f32_16x16x32_bf16 v[56:59], v[236:239], v[196:199], v[56:59]
	v_mfma_f32_16x16x32_bf16 v[44:47], v[228:231], v[204:207], v[44:47]
	v_mfma_f32_16x16x32_bf16 v[40:43], v[236:239], v[204:207], v[40:43]
	v_mfma_f32_16x16x32_bf16 v[28:31], v[228:231], v[212:215], v[28:31]
	v_mfma_f32_16x16x32_bf16 v[24:27], v[236:239], v[212:215], v[24:27]
	v_mfma_f32_16x16x32_bf16 v[12:15], v[228:231], v[220:223], v[12:15]
	v_mfma_f32_16x16x32_bf16 v[8:11], v[236:239], v[220:223], v[8:11]
	s_barrier
	s_setprio 0
	s_add_i32 s42, 0, 0x18000
	v_add_u32_e32 v136, s42, v155
	ds_read_b128 v[172:175], v136
	ds_read_b128 v[180:183], v136 offset:1024
	ds_read_b128 v[184:187], v136 offset:2048
	ds_read_b128 v[188:191], v136 offset:3072
	s_add_u32 s10, s10, 0x80000
	s_addc_u32 s11, s11, 0
	s_mov_b32 m0, s64
	v_lshl_add_u64 v[224:225], s[10:11], 0, v[128:129]
	ds_read_b128 v[192:195], v158 offset:32768
	ds_read_b128 v[196:199], v158 offset:33792
	ds_read_b128 v[200:203], v158 offset:34816
	ds_read_b128 v[204:207], v158 offset:35840
	ds_read_b128 v[208:211], v158 offset:36864
	ds_read_b128 v[212:215], v158 offset:37888
	ds_read_b128 v[216:219], v158 offset:38912
	ds_read_b128 v[220:223], v158 offset:39936
	global_load_lds_dwordx4 v[224:225], off
	v_lshl_add_u64 v[224:225], s[10:11], 0, v[132:133]
	s_mov_b32 m0, s65
	s_nop 0
	global_load_lds_dwordx4 v[224:225], off
	s_add_i32 s10, 0, 0x1c000
	v_add_u32_e32 v136, s10, v155
	ds_read_b128 v[224:227], v136
	ds_read_b128 v[228:231], v136 offset:1024
	ds_read_b128 v[232:235], v136 offset:2048
	ds_read_b128 v[236:239], v136 offset:3072
	s_waitcnt lgkmcnt(0)
	s_waitcnt vmcnt(8)
	s_setprio 1
	s_barrier
	v_mfma_f32_16x16x32_bf16 v[116:119], v[172:175], v[192:195], v[116:119]
	v_mfma_f32_16x16x32_bf16 v[112:115], v[184:187], v[192:195], v[112:115]
	v_mfma_f32_16x16x32_bf16 v[100:103], v[172:175], v[200:203], v[100:103]
	v_mfma_f32_16x16x32_bf16 v[96:99], v[184:187], v[200:203], v[96:99]
	v_mfma_f32_16x16x32_bf16 v[84:87], v[172:175], v[208:211], v[84:87]
	v_mfma_f32_16x16x32_bf16 v[80:83], v[184:187], v[208:211], v[80:83]
	v_mfma_f32_16x16x32_bf16 v[68:71], v[172:175], v[216:219], v[68:71]
	v_mfma_f32_16x16x32_bf16 v[64:67], v[184:187], v[216:219], v[64:67]
	v_mfma_f32_16x16x32_bf16 v[116:119], v[180:183], v[196:199], v[116:119]
	v_mfma_f32_16x16x32_bf16 v[112:115], v[188:191], v[196:199], v[112:115]
	v_mfma_f32_16x16x32_bf16 v[100:103], v[180:183], v[204:207], v[100:103]
	v_mfma_f32_16x16x32_bf16 v[96:99], v[188:191], v[204:207], v[96:99]
	v_mfma_f32_16x16x32_bf16 v[84:87], v[180:183], v[212:215], v[84:87]
	v_mfma_f32_16x16x32_bf16 v[80:83], v[188:191], v[212:215], v[80:83]
	v_mfma_f32_16x16x32_bf16 v[68:71], v[180:183], v[220:223], v[68:71]
	v_mfma_f32_16x16x32_bf16 v[64:67], v[188:191], v[220:223], v[64:67]
	v_mfma_f32_16x16x32_bf16 v[124:127], v[224:227], v[192:195], v[124:127]
	v_mfma_f32_16x16x32_bf16 v[120:123], v[232:235], v[192:195], v[120:123]
	v_mfma_f32_16x16x32_bf16 v[108:111], v[224:227], v[200:203], v[108:111]
	v_mfma_f32_16x16x32_bf16 v[104:107], v[232:235], v[200:203], v[104:107]
	v_mfma_f32_16x16x32_bf16 v[92:95], v[224:227], v[208:211], v[92:95]
	v_mfma_f32_16x16x32_bf16 v[88:91], v[232:235], v[208:211], v[88:91]
	v_mfma_f32_16x16x32_bf16 v[76:79], v[224:227], v[216:219], v[76:79]
	v_mfma_f32_16x16x32_bf16 v[72:75], v[232:235], v[216:219], v[72:75]
	v_mfma_f32_16x16x32_bf16 v[124:127], v[228:231], v[196:199], v[124:127]
	v_mfma_f32_16x16x32_bf16 v[120:123], v[236:239], v[196:199], v[120:123]
	v_mfma_f32_16x16x32_bf16 v[108:111], v[228:231], v[204:207], v[108:111]
	v_mfma_f32_16x16x32_bf16 v[104:107], v[236:239], v[204:207], v[104:107]
	v_mfma_f32_16x16x32_bf16 v[92:95], v[228:231], v[212:215], v[92:95]
	v_mfma_f32_16x16x32_bf16 v[88:91], v[236:239], v[212:215], v[88:91]
	v_mfma_f32_16x16x32_bf16 v[76:79], v[228:231], v[220:223], v[76:79]
	v_mfma_f32_16x16x32_bf16 v[72:75], v[236:239], v[220:223], v[72:75]
	s_barrier
; #define PG8_STAGE(bufoff, gbase, voff) do { _Pragma("unroll") for (int _i = 0; _i < 2; ++_i) \
;         __builtin_amdgcn_global_load_lds((const unsigned*)((const char*)(gbase) + (voff)[_i]), (LAS unsigned*)(lds + (bufoff) + ldsw + _i * 8192), 16, 0, 0); } while (0)
; #define PG8_LDA(dst, b, h) do { _Pragma("unroll") for (int m = 0; m < 4; ++m) _Pragma("unroll") for (int k = 0; k < 2; ++k) dst[m][k] = *(const LAS bf16x8*)(lds + PG8_SA(b, h) + aoff + m * 2048 + k * 1024); } while (0)
; #define PG8_LDB(dst, b, h) do { _Pragma("unroll") for (int n = 0; n < 2; ++n) _Pragma("unroll") for (int k = 0; k < 2; ++k) dst[n][k] = *(const LAS bf16x8*)(lds + PG8_SB(b, h) + boff + n * 2048 + k * 1024); } while (0)
; #define PG8_MMA(ai, bj, At, Bt) do { __builtin_amdgcn_s_setprio(1); _Pragma("unroll") for (int m = 0; m < 4; ++m) _Pragma("unroll") for (int n = 0; n < 2; ++n) _Pragma("unroll") for (int k = 0; k < 2; ++k) \
;         acc[ai][bj][m][n] = __builtin_amdgcn_mfma_f32_16x16x32_bf16(Bt[n][k], At[m][k], acc[ai][bj][m][n], 0, 0, 0); __builtin_amdgcn_s_setprio(0); } while (0)
; #define PG8_WAIT_V(n) asm volatile("s_waitcnt vmcnt(" #n ")" ::: "memory")
; #define PG8_WAIT_L(n) asm volatile("s_waitcnt lgkmcnt(" #n ")" ::: "memory")
; #define PG8_BAR __builtin_amdgcn_s_barrier()
; #define PG8_SCHED __builtin_amdgcn_sched_barrier(0)
; template <class Epi>
; __device__ __forceinline__ void gemm_phase(LAS unsigned char* lds, const Gemm g, const StaticOrder& S, const Epi& E) {
;     ...
;             PG8_LDB(B0, 1, 0); PG8_SCHED; PG8_LDA(At, 1, 0); PG8_STAGE(PG8_SA(0, 1), a2 + hstep, voffA);
;             PG8_WAIT_L(8); PG8_BAR; PG8_WAIT_L(0); PG8_MMA(0, 0, At, B0); PG8_BAR; PG8_SCHED;
;             PG8_LDB(B1, 1, 1); PG8_STAGE(PG8_SB(1, 0), b3, voffB);
;             PG8_BAR; PG8_WAIT_L(0); PG8_MMA(0, 1, At, B1); PG8_BAR;
;             PG8_LDA(At, 1, 1); PG8_STAGE(PG8_SA(1, 0), a3, voffA);
;             PG8_BAR; PG8_WAIT_L(0); PG8_MMA(1, 0, At, B0); PG8_BAR; PG8_SCHED;
;             PG8_STAGE(PG8_SB(1, 1), b3 + hstep, voffB);
;             PG8_WAIT_V(6); PG8_BAR; PG8_MMA(1, 1, At, B1); PG8_BAR;
	s_setprio 0
	s_add_i32 s11, s42, s57
	v_lshl_add_u64 v[152:153], v[152:153], 0, s[24:25]
	s_mov_b32 m0, s11
	s_nop 0
	global_load_lds_dwordx4 v[152:153], off
	v_lshl_add_u64 v[152:153], v[176:177], 0, s[24:25]
	s_add_i32 m0, s11, 0x2000
	s_nop 0
	global_load_lds_dwordx4 v[152:153], off
	s_mov_b32 m0, s67
	v_lshl_add_u64 v[152:153], v[240:241], 0, s[24:25]
	ds_read_b128 v[192:195], v158 offset:49152
	ds_read_b128 v[196:199], v158 offset:50176
	ds_read_b128 v[200:203], v158 offset:51200
	ds_read_b128 v[204:207], v158 offset:52224
	ds_read_b128 v[208:211], v158 offset:53248
	ds_read_b128 v[212:215], v158 offset:54272
	ds_read_b128 v[216:219], v158 offset:55296
	ds_read_b128 v[220:223], v158 offset:56320
	global_load_lds_dwordx4 v[152:153], off
	v_lshl_add_u64 v[152:153], v[242:243], 0, s[24:25]
	s_mov_b32 m0, s68
	s_nop 0
	global_load_lds_dwordx4 v[152:153], off
	s_add_u32 s8, s8, 0x80080
	s_addc_u32 s9, s9, 0
	s_add_i32 s10, s10, s57
	v_lshl_add_u64 v[152:153], s[8:9], 0, v[130:131]
	s_mov_b32 m0, s10
	s_nop 0
	global_load_lds_dwordx4 v[152:153], off
	v_lshl_add_u64 v[152:153], s[8:9], 0, v[134:135]
	s_add_i32 m0, s10, 0x2000
	s_nop 0
	global_load_lds_dwordx4 v[152:153], off
	s_waitcnt lgkmcnt(0)
	s_waitcnt vmcnt(8)
	s_setprio 1
	s_barrier
	v_mfma_f32_16x16x32_bf16 v[52:55], v[172:175], v[192:195], v[52:55]
	v_mfma_f32_16x16x32_bf16 v[48:51], v[184:187], v[192:195], v[48:51]
	v_mfma_f32_16x16x32_bf16 v[36:39], v[172:175], v[200:203], v[36:39]
	v_mfma_f32_16x16x32_bf16 v[32:35], v[184:187], v[200:203], v[32:35]
	v_mfma_f32_16x16x32_bf16 v[20:23], v[172:175], v[208:211], v[20:23]
	v_mfma_f32_16x16x32_bf16 v[16:19], v[184:187], v[208:211], v[16:19]
	v_mfma_f32_16x16x32_bf16 v[4:7], v[172:175], v[216:219], v[4:7]
	v_mfma_f32_16x16x32_bf16 v[0:3], v[184:187], v[216:219], v[0:3]
	v_mfma_f32_16x16x32_bf16 v[52:55], v[180:183], v[196:199], v[52:55]
	v_mfma_f32_16x16x32_bf16 v[48:51], v[188:191], v[196:199], v[48:51]
	v_mfma_f32_16x16x32_bf16 v[36:39], v[180:183], v[204:207], v[36:39]
	v_mfma_f32_16x16x32_bf16 v[32:35], v[188:191], v[204:207], v[32:35]
	v_mfma_f32_16x16x32_bf16 v[20:23], v[180:183], v[212:215], v[20:23]
	v_mfma_f32_16x16x32_bf16 v[16:19], v[188:191], v[212:215], v[16:19]
	v_mfma_f32_16x16x32_bf16 v[4:7], v[180:183], v[220:223], v[4:7]
	v_mfma_f32_16x16x32_bf16 v[0:3], v[188:191], v[220:223], v[0:3]
	v_mfma_f32_16x16x32_bf16 v[60:63], v[224:227], v[192:195], v[60:63]
	v_mfma_f32_16x16x32_bf16 v[56:59], v[232:235], v[192:195], v[56:59]
	v_mfma_f32_16x16x32_bf16 v[44:47], v[224:227], v[200:203], v[44:47]
	v_mfma_f32_16x16x32_bf16 v[40:43], v[232:235], v[200:203], v[40:43]
	v_mfma_f32_16x16x32_bf16 v[28:31], v[224:227], v[208:211], v[28:31]
	v_mfma_f32_16x16x32_bf16 v[24:27], v[232:235], v[208:211], v[24:27]
	v_mfma_f32_16x16x32_bf16 v[12:15], v[224:227], v[216:219], v[12:15]
	v_mfma_f32_16x16x32_bf16 v[8:11], v[232:235], v[216:219], v[8:11]
	v_mfma_f32_16x16x32_bf16 v[60:63], v[228:231], v[196:199], v[60:63]
	v_mfma_f32_16x16x32_bf16 v[56:59], v[236:239], v[196:199], v[56:59]
	v_mfma_f32_16x16x32_bf16 v[44:47], v[228:231], v[204:207], v[44:47]
	v_mfma_f32_16x16x32_bf16 v[40:43], v[236:239], v[204:207], v[40:43]
	v_mfma_f32_16x16x32_bf16 v[28:31], v[228:231], v[212:215], v[28:31]
	v_mfma_f32_16x16x32_bf16 v[24:27], v[236:239], v[212:215], v[24:27]
	v_mfma_f32_16x16x32_bf16 v[12:15], v[228:231], v[220:223], v[12:15]
	v_mfma_f32_16x16x32_bf16 v[8:11], v[236:239], v[220:223], v[8:11]
	s_barrier
	s_setprio 0
	s_add_i32 s37, s37, 2
	s_add_u32 s6, s6, 0x100
	s_addc_u32 s7, s7, 0
	s_add_u32 s33, s33, 0x100
	s_addc_u32 s35, s35, 0
	s_cmp_gt_u32 s37, 29
	.p2align	6

; #define PG8_STAGE(bufoff, gbase, voff) do { _Pragma("unroll") for (int _i = 0; _i < 2; ++_i) \
;         __builtin_amdgcn_global_load_lds((const unsigned*)((const char*)(gbase) + (voff)[_i]), (LAS unsigned*)(lds + (bufoff) + ldsw + _i * 8192), 16, 0, 0); } while (0)
; #define PG8_LDA(dst, b, h) do { _Pragma("unroll") for (int m = 0; m < 4; ++m) _Pragma("unroll") for (int k = 0; k < 2; ++k) dst[m][k] = *(const LAS bf16x8*)(lds + PG8_SA(b, h) + aoff + m * 2048 + k * 1024); } while (0)
; #define PG8_LDB(dst, b, h) do { _Pragma("unroll") for (int n = 0; n < 2; ++n) _Pragma("unroll") for (int k = 0; k < 2; ++k) dst[n][k] = *(const LAS bf16x8*)(lds + PG8_SB(b, h) + boff + n * 2048 + k * 1024); } while (0)
; #define PG8_WAIT_V(n) asm volatile("s_waitcnt vmcnt(" #n ")" ::: "memory")
; #define PG8_WAIT_L(n) asm volatile("s_waitcnt lgkmcnt(" #n ")" ::: "memory")
; #define PG8_BAR __builtin_amdgcn_s_barrier()
; #define PG8_SCHED __builtin_amdgcn_sched_barrier(0)
; template <class Epi>
; __device__ __forceinline__ void gemm_phase(LAS unsigned char* lds, const Gemm g, const StaticOrder& S, const Epi& E) {
;     ...
;         const bool has_next = S.next(ui + 1, nxt);
;         const char* nA = has_next ? (const char*)g.A + (size_t)nxt.pm * tstep : cA; const char* nB = has_next ? (const char*)g.Bt + (size_t)nxt.pn * tstep : cB;
;         for (int t = 0; t < nt; t += 2) {
;             const bool last = (t == nt - 2);
;             const char* a1 = cA + (size_t)(t + 1) * kstep;
;             const char* a2 = last ? nA : cA + (size_t)(t + 2) * kstep; const char* b2 = last ? nB : cB + (size_t)(t + 2) * kstep;
;             const char* a3 = a2 + kstep; const char* b3 = b2 + kstep;
;             PG8_LDB(B0, 0, 0); PG8_SCHED; PG8_LDA(At, 0, 0); PG8_STAGE(PG8_SA(1, 1), a1 + hstep, voffA);
;             PG8_WAIT_L(8); PG8_BAR; PG8_WAIT_L(0); PG8_MMA(0, 0, At, B0); PG8_BAR; PG8_SCHED;
;             PG8_LDB(B1, 0, 1); PG8_STAGE(PG8_SB(0, 0), b2, voffB);
;             PG8_BAR; PG8_WAIT_L(0); PG8_MMA(0, 1, At, B1); PG8_BAR;
;             PG8_LDA(At, 0, 1); PG8_STAGE(PG8_SA(0, 0), a2, voffA);
;             PG8_BAR; PG8_WAIT_L(0); PG8_MMA(1, 0, At, B0); PG8_BAR; PG8_SCHED;
;             PG8_STAGE(PG8_SB(0, 1), b2 + hstep, voffB);
;             PG8_WAIT_V(6); PG8_BAR; PG8_MMA(1, 1, At, B1); PG8_BAR;
.LBB0_2459:
	s_ashr_i32 s13, s12, 31
	v_cmp_lt_i64_e32 vcc, s[14:15], v[148:149]
	s_lshl_b64 s[14:15], s[12:13], 20
	s_add_u32 s14, s36, s14
	s_addc_u32 s15, s37, s15
	s_and_b64 s[16:17], vcc, exec
	s_cselect_b32 s13, s15, s23
	s_cselect_b32 s19, s14, s22
	s_ashr_i32 s11, s10, 31
	s_lshl_b64 s[16:17], s[10:11], 20
	s_add_u32 s16, s34, s16
	s_addc_u32 s17, s35, s17
	s_and_b64 s[30:31], vcc, exec
	s_cselect_b32 s11, s17, s25
	s_cselect_b32 s58, s16, s24
	s_add_u32 s22, s22, 0x80080
	s_addc_u32 s23, s23, 0
	s_add_u32 s59, s24, 0x100
	s_addc_u32 s60, s25, 0
	s_mov_b32 s61, -2
	s_waitcnt lgkmcnt(0)
	ds_read_b128 v[128:131], v161
	ds_read_b128 v[132:135], v161 offset:1024
	ds_read_b128 v[152:155], v161 offset:2048
	ds_read_b128 v[166:169], v161 offset:3072
	s_add_u32 s24, s22, 0xfff80080
	s_addc_u32 s25, s23, -1
	s_cmp_eq_u32 s61, 28
	s_cselect_b32 s31, s13, s25
	s_cselect_b32 s30, s19, s24
	s_cselect_b32 s25, s11, s60
	s_cselect_b32 s24, s58, s59
	v_lshl_add_u64 v[156:157], s[22:23], 0, v[144:145]
	s_add_i32 m0, s21, 0xc000
	ds_read_b128 v[170:173], v162
	ds_read_b128 v[174:177], v162 offset:1024
	ds_read_b128 v[180:183], v162 offset:2048
	ds_read_b128 v[184:187], v162 offset:3072
	ds_read_b128 v[188:191], v162 offset:4096
	ds_read_b128 v[192:195], v162 offset:5120
	ds_read_b128 v[196:199], v162 offset:6144
	ds_read_b128 v[200:203], v162 offset:7168
	global_load_lds_dwordx4 v[156:157], off
	v_lshl_add_u64 v[156:157], s[22:23], 0, v[146:147]
	s_add_i32 m0, s21, 0xe000
	s_nop 0
	global_load_lds_dwordx4 v[156:157], off
	ds_read_b128 v[204:207], v163
	ds_read_b128 v[208:211], v163 offset:1024
	ds_read_b128 v[212:215], v163 offset:2048
	ds_read_b128 v[216:219], v163 offset:3072
	s_waitcnt lgkmcnt(0)
	s_waitcnt vmcnt(8)
	s_setprio 1
	s_barrier
	v_mfma_f32_16x16x32_bf16 v[124:127], v[128:131], v[170:173], 0
	v_mfma_f32_16x16x32_bf16 v[120:123], v[152:155], v[170:173], 0
	v_mfma_f32_16x16x32_bf16 v[108:111], v[128:131], v[180:183], 0
	v_mfma_f32_16x16x32_bf16 v[104:107], v[152:155], v[180:183], 0
	v_mfma_f32_16x16x32_bf16 v[92:95], v[128:131], v[188:191], 0
	v_mfma_f32_16x16x32_bf16 v[88:91], v[152:155], v[188:191], 0
	v_mfma_f32_16x16x32_bf16 v[76:79], v[128:131], v[196:199], 0
	v_mfma_f32_16x16x32_bf16 v[72:75], v[152:155], v[196:199], 0
	v_mfma_f32_16x16x32_bf16 v[124:127], v[132:135], v[174:177], v[124:127]
	v_mfma_f32_16x16x32_bf16 v[120:123], v[166:169], v[174:177], v[120:123]
	v_mfma_f32_16x16x32_bf16 v[108:111], v[132:135], v[184:187], v[108:111]
	v_mfma_f32_16x16x32_bf16 v[104:107], v[166:169], v[184:187], v[104:107]
	v_mfma_f32_16x16x32_bf16 v[92:95], v[132:135], v[192:195], v[92:95]
	v_mfma_f32_16x16x32_bf16 v[88:91], v[166:169], v[192:195], v[88:91]
	v_mfma_f32_16x16x32_bf16 v[76:79], v[132:135], v[200:203], v[76:79]
	v_mfma_f32_16x16x32_bf16 v[72:75], v[166:169], v[200:203], v[72:75]
	v_mfma_f32_16x16x32_bf16 v[116:119], v[204:207], v[170:173], 0
	v_mfma_f32_16x16x32_bf16 v[112:115], v[212:215], v[170:173], 0
	v_mfma_f32_16x16x32_bf16 v[100:103], v[204:207], v[180:183], 0
	v_mfma_f32_16x16x32_bf16 v[96:99], v[212:215], v[180:183], 0
	v_mfma_f32_16x16x32_bf16 v[84:87], v[204:207], v[188:191], 0
	v_mfma_f32_16x16x32_bf16 v[80:83], v[212:215], v[188:191], 0
	v_mfma_f32_16x16x32_bf16 v[68:71], v[204:207], v[196:199], 0
	v_mfma_f32_16x16x32_bf16 v[64:67], v[212:215], v[196:199], 0
	v_mfma_f32_16x16x32_bf16 v[116:119], v[208:211], v[174:177], v[116:119]
	v_mfma_f32_16x16x32_bf16 v[112:115], v[216:219], v[174:177], v[112:115]
	v_mfma_f32_16x16x32_bf16 v[100:103], v[208:211], v[184:187], v[100:103]
	v_mfma_f32_16x16x32_bf16 v[96:99], v[216:219], v[184:187], v[96:99]
	v_mfma_f32_16x16x32_bf16 v[84:87], v[208:211], v[192:195], v[84:87]
	v_mfma_f32_16x16x32_bf16 v[80:83], v[216:219], v[192:195], v[80:83]
	v_mfma_f32_16x16x32_bf16 v[68:71], v[208:211], v[200:203], v[68:71]
	v_mfma_f32_16x16x32_bf16 v[64:67], v[216:219], v[200:203], v[64:67]
	s_barrier
	s_setprio 0
	s_add_i32 s62, s56, s38
	v_lshl_add_u64 v[156:157], s[24:25], 0, v[138:139]
	s_mov_b32 m0, s62
	s_nop 0
	global_load_lds_dwordx4 v[156:157], off
	v_lshl_add_u64 v[220:221], s[24:25], 0, v[142:143]
	s_add_i32 m0, s62, 0x2000
	s_nop 0
	global_load_lds_dwordx4 v[220:221], off
	s_mov_b32 m0, s21
	v_lshl_add_u64 v[222:223], s[30:31], 0, v[136:137]
	ds_read_b128 v[170:173], v162 offset:16384
	ds_read_b128 v[174:177], v162 offset:17408
	ds_read_b128 v[180:183], v162 offset:18432
	ds_read_b128 v[184:187], v162 offset:19456
	ds_read_b128 v[188:191], v162 offset:20480
	ds_read_b128 v[192:195], v162 offset:21504
	ds_read_b128 v[196:199], v162 offset:22528
	ds_read_b128 v[200:203], v162 offset:23552
	global_load_lds_dwordx4 v[222:223], off
	v_lshl_add_u64 v[224:225], s[30:31], 0, v[140:141]
	s_mov_b32 m0, s39
	s_nop 0
	global_load_lds_dwordx4 v[224:225], off
	s_add_u32 s62, s24, 0x80000
	s_addc_u32 s63, s25, 0
	s_add_i32 s64, s57, s38
	v_lshl_add_u64 v[252:253], s[62:63], 0, v[138:139]
	s_mov_b32 m0, s64
	s_nop 0
	global_load_lds_dwordx4 v[252:253], off
	v_lshl_add_u64 v[252:253], s[62:63], 0, v[142:143]
	s_add_i32 m0, s64, 0x2000
	s_nop 0
	global_load_lds_dwordx4 v[252:253], off
	s_waitcnt lgkmcnt(0)
	s_waitcnt vmcnt(8)
	s_setprio 1
	s_barrier
; #define PG8_STAGE(bufoff, gbase, voff) do { _Pragma("unroll") for (int _i = 0; _i < 2; ++_i) \
;         __builtin_amdgcn_global_load_lds((const unsigned*)((const char*)(gbase) + (voff)[_i]), (LAS unsigned*)(lds + (bufoff) + ldsw + _i * 8192), 16, 0, 0); } while (0)
; #define PG8_LDA(dst, b, h) do { _Pragma("unroll") for (int m = 0; m < 4; ++m) _Pragma("unroll") for (int k = 0; k < 2; ++k) dst[m][k] = *(const LAS bf16x8*)(lds + PG8_SA(b, h) + aoff + m * 2048 + k * 1024); } while (0)
; #define PG8_LDB(dst, b, h) do { _Pragma("unroll") for (int n = 0; n < 2; ++n) _Pragma("unroll") for (int k = 0; k < 2; ++k) dst[n][k] = *(const LAS bf16x8*)(lds + PG8_SB(b, h) + boff + n * 2048 + k * 1024); } while (0)
; #define PG8_MMA(ai, bj, At, Bt) do { __builtin_amdgcn_s_setprio(1); _Pragma("unroll") for (int m = 0; m < 4; ++m) _Pragma("unroll") for (int n = 0; n < 2; ++n) _Pragma("unroll") for (int k = 0; k < 2; ++k) \
;         acc[ai][bj][m][n] = __builtin_amdgcn_mfma_f32_16x16x32_bf16(Bt[n][k], At[m][k], acc[ai][bj][m][n], 0, 0, 0); __builtin_amdgcn_s_setprio(0); } while (0)
; #define PG8_WAIT_V(n) asm volatile("s_waitcnt vmcnt(" #n ")" ::: "memory")
; #define PG8_WAIT_L(n) asm volatile("s_waitcnt lgkmcnt(" #n ")" ::: "memory")
; #define PG8_BAR __builtin_amdgcn_s_barrier()
; #define PG8_SCHED __builtin_amdgcn_sched_barrier(0)
; template <class Epi>
; __device__ __forceinline__ void gemm_phase(LAS unsigned char* lds, const Gemm g, const StaticOrder& S, const Epi& E) {
;     ...
;             PG8_LDA(At, 0, 1); PG8_STAGE(PG8_SA(0, 0), a2, voffA);
;             PG8_BAR; PG8_WAIT_L(0); PG8_MMA(1, 0, At, B0); PG8_BAR; PG8_SCHED;
;             PG8_STAGE(PG8_SB(0, 1), b2 + hstep, voffB);
;             PG8_WAIT_V(6); PG8_BAR; PG8_MMA(1, 1, At, B1); PG8_BAR;
;             PG8_LDB(B0, 1, 0); PG8_SCHED; PG8_LDA(At, 1, 0); PG8_STAGE(PG8_SA(0, 1), a2 + hstep, voffA);
;             PG8_WAIT_L(8); PG8_BAR; PG8_WAIT_L(0); PG8_MMA(0, 0, At, B0); PG8_BAR; PG8_SCHED;
;             PG8_LDB(B1, 1, 1); PG8_STAGE(PG8_SB(1, 0), b3, voffB);
;             PG8_BAR; PG8_WAIT_L(0); PG8_MMA(0, 1, At, B1); PG8_BAR;
;             PG8_LDA(At, 1, 1); PG8_STAGE(PG8_SA(1, 0), a3, voffA);
;             PG8_BAR; PG8_WAIT_L(0); PG8_MMA(1, 0, At, B0); PG8_BAR; PG8_SCHED;
	v_mfma_f32_16x16x32_bf16 v[60:63], v[128:131], v[170:173], 0
	v_mfma_f32_16x16x32_bf16 v[56:59], v[152:155], v[170:173], 0
	v_mfma_f32_16x16x32_bf16 v[44:47], v[128:131], v[180:183], 0
	v_mfma_f32_16x16x32_bf16 v[40:43], v[152:155], v[180:183], 0
	v_mfma_f32_16x16x32_bf16 v[28:31], v[128:131], v[188:191], 0
	v_mfma_f32_16x16x32_bf16 v[24:27], v[152:155], v[188:191], 0
	v_mfma_f32_16x16x32_bf16 v[12:15], v[128:131], v[196:199], 0
	v_mfma_f32_16x16x32_bf16 v[8:11], v[152:155], v[196:199], 0
	v_mfma_f32_16x16x32_bf16 v[60:63], v[132:135], v[174:177], v[60:63]
	v_mfma_f32_16x16x32_bf16 v[56:59], v[166:169], v[174:177], v[56:59]
	v_mfma_f32_16x16x32_bf16 v[44:47], v[132:135], v[184:187], v[44:47]
	v_mfma_f32_16x16x32_bf16 v[40:43], v[166:169], v[184:187], v[40:43]
	v_mfma_f32_16x16x32_bf16 v[28:31], v[132:135], v[192:195], v[28:31]
	v_mfma_f32_16x16x32_bf16 v[24:27], v[166:169], v[192:195], v[24:27]
	v_mfma_f32_16x16x32_bf16 v[12:15], v[132:135], v[200:203], v[12:15]
	v_mfma_f32_16x16x32_bf16 v[8:11], v[166:169], v[200:203], v[8:11]
	v_mfma_f32_16x16x32_bf16 v[52:55], v[204:207], v[170:173], 0
	v_mfma_f32_16x16x32_bf16 v[48:51], v[212:215], v[170:173], 0
	v_mfma_f32_16x16x32_bf16 v[36:39], v[204:207], v[180:183], 0
	v_mfma_f32_16x16x32_bf16 v[32:35], v[212:215], v[180:183], 0
	v_mfma_f32_16x16x32_bf16 v[20:23], v[204:207], v[188:191], 0
	v_mfma_f32_16x16x32_bf16 v[16:19], v[212:215], v[188:191], 0
	v_mfma_f32_16x16x32_bf16 v[4:7], v[204:207], v[196:199], 0
	v_mfma_f32_16x16x32_bf16 v[0:3], v[212:215], v[196:199], 0
	v_mfma_f32_16x16x32_bf16 v[52:55], v[208:211], v[174:177], v[52:55]
	v_mfma_f32_16x16x32_bf16 v[48:51], v[216:219], v[174:177], v[48:51]
	v_mfma_f32_16x16x32_bf16 v[36:39], v[208:211], v[184:187], v[36:39]
	v_mfma_f32_16x16x32_bf16 v[32:35], v[216:219], v[184:187], v[32:35]
	v_mfma_f32_16x16x32_bf16 v[20:23], v[208:211], v[192:195], v[20:23]
	v_mfma_f32_16x16x32_bf16 v[16:19], v[216:219], v[192:195], v[16:19]
	v_mfma_f32_16x16x32_bf16 v[4:7], v[208:211], v[200:203], v[4:7]
	v_mfma_f32_16x16x32_bf16 v[0:3], v[216:219], v[200:203], v[0:3]
	s_barrier
	s_setprio 0
	s_add_i32 s62, 0, 0x18000
	v_add_u32_e32 v165, s62, v158
	ds_read_b128 v[128:131], v165
	ds_read_b128 v[132:135], v165 offset:1024
	ds_read_b128 v[152:155], v165 offset:2048
	ds_read_b128 v[166:169], v165 offset:3072
	s_add_u32 s30, s30, 0x80000
	s_addc_u32 s31, s31, 0
	s_mov_b32 m0, s40
	v_lshl_add_u64 v[204:205], s[30:31], 0, v[136:137]
	ds_read_b128 v[170:173], v162 offset:32768
	ds_read_b128 v[174:177], v162 offset:33792
	ds_read_b128 v[180:183], v162 offset:34816
	ds_read_b128 v[184:187], v162 offset:35840
	ds_read_b128 v[188:191], v162 offset:36864
	ds_read_b128 v[192:195], v162 offset:37888
	ds_read_b128 v[196:199], v162 offset:38912
	ds_read_b128 v[200:203], v162 offset:39936
	global_load_lds_dwordx4 v[204:205], off
	v_lshl_add_u64 v[204:205], s[30:31], 0, v[140:141]
	s_mov_b32 m0, s41
	s_nop 0
	global_load_lds_dwordx4 v[204:205], off
	s_add_i32 s30, 0, 0x1c000
	v_add_u32_e32 v165, s30, v158
	ds_read_b128 v[204:207], v165
	ds_read_b128 v[208:211], v165 offset:1024
	ds_read_b128 v[212:215], v165 offset:2048
	ds_read_b128 v[216:219], v165 offset:3072
	s_waitcnt lgkmcnt(0)
	s_waitcnt vmcnt(8)
	s_setprio 1
	s_barrier
	v_mfma_f32_16x16x32_bf16 v[124:127], v[128:131], v[170:173], v[124:127]
	v_mfma_f32_16x16x32_bf16 v[120:123], v[152:155], v[170:173], v[120:123]
	v_mfma_f32_16x16x32_bf16 v[108:111], v[128:131], v[180:183], v[108:111]
	v_mfma_f32_16x16x32_bf16 v[104:107], v[152:155], v[180:183], v[104:107]
	v_mfma_f32_16x16x32_bf16 v[92:95], v[128:131], v[188:191], v[92:95]
	v_mfma_f32_16x16x32_bf16 v[88:91], v[152:155], v[188:191], v[88:91]
	v_mfma_f32_16x16x32_bf16 v[76:79], v[128:131], v[196:199], v[76:79]
	v_mfma_f32_16x16x32_bf16 v[72:75], v[152:155], v[196:199], v[72:75]
	v_mfma_f32_16x16x32_bf16 v[124:127], v[132:135], v[174:177], v[124:127]
	v_mfma_f32_16x16x32_bf16 v[120:123], v[166:169], v[174:177], v[120:123]
	v_mfma_f32_16x16x32_bf16 v[108:111], v[132:135], v[184:187], v[108:111]
	v_mfma_f32_16x16x32_bf16 v[104:107], v[166:169], v[184:187], v[104:107]
	v_mfma_f32_16x16x32_bf16 v[92:95], v[132:135], v[192:195], v[92:95]
	v_mfma_f32_16x16x32_bf16 v[88:91], v[166:169], v[192:195], v[88:91]
	v_mfma_f32_16x16x32_bf16 v[76:79], v[132:135], v[200:203], v[76:79]
	v_mfma_f32_16x16x32_bf16 v[72:75], v[166:169], v[200:203], v[72:75]
	v_mfma_f32_16x16x32_bf16 v[116:119], v[204:207], v[170:173], v[116:119]
	v_mfma_f32_16x16x32_bf16 v[112:115], v[212:215], v[170:173], v[112:115]
	v_mfma_f32_16x16x32_bf16 v[100:103], v[204:207], v[180:183], v[100:103]
	v_mfma_f32_16x16x32_bf16 v[96:99], v[212:215], v[180:183], v[96:99]
	v_mfma_f32_16x16x32_bf16 v[84:87], v[204:207], v[188:191], v[84:87]
	v_mfma_f32_16x16x32_bf16 v[80:83], v[212:215], v[188:191], v[80:83]
	v_mfma_f32_16x16x32_bf16 v[68:71], v[204:207], v[196:199], v[68:71]
	v_mfma_f32_16x16x32_bf16 v[64:67], v[212:215], v[196:199], v[64:67]
	v_mfma_f32_16x16x32_bf16 v[116:119], v[208:211], v[174:177], v[116:119]
	v_mfma_f32_16x16x32_bf16 v[112:115], v[216:219], v[174:177], v[112:115]
	v_mfma_f32_16x16x32_bf16 v[100:103], v[208:211], v[184:187], v[100:103]
	v_mfma_f32_16x16x32_bf16 v[96:99], v[216:219], v[184:187], v[96:99]
	v_mfma_f32_16x16x32_bf16 v[84:87], v[208:211], v[192:195], v[84:87]
	v_mfma_f32_16x16x32_bf16 v[80:83], v[216:219], v[192:195], v[80:83]
	v_mfma_f32_16x16x32_bf16 v[68:71], v[208:211], v[200:203], v[68:71]
	v_mfma_f32_16x16x32_bf16 v[64:67], v[216:219], v[200:203], v[64:67]
	s_barrier
; #define PG8_STAGE(bufoff, gbase, voff) do { _Pragma("unroll") for (int _i = 0; _i < 2; ++_i) \
;         __builtin_amdgcn_global_load_lds((const unsigned*)((const char*)(gbase) + (voff)[_i]), (LAS unsigned*)(lds + (bufoff) + ldsw + _i * 8192), 16, 0, 0); } while (0)
; #define PG8_LDA(dst, b, h) do { _Pragma("unroll") for (int m = 0; m < 4; ++m) _Pragma("unroll") for (int k = 0; k < 2; ++k) dst[m][k] = *(const LAS bf16x8*)(lds + PG8_SA(b, h) + aoff + m * 2048 + k * 1024); } while (0)
; #define PG8_MMA(ai, bj, At, Bt) do { __builtin_amdgcn_s_setprio(1); _Pragma("unroll") for (int m = 0; m < 4; ++m) _Pragma("unroll") for (int n = 0; n < 2; ++n) _Pragma("unroll") for (int k = 0; k < 2; ++k) \
;         acc[ai][bj][m][n] = __builtin_amdgcn_mfma_f32_16x16x32_bf16(Bt[n][k], At[m][k], acc[ai][bj][m][n], 0, 0, 0); __builtin_amdgcn_s_setprio(0); } while (0)
; #define PG8_WAIT_V(n) asm volatile("s_waitcnt vmcnt(" #n ")" ::: "memory")
; #define PG8_WAIT_L(n) asm volatile("s_waitcnt lgkmcnt(" #n ")" ::: "memory")
; #define PG8_BAR __builtin_amdgcn_s_barrier()
; #define PG8_SCHED __builtin_amdgcn_sched_barrier(0)
; template <class Epi>
; __device__ __forceinline__ void gemm_phase(LAS unsigned char* lds, const Gemm g, const StaticOrder& S, const Epi& E) {
;     ...
;             PG8_LDA(At, 1, 1); PG8_STAGE(PG8_SA(1, 0), a3, voffA);
;             PG8_BAR; PG8_WAIT_L(0); PG8_MMA(1, 0, At, B0); PG8_BAR; PG8_SCHED;
;             PG8_STAGE(PG8_SB(1, 1), b3 + hstep, voffB);
;             PG8_WAIT_V(6); PG8_BAR; PG8_MMA(1, 1, At, B1); PG8_BAR;
	s_setprio 0
	s_add_i32 s31, s62, s38
	v_lshl_add_u64 v[156:157], v[156:157], 0, s[8:9]
	s_mov_b32 m0, s31
	s_nop 0
	global_load_lds_dwordx4 v[156:157], off
	v_lshl_add_u64 v[156:157], v[220:221], 0, s[8:9]
	s_add_i32 m0, s31, 0x2000
	s_nop 0
	global_load_lds_dwordx4 v[156:157], off
	s_mov_b32 m0, s43
	v_lshl_add_u64 v[156:157], v[222:223], 0, s[8:9]
	ds_read_b128 v[170:173], v162 offset:49152
	ds_read_b128 v[174:177], v162 offset:50176
	ds_read_b128 v[180:183], v162 offset:51200
	ds_read_b128 v[184:187], v162 offset:52224
	ds_read_b128 v[188:191], v162 offset:53248
	ds_read_b128 v[192:195], v162 offset:54272
	ds_read_b128 v[196:199], v162 offset:55296
	ds_read_b128 v[200:203], v162 offset:56320
	global_load_lds_dwordx4 v[156:157], off
	v_lshl_add_u64 v[156:157], v[224:225], 0, s[8:9]
	s_mov_b32 m0, s44
	s_nop 0
	global_load_lds_dwordx4 v[156:157], off
	s_add_u32 s24, s24, 0x80080
	s_addc_u32 s25, s25, 0
	s_add_i32 s30, s30, s38
	v_lshl_add_u64 v[252:253], s[24:25], 0, v[138:139]
	s_mov_b32 m0, s30
	s_nop 0
	global_load_lds_dwordx4 v[252:253], off
	v_lshl_add_u64 v[252:253], s[24:25], 0, v[142:143]
	s_add_i32 m0, s30, 0x2000
	s_nop 0
	global_load_lds_dwordx4 v[252:253], off
	s_waitcnt lgkmcnt(0)
	s_waitcnt vmcnt(8)
	s_setprio 1
	s_barrier
	v_mfma_f32_16x16x32_bf16 v[60:63], v[128:131], v[170:173], v[60:63]
	v_mfma_f32_16x16x32_bf16 v[56:59], v[152:155], v[170:173], v[56:59]
	v_mfma_f32_16x16x32_bf16 v[44:47], v[128:131], v[180:183], v[44:47]
	v_mfma_f32_16x16x32_bf16 v[40:43], v[152:155], v[180:183], v[40:43]
	v_mfma_f32_16x16x32_bf16 v[28:31], v[128:131], v[188:191], v[28:31]
	v_mfma_f32_16x16x32_bf16 v[24:27], v[152:155], v[188:191], v[24:27]
	v_mfma_f32_16x16x32_bf16 v[12:15], v[128:131], v[196:199], v[12:15]
	v_mfma_f32_16x16x32_bf16 v[8:11], v[152:155], v[196:199], v[8:11]
	v_mfma_f32_16x16x32_bf16 v[60:63], v[132:135], v[174:177], v[60:63]
	v_mfma_f32_16x16x32_bf16 v[56:59], v[166:169], v[174:177], v[56:59]
	v_mfma_f32_16x16x32_bf16 v[44:47], v[132:135], v[184:187], v[44:47]
	v_mfma_f32_16x16x32_bf16 v[40:43], v[166:169], v[184:187], v[40:43]
	v_mfma_f32_16x16x32_bf16 v[28:31], v[132:135], v[192:195], v[28:31]
	v_mfma_f32_16x16x32_bf16 v[24:27], v[166:169], v[192:195], v[24:27]
	v_mfma_f32_16x16x32_bf16 v[12:15], v[132:135], v[200:203], v[12:15]
	v_mfma_f32_16x16x32_bf16 v[8:11], v[166:169], v[200:203], v[8:11]
	v_mfma_f32_16x16x32_bf16 v[52:55], v[204:207], v[170:173], v[52:55]
	v_mfma_f32_16x16x32_bf16 v[48:51], v[212:215], v[170:173], v[48:51]
	v_mfma_f32_16x16x32_bf16 v[36:39], v[204:207], v[180:183], v[36:39]
	v_mfma_f32_16x16x32_bf16 v[32:35], v[212:215], v[180:183], v[32:35]
	v_mfma_f32_16x16x32_bf16 v[20:23], v[204:207], v[188:191], v[20:23]
	v_mfma_f32_16x16x32_bf16 v[16:19], v[212:215], v[188:191], v[16:19]
	v_mfma_f32_16x16x32_bf16 v[4:7], v[204:207], v[196:199], v[4:7]
	v_mfma_f32_16x16x32_bf16 v[0:3], v[212:215], v[196:199], v[0:3]
	v_mfma_f32_16x16x32_bf16 v[52:55], v[208:211], v[174:177], v[52:55]
	v_mfma_f32_16x16x32_bf16 v[48:51], v[216:219], v[174:177], v[48:51]
	v_mfma_f32_16x16x32_bf16 v[36:39], v[208:211], v[184:187], v[36:39]
	v_mfma_f32_16x16x32_bf16 v[32:35], v[216:219], v[184:187], v[32:35]
	v_mfma_f32_16x16x32_bf16 v[20:23], v[208:211], v[192:195], v[20:23]
	v_mfma_f32_16x16x32_bf16 v[16:19], v[216:219], v[192:195], v[16:19]
	v_mfma_f32_16x16x32_bf16 v[4:7], v[208:211], v[200:203], v[4:7]
	v_mfma_f32_16x16x32_bf16 v[0:3], v[216:219], v[200:203], v[0:3]
	s_barrier
	s_setprio 0
	s_add_i32 s61, s61, 2
	s_add_u32 s22, s22, 0x100
	s_addc_u32 s23, s23, 0
	s_add_u32 s59, s59, 0x100
	s_addc_u32 s60, s60, 0
	s_cmp_gt_u32 s61, 29
	.p2align	6

; #define PG8_STAGE(bufoff, gbase, voff) do { _Pragma("unroll") for (int _i = 0; _i < 2; ++_i) \
;         __builtin_amdgcn_global_load_lds((const unsigned*)((const char*)(gbase) + (voff)[_i]), (LAS unsigned*)(lds + (bufoff) + ldsw + _i * 8192), 16, 0, 0); } while (0)
; #define PG8_LDA(dst, b, h) do { _Pragma("unroll") for (int m = 0; m < 4; ++m) _Pragma("unroll") for (int k = 0; k < 2; ++k) dst[m][k] = *(const LAS bf16x8*)(lds + PG8_SA(b, h) + aoff + m * 2048 + k * 1024); } while (0)
; #define PG8_LDB(dst, b, h) do { _Pragma("unroll") for (int n = 0; n < 2; ++n) _Pragma("unroll") for (int k = 0; k < 2; ++k) dst[n][k] = *(const LAS bf16x8*)(lds + PG8_SB(b, h) + boff + n * 2048 + k * 1024); } while (0)
; #define PG8_WAIT_V(n) asm volatile("s_waitcnt vmcnt(" #n ")" ::: "memory")
; #define PG8_WAIT_L(n) asm volatile("s_waitcnt lgkmcnt(" #n ")" ::: "memory")
; #define PG8_BAR __builtin_amdgcn_s_barrier()
; #define PG8_SCHED __builtin_amdgcn_sched_barrier(0)
; template <class Epi>
; __device__ __forceinline__ void gemm_phase(LAS unsigned char* lds, const Gemm g, const StaticOrder& S, const Epi& E) {
;     ...
;         const bool has_next = S.next(ui + 1, nxt);
;         const char* nA = has_next ? (const char*)g.A + (size_t)nxt.pm * tstep : cA; const char* nB = has_next ? (const char*)g.Bt + (size_t)nxt.pn * tstep : cB;
;         for (int t = 0; t < nt; t += 2) {
;             const bool last = (t == nt - 2);
;             const char* a1 = cA + (size_t)(t + 1) * kstep;
;             const char* a2 = last ? nA : cA + (size_t)(t + 2) * kstep; const char* b2 = last ? nB : cB + (size_t)(t + 2) * kstep;
;             const char* a3 = a2 + kstep; const char* b3 = b2 + kstep;
;             PG8_LDB(B0, 0, 0); PG8_SCHED; PG8_LDA(At, 0, 0); PG8_STAGE(PG8_SA(1, 1), a1 + hstep, voffA);
;             PG8_WAIT_L(8); PG8_BAR; PG8_WAIT_L(0); PG8_MMA(0, 0, At, B0); PG8_BAR; PG8_SCHED;
;             PG8_LDB(B1, 0, 1); PG8_STAGE(PG8_SB(0, 0), b2, voffB);
;             PG8_BAR; PG8_WAIT_L(0); PG8_MMA(0, 1, At, B1); PG8_BAR;
;             PG8_LDA(At, 0, 1); PG8_STAGE(PG8_SA(0, 0), a2, voffA);
;             PG8_BAR; PG8_WAIT_L(0); PG8_MMA(1, 0, At, B0); PG8_BAR; PG8_SCHED;
;             PG8_STAGE(PG8_SB(0, 1), b2 + hstep, voffB);
;             PG8_WAIT_V(6); PG8_BAR; PG8_MMA(1, 1, At, B1); PG8_BAR;
.LBB0_2545:
	s_ashr_i32 s9, s8, 31
	v_cmp_lt_i64_e32 vcc, s[10:11], v[140:141]
	s_lshl_b64 s[10:11], s[8:9], 20
	s_add_u32 s10, s23, s10
	s_addc_u32 s11, s24, s11
	s_and_b64 s[12:13], vcc, exec
	s_cselect_b32 s9, s11, s17
	s_cselect_b32 s47, s10, s16
	s_ashr_i32 s7, s6, 31
	s_lshl_b64 s[12:13], s[6:7], 20
	s_add_u32 s12, s25, s12
	s_addc_u32 s13, s30, s13
	s_and_b64 s[20:21], vcc, exec
	s_cselect_b32 s7, s13, s19
	s_cselect_b32 s56, s12, s18
	s_add_u32 s16, s16, 0x80080
	s_addc_u32 s17, s17, 0
	s_add_u32 s57, s18, 0x100
	s_addc_u32 s58, s19, 0
	s_mov_b32 s59, -2
	ds_read_b128 v[160:163], v148
	ds_read_b128 v[164:167], v148 offset:1024
	ds_read_b128 v[168:171], v148 offset:2048
	ds_read_b128 v[172:175], v148 offset:3072
	s_add_u32 s18, s16, 0xfff80080
	s_addc_u32 s19, s17, -1
	s_cmp_eq_u32 s59, 28
	s_cselect_b32 s21, s9, s19
	s_cselect_b32 s20, s47, s18
	s_cselect_b32 s19, s7, s58
	s_cselect_b32 s18, s56, s57
	v_lshl_add_u64 v[176:177], s[16:17], 0, v[136:137]
	s_add_i32 m0, s35, 0xc000
	ds_read_b128 v[180:183], v149
	ds_read_b128 v[184:187], v149 offset:1024
	ds_read_b128 v[188:191], v149 offset:2048
	ds_read_b128 v[192:195], v149 offset:3072
	ds_read_b128 v[196:199], v149 offset:4096
	ds_read_b128 v[200:203], v149 offset:5120
	ds_read_b128 v[204:207], v149 offset:6144
	ds_read_b128 v[208:211], v149 offset:7168
	global_load_lds_dwordx4 v[176:177], off
	v_lshl_add_u64 v[176:177], s[16:17], 0, v[138:139]
	s_add_i32 m0, s35, 0xe000
	s_nop 0
	global_load_lds_dwordx4 v[176:177], off
	ds_read_b128 v[212:215], v150
	ds_read_b128 v[216:219], v150 offset:1024
	ds_read_b128 v[220:223], v150 offset:2048
	ds_read_b128 v[224:227], v150 offset:3072
	s_waitcnt lgkmcnt(0)
	s_waitcnt vmcnt(8)
	s_setprio 1
	s_barrier
	v_mfma_f32_16x16x32_bf16 v[124:127], v[160:163], v[180:183], 0
	v_mfma_f32_16x16x32_bf16 v[116:119], v[168:171], v[180:183], 0
	v_mfma_f32_16x16x32_bf16 v[108:111], v[160:163], v[188:191], 0
	v_mfma_f32_16x16x32_bf16 v[100:103], v[168:171], v[188:191], 0
	v_mfma_f32_16x16x32_bf16 v[92:95], v[160:163], v[196:199], 0
	v_mfma_f32_16x16x32_bf16 v[84:87], v[168:171], v[196:199], 0
	v_mfma_f32_16x16x32_bf16 v[76:79], v[160:163], v[204:207], 0
	v_mfma_f32_16x16x32_bf16 v[68:71], v[168:171], v[204:207], 0
	v_mfma_f32_16x16x32_bf16 v[124:127], v[164:167], v[184:187], v[124:127]
	v_mfma_f32_16x16x32_bf16 v[116:119], v[172:175], v[184:187], v[116:119]
	v_mfma_f32_16x16x32_bf16 v[108:111], v[164:167], v[192:195], v[108:111]
	v_mfma_f32_16x16x32_bf16 v[100:103], v[172:175], v[192:195], v[100:103]
	v_mfma_f32_16x16x32_bf16 v[92:95], v[164:167], v[200:203], v[92:95]
	v_mfma_f32_16x16x32_bf16 v[84:87], v[172:175], v[200:203], v[84:87]
	v_mfma_f32_16x16x32_bf16 v[76:79], v[164:167], v[208:211], v[76:79]
	v_mfma_f32_16x16x32_bf16 v[68:71], v[172:175], v[208:211], v[68:71]
	v_mfma_f32_16x16x32_bf16 v[120:123], v[212:215], v[180:183], 0
	v_mfma_f32_16x16x32_bf16 v[112:115], v[220:223], v[180:183], 0
	v_mfma_f32_16x16x32_bf16 v[104:107], v[212:215], v[188:191], 0
	v_mfma_f32_16x16x32_bf16 v[96:99], v[220:223], v[188:191], 0
	v_mfma_f32_16x16x32_bf16 v[88:91], v[212:215], v[196:199], 0
	v_mfma_f32_16x16x32_bf16 v[80:83], v[220:223], v[196:199], 0
	v_mfma_f32_16x16x32_bf16 v[72:75], v[212:215], v[204:207], 0
	v_mfma_f32_16x16x32_bf16 v[64:67], v[220:223], v[204:207], 0
	v_mfma_f32_16x16x32_bf16 v[120:123], v[216:219], v[184:187], v[120:123]
	v_mfma_f32_16x16x32_bf16 v[112:115], v[224:227], v[184:187], v[112:115]
	v_mfma_f32_16x16x32_bf16 v[104:107], v[216:219], v[192:195], v[104:107]
	v_mfma_f32_16x16x32_bf16 v[96:99], v[224:227], v[192:195], v[96:99]
	v_mfma_f32_16x16x32_bf16 v[88:91], v[216:219], v[200:203], v[88:91]
	v_mfma_f32_16x16x32_bf16 v[80:83], v[224:227], v[200:203], v[80:83]
	v_mfma_f32_16x16x32_bf16 v[72:75], v[216:219], v[208:211], v[72:75]
	v_mfma_f32_16x16x32_bf16 v[64:67], v[224:227], v[208:211], v[64:67]
	s_barrier
	s_setprio 0
	s_add_i32 s60, s44, s31
	v_lshl_add_u64 v[176:177], s[18:19], 0, v[132:133]
	s_mov_b32 m0, s60
	s_nop 0
	global_load_lds_dwordx4 v[176:177], off
	v_lshl_add_u64 v[228:229], s[18:19], 0, v[128:129]
	s_add_i32 m0, s60, 0x2000
	s_nop 0
	global_load_lds_dwordx4 v[228:229], off
	s_mov_b32 m0, s35
	v_lshl_add_u64 v[230:231], s[20:21], 0, v[134:135]
	ds_read_b128 v[180:183], v149 offset:16384
	ds_read_b128 v[184:187], v149 offset:17408
	ds_read_b128 v[188:191], v149 offset:18432
	ds_read_b128 v[192:195], v149 offset:19456
	ds_read_b128 v[196:199], v149 offset:20480
	ds_read_b128 v[200:203], v149 offset:21504
	ds_read_b128 v[204:207], v149 offset:22528
	ds_read_b128 v[208:211], v149 offset:23552
	global_load_lds_dwordx4 v[230:231], off
	v_lshl_add_u64 v[232:233], s[20:21], 0, v[130:131]
	s_mov_b32 m0, s36
	s_nop 0
	global_load_lds_dwordx4 v[232:233], off
	s_add_u32 s60, s18, 0x80000
	s_addc_u32 s61, s19, 0
	s_add_i32 s62, s45, s31
	v_lshl_add_u64 v[252:253], s[60:61], 0, v[132:133]
	s_mov_b32 m0, s62
	s_nop 0
	global_load_lds_dwordx4 v[252:253], off
	v_lshl_add_u64 v[252:253], s[60:61], 0, v[128:129]
	s_add_i32 m0, s62, 0x2000
	s_nop 0
	global_load_lds_dwordx4 v[252:253], off
	s_waitcnt lgkmcnt(0)
	s_waitcnt vmcnt(8)
	s_setprio 1
	s_barrier
; #define PG8_STAGE(bufoff, gbase, voff) do { _Pragma("unroll") for (int _i = 0; _i < 2; ++_i) \
;         __builtin_amdgcn_global_load_lds((const unsigned*)((const char*)(gbase) + (voff)[_i]), (LAS unsigned*)(lds + (bufoff) + ldsw + _i * 8192), 16, 0, 0); } while (0)
; #define PG8_LDA(dst, b, h) do { _Pragma("unroll") for (int m = 0; m < 4; ++m) _Pragma("unroll") for (int k = 0; k < 2; ++k) dst[m][k] = *(const LAS bf16x8*)(lds + PG8_SA(b, h) + aoff + m * 2048 + k * 1024); } while (0)
; #define PG8_LDB(dst, b, h) do { _Pragma("unroll") for (int n = 0; n < 2; ++n) _Pragma("unroll") for (int k = 0; k < 2; ++k) dst[n][k] = *(const LAS bf16x8*)(lds + PG8_SB(b, h) + boff + n * 2048 + k * 1024); } while (0)
; #define PG8_MMA(ai, bj, At, Bt) do { __builtin_amdgcn_s_setprio(1); _Pragma("unroll") for (int m = 0; m < 4; ++m) _Pragma("unroll") for (int n = 0; n < 2; ++n) _Pragma("unroll") for (int k = 0; k < 2; ++k) \
;         acc[ai][bj][m][n] = __builtin_amdgcn_mfma_f32_16x16x32_bf16(Bt[n][k], At[m][k], acc[ai][bj][m][n], 0, 0, 0); __builtin_amdgcn_s_setprio(0); } while (0)
; #define PG8_WAIT_V(n) asm volatile("s_waitcnt vmcnt(" #n ")" ::: "memory")
; #define PG8_WAIT_L(n) asm volatile("s_waitcnt lgkmcnt(" #n ")" ::: "memory")
; #define PG8_BAR __builtin_amdgcn_s_barrier()
; #define PG8_SCHED __builtin_amdgcn_sched_barrier(0)
; template <class Epi>
; __device__ __forceinline__ void gemm_phase(LAS unsigned char* lds, const Gemm g, const StaticOrder& S, const Epi& E) {
;     ...
;             PG8_LDA(At, 0, 1); PG8_STAGE(PG8_SA(0, 0), a2, voffA);
;             PG8_BAR; PG8_WAIT_L(0); PG8_MMA(1, 0, At, B0); PG8_BAR; PG8_SCHED;
;             PG8_STAGE(PG8_SB(0, 1), b2 + hstep, voffB);
;             PG8_WAIT_V(6); PG8_BAR; PG8_MMA(1, 1, At, B1); PG8_BAR;
;             PG8_LDB(B0, 1, 0); PG8_SCHED; PG8_LDA(At, 1, 0); PG8_STAGE(PG8_SA(0, 1), a2 + hstep, voffA);
;             PG8_WAIT_L(8); PG8_BAR; PG8_WAIT_L(0); PG8_MMA(0, 0, At, B0); PG8_BAR; PG8_SCHED;
;             PG8_LDB(B1, 1, 1); PG8_STAGE(PG8_SB(1, 0), b3, voffB);
;             PG8_BAR; PG8_WAIT_L(0); PG8_MMA(0, 1, At, B1); PG8_BAR;
;             PG8_LDA(At, 1, 1); PG8_STAGE(PG8_SA(1, 0), a3, voffA);
;             PG8_BAR; PG8_WAIT_L(0); PG8_MMA(1, 0, At, B0); PG8_BAR; PG8_SCHED;
	v_mfma_f32_16x16x32_bf16 v[60:63], v[160:163], v[180:183], 0
	v_mfma_f32_16x16x32_bf16 v[52:55], v[168:171], v[180:183], 0
	v_mfma_f32_16x16x32_bf16 v[44:47], v[160:163], v[188:191], 0
	v_mfma_f32_16x16x32_bf16 v[36:39], v[168:171], v[188:191], 0
	v_mfma_f32_16x16x32_bf16 v[28:31], v[160:163], v[196:199], 0
	v_mfma_f32_16x16x32_bf16 v[20:23], v[168:171], v[196:199], 0
	v_mfma_f32_16x16x32_bf16 v[12:15], v[160:163], v[204:207], 0
	v_mfma_f32_16x16x32_bf16 v[4:7], v[168:171], v[204:207], 0
	v_mfma_f32_16x16x32_bf16 v[60:63], v[164:167], v[184:187], v[60:63]
	v_mfma_f32_16x16x32_bf16 v[52:55], v[172:175], v[184:187], v[52:55]
	v_mfma_f32_16x16x32_bf16 v[44:47], v[164:167], v[192:195], v[44:47]
	v_mfma_f32_16x16x32_bf16 v[36:39], v[172:175], v[192:195], v[36:39]
	v_mfma_f32_16x16x32_bf16 v[28:31], v[164:167], v[200:203], v[28:31]
	v_mfma_f32_16x16x32_bf16 v[20:23], v[172:175], v[200:203], v[20:23]
	v_mfma_f32_16x16x32_bf16 v[12:15], v[164:167], v[208:211], v[12:15]
	v_mfma_f32_16x16x32_bf16 v[4:7], v[172:175], v[208:211], v[4:7]
	v_mfma_f32_16x16x32_bf16 v[56:59], v[212:215], v[180:183], 0
	v_mfma_f32_16x16x32_bf16 v[48:51], v[220:223], v[180:183], 0
	v_mfma_f32_16x16x32_bf16 v[40:43], v[212:215], v[188:191], 0
	v_mfma_f32_16x16x32_bf16 v[32:35], v[220:223], v[188:191], 0
	v_mfma_f32_16x16x32_bf16 v[24:27], v[212:215], v[196:199], 0
	v_mfma_f32_16x16x32_bf16 v[16:19], v[220:223], v[196:199], 0
	v_mfma_f32_16x16x32_bf16 v[8:11], v[212:215], v[204:207], 0
	v_mfma_f32_16x16x32_bf16 v[0:3], v[220:223], v[204:207], 0
	v_mfma_f32_16x16x32_bf16 v[56:59], v[216:219], v[184:187], v[56:59]
	v_mfma_f32_16x16x32_bf16 v[48:51], v[224:227], v[184:187], v[48:51]
	v_mfma_f32_16x16x32_bf16 v[40:43], v[216:219], v[192:195], v[40:43]
	v_mfma_f32_16x16x32_bf16 v[32:35], v[224:227], v[192:195], v[32:35]
	v_mfma_f32_16x16x32_bf16 v[24:27], v[216:219], v[200:203], v[24:27]
	v_mfma_f32_16x16x32_bf16 v[16:19], v[224:227], v[200:203], v[16:19]
	v_mfma_f32_16x16x32_bf16 v[8:11], v[216:219], v[208:211], v[8:11]
	v_mfma_f32_16x16x32_bf16 v[0:3], v[224:227], v[208:211], v[0:3]
	s_barrier
	s_setprio 0
	s_add_i32 s60, 0, 0x18000
	v_add_u32_e32 v159, s60, v145
	ds_read_b128 v[160:163], v159
	ds_read_b128 v[164:167], v159 offset:1024
	ds_read_b128 v[168:171], v159 offset:2048
	ds_read_b128 v[172:175], v159 offset:3072
	s_add_u32 s20, s20, 0x80000
	s_addc_u32 s21, s21, 0
	s_mov_b32 m0, s37
	v_lshl_add_u64 v[212:213], s[20:21], 0, v[134:135]
	ds_read_b128 v[180:183], v149 offset:32768
	ds_read_b128 v[184:187], v149 offset:33792
	ds_read_b128 v[188:191], v149 offset:34816
	ds_read_b128 v[192:195], v149 offset:35840
	ds_read_b128 v[196:199], v149 offset:36864
	ds_read_b128 v[200:203], v149 offset:37888
	ds_read_b128 v[204:207], v149 offset:38912
	ds_read_b128 v[208:211], v149 offset:39936
	global_load_lds_dwordx4 v[212:213], off
	v_lshl_add_u64 v[212:213], s[20:21], 0, v[130:131]
	s_mov_b32 m0, s38
	s_nop 0
	global_load_lds_dwordx4 v[212:213], off
	s_add_i32 s20, 0, 0x1c000
	v_add_u32_e32 v159, s20, v145
	ds_read_b128 v[212:215], v159
	ds_read_b128 v[216:219], v159 offset:1024
	ds_read_b128 v[220:223], v159 offset:2048
	ds_read_b128 v[224:227], v159 offset:3072
	s_waitcnt lgkmcnt(0)
	s_waitcnt vmcnt(8)
	s_setprio 1
	s_barrier
	v_mfma_f32_16x16x32_bf16 v[124:127], v[160:163], v[180:183], v[124:127]
	v_mfma_f32_16x16x32_bf16 v[116:119], v[168:171], v[180:183], v[116:119]
	v_mfma_f32_16x16x32_bf16 v[108:111], v[160:163], v[188:191], v[108:111]
	v_mfma_f32_16x16x32_bf16 v[100:103], v[168:171], v[188:191], v[100:103]
	v_mfma_f32_16x16x32_bf16 v[92:95], v[160:163], v[196:199], v[92:95]
	v_mfma_f32_16x16x32_bf16 v[84:87], v[168:171], v[196:199], v[84:87]
	v_mfma_f32_16x16x32_bf16 v[76:79], v[160:163], v[204:207], v[76:79]
	v_mfma_f32_16x16x32_bf16 v[68:71], v[168:171], v[204:207], v[68:71]
	v_mfma_f32_16x16x32_bf16 v[124:127], v[164:167], v[184:187], v[124:127]
	v_mfma_f32_16x16x32_bf16 v[116:119], v[172:175], v[184:187], v[116:119]
	v_mfma_f32_16x16x32_bf16 v[108:111], v[164:167], v[192:195], v[108:111]
	v_mfma_f32_16x16x32_bf16 v[100:103], v[172:175], v[192:195], v[100:103]
	v_mfma_f32_16x16x32_bf16 v[92:95], v[164:167], v[200:203], v[92:95]
	v_mfma_f32_16x16x32_bf16 v[84:87], v[172:175], v[200:203], v[84:87]
	v_mfma_f32_16x16x32_bf16 v[76:79], v[164:167], v[208:211], v[76:79]
	v_mfma_f32_16x16x32_bf16 v[68:71], v[172:175], v[208:211], v[68:71]
	v_mfma_f32_16x16x32_bf16 v[120:123], v[212:215], v[180:183], v[120:123]
	v_mfma_f32_16x16x32_bf16 v[112:115], v[220:223], v[180:183], v[112:115]
	v_mfma_f32_16x16x32_bf16 v[104:107], v[212:215], v[188:191], v[104:107]
	v_mfma_f32_16x16x32_bf16 v[96:99], v[220:223], v[188:191], v[96:99]
	v_mfma_f32_16x16x32_bf16 v[88:91], v[212:215], v[196:199], v[88:91]
	v_mfma_f32_16x16x32_bf16 v[80:83], v[220:223], v[196:199], v[80:83]
	v_mfma_f32_16x16x32_bf16 v[72:75], v[212:215], v[204:207], v[72:75]
	v_mfma_f32_16x16x32_bf16 v[64:67], v[220:223], v[204:207], v[64:67]
	v_mfma_f32_16x16x32_bf16 v[120:123], v[216:219], v[184:187], v[120:123]
	v_mfma_f32_16x16x32_bf16 v[112:115], v[224:227], v[184:187], v[112:115]
	v_mfma_f32_16x16x32_bf16 v[104:107], v[216:219], v[192:195], v[104:107]
	v_mfma_f32_16x16x32_bf16 v[96:99], v[224:227], v[192:195], v[96:99]
	v_mfma_f32_16x16x32_bf16 v[88:91], v[216:219], v[200:203], v[88:91]
	v_mfma_f32_16x16x32_bf16 v[80:83], v[224:227], v[200:203], v[80:83]
	v_mfma_f32_16x16x32_bf16 v[72:75], v[216:219], v[208:211], v[72:75]
	v_mfma_f32_16x16x32_bf16 v[64:67], v[224:227], v[208:211], v[64:67]
	s_barrier
; #define PG8_STAGE(bufoff, gbase, voff) do { _Pragma("unroll") for (int _i = 0; _i < 2; ++_i) \
;         __builtin_amdgcn_global_load_lds((const unsigned*)((const char*)(gbase) + (voff)[_i]), (LAS unsigned*)(lds + (bufoff) + ldsw + _i * 8192), 16, 0, 0); } while (0)
; #define PG8_LDA(dst, b, h) do { _Pragma("unroll") for (int m = 0; m < 4; ++m) _Pragma("unroll") for (int k = 0; k < 2; ++k) dst[m][k] = *(const LAS bf16x8*)(lds + PG8_SA(b, h) + aoff + m * 2048 + k * 1024); } while (0)
; #define PG8_MMA(ai, bj, At, Bt) do { __builtin_amdgcn_s_setprio(1); _Pragma("unroll") for (int m = 0; m < 4; ++m) _Pragma("unroll") for (int n = 0; n < 2; ++n) _Pragma("unroll") for (int k = 0; k < 2; ++k) \
;         acc[ai][bj][m][n] = __builtin_amdgcn_mfma_f32_16x16x32_bf16(Bt[n][k], At[m][k], acc[ai][bj][m][n], 0, 0, 0); __builtin_amdgcn_s_setprio(0); } while (0)
; #define PG8_WAIT_V(n) asm volatile("s_waitcnt vmcnt(" #n ")" ::: "memory")
; #define PG8_WAIT_L(n) asm volatile("s_waitcnt lgkmcnt(" #n ")" ::: "memory")
; #define PG8_BAR __builtin_amdgcn_s_barrier()
; #define PG8_SCHED __builtin_amdgcn_sched_barrier(0)
; template <class Epi>
; __device__ __forceinline__ void gemm_phase(LAS unsigned char* lds, const Gemm g, const StaticOrder& S, const Epi& E) {
;     ...
;             PG8_LDA(At, 1, 1); PG8_STAGE(PG8_SA(1, 0), a3, voffA);
;             PG8_BAR; PG8_WAIT_L(0); PG8_MMA(1, 0, At, B0); PG8_BAR; PG8_SCHED;
;             PG8_STAGE(PG8_SB(1, 1), b3 + hstep, voffB);
;             PG8_WAIT_V(6); PG8_BAR; PG8_MMA(1, 1, At, B1); PG8_BAR;
	s_setprio 0
	s_add_i32 s21, s60, s31
	v_lshl_add_u64 v[176:177], v[176:177], 0, s[4:5]
	s_mov_b32 m0, s21
	s_nop 0
	global_load_lds_dwordx4 v[176:177], off
	v_lshl_add_u64 v[176:177], v[228:229], 0, s[4:5]
	s_add_i32 m0, s21, 0x2000
	s_nop 0
	global_load_lds_dwordx4 v[176:177], off
	s_mov_b32 m0, s40
	v_lshl_add_u64 v[176:177], v[230:231], 0, s[4:5]
	ds_read_b128 v[180:183], v149 offset:49152
	ds_read_b128 v[184:187], v149 offset:50176
	ds_read_b128 v[188:191], v149 offset:51200
	ds_read_b128 v[192:195], v149 offset:52224
	ds_read_b128 v[196:199], v149 offset:53248
	ds_read_b128 v[200:203], v149 offset:54272
	ds_read_b128 v[204:207], v149 offset:55296
	ds_read_b128 v[208:211], v149 offset:56320
	global_load_lds_dwordx4 v[176:177], off
	v_lshl_add_u64 v[176:177], v[232:233], 0, s[4:5]
	s_mov_b32 m0, s41
	s_nop 0
	global_load_lds_dwordx4 v[176:177], off
	s_add_u32 s18, s18, 0x80080
	s_addc_u32 s19, s19, 0
	s_add_i32 s20, s20, s31
	v_lshl_add_u64 v[252:253], s[18:19], 0, v[132:133]
	s_mov_b32 m0, s20
	s_nop 0
	global_load_lds_dwordx4 v[252:253], off
	v_lshl_add_u64 v[252:253], s[18:19], 0, v[128:129]
	s_add_i32 m0, s20, 0x2000
	s_nop 0
	global_load_lds_dwordx4 v[252:253], off
	s_waitcnt lgkmcnt(0)
	s_waitcnt vmcnt(8)
	s_setprio 1
	s_barrier
	v_mfma_f32_16x16x32_bf16 v[60:63], v[160:163], v[180:183], v[60:63]
	v_mfma_f32_16x16x32_bf16 v[52:55], v[168:171], v[180:183], v[52:55]
	v_mfma_f32_16x16x32_bf16 v[44:47], v[160:163], v[188:191], v[44:47]
	v_mfma_f32_16x16x32_bf16 v[36:39], v[168:171], v[188:191], v[36:39]
	v_mfma_f32_16x16x32_bf16 v[28:31], v[160:163], v[196:199], v[28:31]
	v_mfma_f32_16x16x32_bf16 v[20:23], v[168:171], v[196:199], v[20:23]
	v_mfma_f32_16x16x32_bf16 v[12:15], v[160:163], v[204:207], v[12:15]
	v_mfma_f32_16x16x32_bf16 v[4:7], v[168:171], v[204:207], v[4:7]
	v_mfma_f32_16x16x32_bf16 v[60:63], v[164:167], v[184:187], v[60:63]
	v_mfma_f32_16x16x32_bf16 v[52:55], v[172:175], v[184:187], v[52:55]
	v_mfma_f32_16x16x32_bf16 v[44:47], v[164:167], v[192:195], v[44:47]
	v_mfma_f32_16x16x32_bf16 v[36:39], v[172:175], v[192:195], v[36:39]
	v_mfma_f32_16x16x32_bf16 v[28:31], v[164:167], v[200:203], v[28:31]
	v_mfma_f32_16x16x32_bf16 v[20:23], v[172:175], v[200:203], v[20:23]
	v_mfma_f32_16x16x32_bf16 v[12:15], v[164:167], v[208:211], v[12:15]
	v_mfma_f32_16x16x32_bf16 v[4:7], v[172:175], v[208:211], v[4:7]
	v_mfma_f32_16x16x32_bf16 v[56:59], v[212:215], v[180:183], v[56:59]
	v_mfma_f32_16x16x32_bf16 v[48:51], v[220:223], v[180:183], v[48:51]
	v_mfma_f32_16x16x32_bf16 v[40:43], v[212:215], v[188:191], v[40:43]
	v_mfma_f32_16x16x32_bf16 v[32:35], v[220:223], v[188:191], v[32:35]
	v_mfma_f32_16x16x32_bf16 v[24:27], v[212:215], v[196:199], v[24:27]
	v_mfma_f32_16x16x32_bf16 v[16:19], v[220:223], v[196:199], v[16:19]
	v_mfma_f32_16x16x32_bf16 v[8:11], v[212:215], v[204:207], v[8:11]
	v_mfma_f32_16x16x32_bf16 v[0:3], v[220:223], v[204:207], v[0:3]
	v_mfma_f32_16x16x32_bf16 v[56:59], v[216:219], v[184:187], v[56:59]
	v_mfma_f32_16x16x32_bf16 v[48:51], v[224:227], v[184:187], v[48:51]
	v_mfma_f32_16x16x32_bf16 v[40:43], v[216:219], v[192:195], v[40:43]
	v_mfma_f32_16x16x32_bf16 v[32:35], v[224:227], v[192:195], v[32:35]
	v_mfma_f32_16x16x32_bf16 v[24:27], v[216:219], v[200:203], v[24:27]
	v_mfma_f32_16x16x32_bf16 v[16:19], v[224:227], v[200:203], v[16:19]
	v_mfma_f32_16x16x32_bf16 v[8:11], v[216:219], v[208:211], v[8:11]
	v_mfma_f32_16x16x32_bf16 v[0:3], v[224:227], v[208:211], v[0:3]
	s_barrier
	s_setprio 0
	s_add_i32 s59, s59, 2
	s_add_u32 s16, s16, 0x100
	s_addc_u32 s17, s17, 0
	s_add_u32 s57, s57, 0x100
	s_addc_u32 s58, s58, 0
	s_cmp_gt_u32 s59, 29
	.p2align	6

; #define PG8_STAGE(bufoff, gbase, voff) do { _Pragma("unroll") for (int _i = 0; _i < 2; ++_i) \
;         __builtin_amdgcn_global_load_lds((const unsigned*)((const char*)(gbase) + (voff)[_i]), (LAS unsigned*)(lds + (bufoff) + ldsw + _i * 8192), 16, 0, 0); } while (0)
; #define PG8_LDA(dst, b, h) do { _Pragma("unroll") for (int m = 0; m < 4; ++m) _Pragma("unroll") for (int k = 0; k < 2; ++k) dst[m][k] = *(const LAS bf16x8*)(lds + PG8_SA(b, h) + aoff + m * 2048 + k * 1024); } while (0)
; #define PG8_LDB(dst, b, h) do { _Pragma("unroll") for (int n = 0; n < 2; ++n) _Pragma("unroll") for (int k = 0; k < 2; ++k) dst[n][k] = *(const LAS bf16x8*)(lds + PG8_SB(b, h) + boff + n * 2048 + k * 1024); } while (0)
; #define PG8_WAIT_V(n) asm volatile("s_waitcnt vmcnt(" #n ")" ::: "memory")
; #define PG8_WAIT_L(n) asm volatile("s_waitcnt lgkmcnt(" #n ")" ::: "memory")
; #define PG8_BAR __builtin_amdgcn_s_barrier()
; #define PG8_SCHED __builtin_amdgcn_sched_barrier(0)
; template <class Epi>
; __device__ __forceinline__ void gemm_phase(LAS unsigned char* lds, const Gemm g, const StaticOrder& S, const Epi& E) {
;     ...
;         const bool has_next = S.next(ui + 1, nxt);
;         const char* nA = has_next ? (const char*)g.A + (size_t)nxt.pm * tstep : cA; const char* nB = has_next ? (const char*)g.Bt + (size_t)nxt.pn * tstep : cB;
;         for (int t = 0; t < nt; t += 2) {
;             const bool last = (t == nt - 2);
;             const char* a1 = cA + (size_t)(t + 1) * kstep;
;             const char* a2 = last ? nA : cA + (size_t)(t + 2) * kstep; const char* b2 = last ? nB : cB + (size_t)(t + 2) * kstep;
;             const char* a3 = a2 + kstep; const char* b3 = b2 + kstep;
;             PG8_LDB(B0, 0, 0); PG8_SCHED; PG8_LDA(At, 0, 0); PG8_STAGE(PG8_SA(1, 1), a1 + hstep, voffA);
;             PG8_WAIT_L(8); PG8_BAR; PG8_WAIT_L(0); PG8_MMA(0, 0, At, B0); PG8_BAR; PG8_SCHED;
;             PG8_LDB(B1, 0, 1); PG8_STAGE(PG8_SB(0, 0), b2, voffB);
;             PG8_BAR; PG8_WAIT_L(0); PG8_MMA(0, 1, At, B1); PG8_BAR;
;             PG8_LDA(At, 0, 1); PG8_STAGE(PG8_SA(0, 0), a2, voffA);
;             PG8_BAR; PG8_WAIT_L(0); PG8_MMA(1, 0, At, B0); PG8_BAR; PG8_SCHED;
;             PG8_STAGE(PG8_SB(0, 1), b2 + hstep, voffB);
;             PG8_WAIT_V(6); PG8_BAR; PG8_MMA(1, 1, At, B1); PG8_BAR;
.LBB0_2625:
	s_add_u32 s18, s18, 0x158080
	s_addc_u32 s19, s19, 0
	s_add_u32 s62, s20, 0x100
	s_addc_u32 s63, s21, 0
	s_mov_b32 s64, -2
	ds_read_b128 v[144:147], v153
	ds_read_b128 v[156:159], v153 offset:1024
	ds_read_b128 v[160:163], v153 offset:2048
	ds_read_b128 v[164:167], v153 offset:3072
	s_add_u32 s20, s18, 0xffea8080
	s_addc_u32 s21, s19, -1
	s_cmpk_eq_i32 s64, 0x52
	s_cselect_b32 s23, s1, s21
	s_cselect_b32 s22, s0, s20
	s_cselect_b32 s21, s5, s63
	s_cselect_b32 s20, s4, s62
	v_lshl_add_u64 v[148:149], s[18:19], 0, v[136:137]
	s_add_i32 m0, s36, 0xc000
	ds_read_b128 v[168:171], v154
	ds_read_b128 v[172:175], v154 offset:1024
	ds_read_b128 v[176:179], v154 offset:2048
	ds_read_b128 v[180:183], v154 offset:3072
	ds_read_b128 v[184:187], v154 offset:4096
	ds_read_b128 v[188:191], v154 offset:5120
	ds_read_b128 v[192:195], v154 offset:6144
	ds_read_b128 v[196:199], v154 offset:7168
	global_load_lds_dwordx4 v[148:149], off
	v_lshl_add_u64 v[148:149], s[18:19], 0, v[138:139]
	s_add_i32 m0, s36, 0xe000
	s_nop 0
	global_load_lds_dwordx4 v[148:149], off
	ds_read_b128 v[200:203], v155
	ds_read_b128 v[204:207], v155 offset:1024
	ds_read_b128 v[208:211], v155 offset:2048
	ds_read_b128 v[212:215], v155 offset:3072
	s_waitcnt lgkmcnt(0)
	s_waitcnt vmcnt(8)
	s_setprio 1
	s_barrier
	v_mfma_f32_16x16x32_bf16 v[124:127], v[144:147], v[168:171], 0
	v_mfma_f32_16x16x32_bf16 v[120:123], v[160:163], v[168:171], 0
	v_mfma_f32_16x16x32_bf16 v[112:115], v[144:147], v[176:179], 0
	v_mfma_f32_16x16x32_bf16 v[104:107], v[160:163], v[176:179], 0
	v_mfma_f32_16x16x32_bf16 v[92:95], v[144:147], v[184:187], 0
	v_mfma_f32_16x16x32_bf16 v[88:91], v[160:163], v[184:187], 0
	v_mfma_f32_16x16x32_bf16 v[80:83], v[144:147], v[192:195], 0
	v_mfma_f32_16x16x32_bf16 v[72:75], v[160:163], v[192:195], 0
	v_mfma_f32_16x16x32_bf16 v[124:127], v[156:159], v[172:175], v[124:127]
	v_mfma_f32_16x16x32_bf16 v[120:123], v[164:167], v[172:175], v[120:123]
	v_mfma_f32_16x16x32_bf16 v[112:115], v[156:159], v[180:183], v[112:115]
	v_mfma_f32_16x16x32_bf16 v[104:107], v[164:167], v[180:183], v[104:107]
	v_mfma_f32_16x16x32_bf16 v[92:95], v[156:159], v[188:191], v[92:95]
	v_mfma_f32_16x16x32_bf16 v[88:91], v[164:167], v[188:191], v[88:91]
	v_mfma_f32_16x16x32_bf16 v[80:83], v[156:159], v[196:199], v[80:83]
	v_mfma_f32_16x16x32_bf16 v[72:75], v[164:167], v[196:199], v[72:75]
	v_mfma_f32_16x16x32_bf16 v[116:119], v[200:203], v[168:171], 0
	v_mfma_f32_16x16x32_bf16 v[108:111], v[208:211], v[168:171], 0
	v_mfma_f32_16x16x32_bf16 v[100:103], v[200:203], v[176:179], 0
	v_mfma_f32_16x16x32_bf16 v[96:99], v[208:211], v[176:179], 0
	v_mfma_f32_16x16x32_bf16 v[84:87], v[200:203], v[184:187], 0
	v_mfma_f32_16x16x32_bf16 v[76:79], v[208:211], v[184:187], 0
	v_mfma_f32_16x16x32_bf16 v[68:71], v[200:203], v[192:195], 0
	v_mfma_f32_16x16x32_bf16 v[64:67], v[208:211], v[192:195], 0
	v_mfma_f32_16x16x32_bf16 v[116:119], v[204:207], v[172:175], v[116:119]
	v_mfma_f32_16x16x32_bf16 v[108:111], v[212:215], v[172:175], v[108:111]
	v_mfma_f32_16x16x32_bf16 v[100:103], v[204:207], v[180:183], v[100:103]
	v_mfma_f32_16x16x32_bf16 v[96:99], v[212:215], v[180:183], v[96:99]
	v_mfma_f32_16x16x32_bf16 v[84:87], v[204:207], v[188:191], v[84:87]
	v_mfma_f32_16x16x32_bf16 v[76:79], v[212:215], v[188:191], v[76:79]
	v_mfma_f32_16x16x32_bf16 v[68:71], v[204:207], v[196:199], v[68:71]
	v_mfma_f32_16x16x32_bf16 v[64:67], v[212:215], v[196:199], v[64:67]
	s_barrier
	s_setprio 0
	s_add_i32 s65, s45, s35
	v_lshl_add_u64 v[148:149], s[20:21], 0, v[130:131]
	s_mov_b32 m0, s65
	s_nop 0
	global_load_lds_dwordx4 v[148:149], off
	v_lshl_add_u64 v[216:217], s[20:21], 0, v[134:135]
	s_add_i32 m0, s65, 0x2000
	s_nop 0
	global_load_lds_dwordx4 v[216:217], off
	s_mov_b32 m0, s36
	v_lshl_add_u64 v[218:219], s[22:23], 0, v[128:129]
	ds_read_b128 v[168:171], v154 offset:16384
	ds_read_b128 v[172:175], v154 offset:17408
	ds_read_b128 v[176:179], v154 offset:18432
	ds_read_b128 v[180:183], v154 offset:19456
	ds_read_b128 v[184:187], v154 offset:20480
	ds_read_b128 v[188:191], v154 offset:21504
	ds_read_b128 v[192:195], v154 offset:22528
	ds_read_b128 v[196:199], v154 offset:23552
	global_load_lds_dwordx4 v[218:219], off
	v_lshl_add_u64 v[220:221], s[22:23], 0, v[132:133]
	s_mov_b32 m0, s37
	s_nop 0
	global_load_lds_dwordx4 v[220:221], off
	s_add_u32 s66, s20, 0x158000
	s_addc_u32 s67, s21, 0
	s_add_i32 s65, s46, s35
	v_lshl_add_u64 v[252:253], s[66:67], 0, v[130:131]
	s_mov_b32 m0, s65
	s_nop 0
	global_load_lds_dwordx4 v[252:253], off
	v_lshl_add_u64 v[252:253], s[66:67], 0, v[134:135]
	s_add_i32 m0, s65, 0x2000
	s_nop 0
	global_load_lds_dwordx4 v[252:253], off
	s_waitcnt lgkmcnt(0)
	s_waitcnt vmcnt(8)
	s_setprio 1
	s_barrier
; #define PG8_STAGE(bufoff, gbase, voff) do { _Pragma("unroll") for (int _i = 0; _i < 2; ++_i) \
;         __builtin_amdgcn_global_load_lds((const unsigned*)((const char*)(gbase) + (voff)[_i]), (LAS unsigned*)(lds + (bufoff) + ldsw + _i * 8192), 16, 0, 0); } while (0)
; #define PG8_LDA(dst, b, h) do { _Pragma("unroll") for (int m = 0; m < 4; ++m) _Pragma("unroll") for (int k = 0; k < 2; ++k) dst[m][k] = *(const LAS bf16x8*)(lds + PG8_SA(b, h) + aoff + m * 2048 + k * 1024); } while (0)
; #define PG8_LDB(dst, b, h) do { _Pragma("unroll") for (int n = 0; n < 2; ++n) _Pragma("unroll") for (int k = 0; k < 2; ++k) dst[n][k] = *(const LAS bf16x8*)(lds + PG8_SB(b, h) + boff + n * 2048 + k * 1024); } while (0)
; #define PG8_MMA(ai, bj, At, Bt) do { __builtin_amdgcn_s_setprio(1); _Pragma("unroll") for (int m = 0; m < 4; ++m) _Pragma("unroll") for (int n = 0; n < 2; ++n) _Pragma("unroll") for (int k = 0; k < 2; ++k) \
;         acc[ai][bj][m][n] = __builtin_amdgcn_mfma_f32_16x16x32_bf16(Bt[n][k], At[m][k], acc[ai][bj][m][n], 0, 0, 0); __builtin_amdgcn_s_setprio(0); } while (0)
; #define PG8_WAIT_V(n) asm volatile("s_waitcnt vmcnt(" #n ")" ::: "memory")
; #define PG8_WAIT_L(n) asm volatile("s_waitcnt lgkmcnt(" #n ")" ::: "memory")
; #define PG8_BAR __builtin_amdgcn_s_barrier()
; #define PG8_SCHED __builtin_amdgcn_sched_barrier(0)
; template <class Epi>
; __device__ __forceinline__ void gemm_phase(LAS unsigned char* lds, const Gemm g, const StaticOrder& S, const Epi& E) {
;     ...
;             PG8_LDA(At, 0, 1); PG8_STAGE(PG8_SA(0, 0), a2, voffA);
;             PG8_BAR; PG8_WAIT_L(0); PG8_MMA(1, 0, At, B0); PG8_BAR; PG8_SCHED;
;             PG8_STAGE(PG8_SB(0, 1), b2 + hstep, voffB);
;             PG8_WAIT_V(6); PG8_BAR; PG8_MMA(1, 1, At, B1); PG8_BAR;
;             PG8_LDB(B0, 1, 0); PG8_SCHED; PG8_LDA(At, 1, 0); PG8_STAGE(PG8_SA(0, 1), a2 + hstep, voffA);
;             PG8_WAIT_L(8); PG8_BAR; PG8_WAIT_L(0); PG8_MMA(0, 0, At, B0); PG8_BAR; PG8_SCHED;
;             PG8_LDB(B1, 1, 1); PG8_STAGE(PG8_SB(1, 0), b3, voffB);
;             PG8_BAR; PG8_WAIT_L(0); PG8_MMA(0, 1, At, B1); PG8_BAR;
;             PG8_LDA(At, 1, 1); PG8_STAGE(PG8_SA(1, 0), a3, voffA);
;             PG8_BAR; PG8_WAIT_L(0); PG8_MMA(1, 0, At, B0); PG8_BAR; PG8_SCHED;
	v_mfma_f32_16x16x32_bf16 v[60:63], v[144:147], v[168:171], 0
	v_mfma_f32_16x16x32_bf16 v[56:59], v[160:163], v[168:171], 0
	v_mfma_f32_16x16x32_bf16 v[48:51], v[144:147], v[176:179], 0
	v_mfma_f32_16x16x32_bf16 v[40:43], v[160:163], v[176:179], 0
	v_mfma_f32_16x16x32_bf16 v[28:31], v[144:147], v[184:187], 0
	v_mfma_f32_16x16x32_bf16 v[24:27], v[160:163], v[184:187], 0
	v_mfma_f32_16x16x32_bf16 v[20:23], v[144:147], v[192:195], 0
	v_mfma_f32_16x16x32_bf16 v[12:15], v[160:163], v[192:195], 0
	v_mfma_f32_16x16x32_bf16 v[60:63], v[156:159], v[172:175], v[60:63]
	v_mfma_f32_16x16x32_bf16 v[56:59], v[164:167], v[172:175], v[56:59]
	v_mfma_f32_16x16x32_bf16 v[48:51], v[156:159], v[180:183], v[48:51]
	v_mfma_f32_16x16x32_bf16 v[40:43], v[164:167], v[180:183], v[40:43]
	v_mfma_f32_16x16x32_bf16 v[28:31], v[156:159], v[188:191], v[28:31]
	v_mfma_f32_16x16x32_bf16 v[24:27], v[164:167], v[188:191], v[24:27]
	v_mfma_f32_16x16x32_bf16 v[20:23], v[156:159], v[196:199], v[20:23]
	v_mfma_f32_16x16x32_bf16 v[12:15], v[164:167], v[196:199], v[12:15]
	v_mfma_f32_16x16x32_bf16 v[52:55], v[200:203], v[168:171], 0
	v_mfma_f32_16x16x32_bf16 v[44:47], v[208:211], v[168:171], 0
	v_mfma_f32_16x16x32_bf16 v[36:39], v[200:203], v[176:179], 0
	v_mfma_f32_16x16x32_bf16 v[32:35], v[208:211], v[176:179], 0
	v_mfma_f32_16x16x32_bf16 v[16:19], v[200:203], v[184:187], 0
	v_mfma_f32_16x16x32_bf16 v[8:11], v[208:211], v[184:187], 0
	v_mfma_f32_16x16x32_bf16 v[4:7], v[200:203], v[192:195], 0
	v_mfma_f32_16x16x32_bf16 v[0:3], v[208:211], v[192:195], 0
	v_mfma_f32_16x16x32_bf16 v[52:55], v[204:207], v[172:175], v[52:55]
	v_mfma_f32_16x16x32_bf16 v[44:47], v[212:215], v[172:175], v[44:47]
	v_mfma_f32_16x16x32_bf16 v[36:39], v[204:207], v[180:183], v[36:39]
	v_mfma_f32_16x16x32_bf16 v[32:35], v[212:215], v[180:183], v[32:35]
	v_mfma_f32_16x16x32_bf16 v[16:19], v[204:207], v[188:191], v[16:19]
	v_mfma_f32_16x16x32_bf16 v[8:11], v[212:215], v[188:191], v[8:11]
	v_mfma_f32_16x16x32_bf16 v[4:7], v[204:207], v[196:199], v[4:7]
	v_mfma_f32_16x16x32_bf16 v[0:3], v[212:215], v[196:199], v[0:3]
	s_barrier
	s_setprio 0
	s_add_i32 s65, 0, 0x18000
	v_add_u32_e32 v164, s65, v150
	ds_read_b128 v[144:147], v164
	ds_read_b128 v[156:159], v164 offset:1024
	ds_read_b128 v[160:163], v164 offset:2048
	ds_read_b128 v[164:167], v164 offset:3072
	s_add_u32 s22, s22, 0x158000
	s_addc_u32 s23, s23, 0
	s_mov_b32 m0, s38
	v_lshl_add_u64 v[200:201], s[22:23], 0, v[128:129]
	ds_read_b128 v[168:171], v154 offset:32768
	ds_read_b128 v[172:175], v154 offset:33792
	ds_read_b128 v[176:179], v154 offset:34816
	ds_read_b128 v[180:183], v154 offset:35840
	ds_read_b128 v[184:187], v154 offset:36864
	ds_read_b128 v[188:191], v154 offset:37888
	ds_read_b128 v[192:195], v154 offset:38912
	ds_read_b128 v[196:199], v154 offset:39936
	global_load_lds_dwordx4 v[200:201], off
	v_lshl_add_u64 v[200:201], s[22:23], 0, v[132:133]
	s_mov_b32 m0, s39
	s_nop 0
	global_load_lds_dwordx4 v[200:201], off
	s_add_i32 s22, 0, 0x1c000
	v_add_u32_e32 v212, s22, v150
	ds_read_b128 v[200:203], v212
	ds_read_b128 v[204:207], v212 offset:1024
	ds_read_b128 v[208:211], v212 offset:2048
	ds_read_b128 v[212:215], v212 offset:3072
	s_waitcnt lgkmcnt(0)
	s_waitcnt vmcnt(8)
	s_setprio 1
	s_barrier
	v_mfma_f32_16x16x32_bf16 v[124:127], v[144:147], v[168:171], v[124:127]
	v_mfma_f32_16x16x32_bf16 v[120:123], v[160:163], v[168:171], v[120:123]
	v_mfma_f32_16x16x32_bf16 v[112:115], v[144:147], v[176:179], v[112:115]
	v_mfma_f32_16x16x32_bf16 v[104:107], v[160:163], v[176:179], v[104:107]
	v_mfma_f32_16x16x32_bf16 v[92:95], v[144:147], v[184:187], v[92:95]
	v_mfma_f32_16x16x32_bf16 v[88:91], v[160:163], v[184:187], v[88:91]
	v_mfma_f32_16x16x32_bf16 v[80:83], v[144:147], v[192:195], v[80:83]
	v_mfma_f32_16x16x32_bf16 v[72:75], v[160:163], v[192:195], v[72:75]
	v_mfma_f32_16x16x32_bf16 v[124:127], v[156:159], v[172:175], v[124:127]
	v_mfma_f32_16x16x32_bf16 v[120:123], v[164:167], v[172:175], v[120:123]
	v_mfma_f32_16x16x32_bf16 v[112:115], v[156:159], v[180:183], v[112:115]
	v_mfma_f32_16x16x32_bf16 v[104:107], v[164:167], v[180:183], v[104:107]
	v_mfma_f32_16x16x32_bf16 v[92:95], v[156:159], v[188:191], v[92:95]
	v_mfma_f32_16x16x32_bf16 v[88:91], v[164:167], v[188:191], v[88:91]
	v_mfma_f32_16x16x32_bf16 v[80:83], v[156:159], v[196:199], v[80:83]
	v_mfma_f32_16x16x32_bf16 v[72:75], v[164:167], v[196:199], v[72:75]
	v_mfma_f32_16x16x32_bf16 v[116:119], v[200:203], v[168:171], v[116:119]
	v_mfma_f32_16x16x32_bf16 v[108:111], v[208:211], v[168:171], v[108:111]
	v_mfma_f32_16x16x32_bf16 v[100:103], v[200:203], v[176:179], v[100:103]
	v_mfma_f32_16x16x32_bf16 v[96:99], v[208:211], v[176:179], v[96:99]
	v_mfma_f32_16x16x32_bf16 v[84:87], v[200:203], v[184:187], v[84:87]
	v_mfma_f32_16x16x32_bf16 v[76:79], v[208:211], v[184:187], v[76:79]
	v_mfma_f32_16x16x32_bf16 v[68:71], v[200:203], v[192:195], v[68:71]
	v_mfma_f32_16x16x32_bf16 v[64:67], v[208:211], v[192:195], v[64:67]
	v_mfma_f32_16x16x32_bf16 v[116:119], v[204:207], v[172:175], v[116:119]
	v_mfma_f32_16x16x32_bf16 v[108:111], v[212:215], v[172:175], v[108:111]
	v_mfma_f32_16x16x32_bf16 v[100:103], v[204:207], v[180:183], v[100:103]
	v_mfma_f32_16x16x32_bf16 v[96:99], v[212:215], v[180:183], v[96:99]
	v_mfma_f32_16x16x32_bf16 v[84:87], v[204:207], v[188:191], v[84:87]
	v_mfma_f32_16x16x32_bf16 v[76:79], v[212:215], v[188:191], v[76:79]
	v_mfma_f32_16x16x32_bf16 v[68:71], v[204:207], v[196:199], v[68:71]
	v_mfma_f32_16x16x32_bf16 v[64:67], v[212:215], v[196:199], v[64:67]
	s_barrier
; #define PG8_STAGE(bufoff, gbase, voff) do { _Pragma("unroll") for (int _i = 0; _i < 2; ++_i) \
;         __builtin_amdgcn_global_load_lds((const unsigned*)((const char*)(gbase) + (voff)[_i]), (LAS unsigned*)(lds + (bufoff) + ldsw + _i * 8192), 16, 0, 0); } while (0)
; #define PG8_LDA(dst, b, h) do { _Pragma("unroll") for (int m = 0; m < 4; ++m) _Pragma("unroll") for (int k = 0; k < 2; ++k) dst[m][k] = *(const LAS bf16x8*)(lds + PG8_SA(b, h) + aoff + m * 2048 + k * 1024); } while (0)
; #define PG8_MMA(ai, bj, At, Bt) do { __builtin_amdgcn_s_setprio(1); _Pragma("unroll") for (int m = 0; m < 4; ++m) _Pragma("unroll") for (int n = 0; n < 2; ++n) _Pragma("unroll") for (int k = 0; k < 2; ++k) \
;         acc[ai][bj][m][n] = __builtin_amdgcn_mfma_f32_16x16x32_bf16(Bt[n][k], At[m][k], acc[ai][bj][m][n], 0, 0, 0); __builtin_amdgcn_s_setprio(0); } while (0)
; #define PG8_WAIT_V(n) asm volatile("s_waitcnt vmcnt(" #n ")" ::: "memory")
; #define PG8_WAIT_L(n) asm volatile("s_waitcnt lgkmcnt(" #n ")" ::: "memory")
; #define PG8_BAR __builtin_amdgcn_s_barrier()
; #define PG8_SCHED __builtin_amdgcn_sched_barrier(0)
; template <class Epi>
; __device__ __forceinline__ void gemm_phase(LAS unsigned char* lds, const Gemm g, const StaticOrder& S, const Epi& E) {
;     ...
;             PG8_LDA(At, 1, 1); PG8_STAGE(PG8_SA(1, 0), a3, voffA);
;             PG8_BAR; PG8_WAIT_L(0); PG8_MMA(1, 0, At, B0); PG8_BAR; PG8_SCHED;
;             PG8_STAGE(PG8_SB(1, 1), b3 + hstep, voffB);
;             PG8_WAIT_V(6); PG8_BAR; PG8_MMA(1, 1, At, B1); PG8_BAR;
	s_setprio 0
	s_add_i32 s23, s65, s35
	v_lshl_add_u64 v[148:149], v[148:149], 0, s[8:9]
	s_mov_b32 m0, s23
	s_nop 0
	global_load_lds_dwordx4 v[148:149], off
	v_lshl_add_u64 v[148:149], v[216:217], 0, s[8:9]
	s_add_i32 m0, s23, 0x2000
	s_nop 0
	global_load_lds_dwordx4 v[148:149], off
	s_mov_b32 m0, s41
	v_lshl_add_u64 v[148:149], v[218:219], 0, s[8:9]
	ds_read_b128 v[168:171], v154 offset:49152
	ds_read_b128 v[172:175], v154 offset:50176
	ds_read_b128 v[176:179], v154 offset:51200
	ds_read_b128 v[180:183], v154 offset:52224
	ds_read_b128 v[184:187], v154 offset:53248
	ds_read_b128 v[188:191], v154 offset:54272
	ds_read_b128 v[192:195], v154 offset:55296
	ds_read_b128 v[196:199], v154 offset:56320
	global_load_lds_dwordx4 v[148:149], off
	v_lshl_add_u64 v[148:149], v[220:221], 0, s[8:9]
	s_mov_b32 m0, s42
	s_nop 0
	global_load_lds_dwordx4 v[148:149], off
	s_add_u32 s20, s20, 0x158080
	s_addc_u32 s21, s21, 0
	s_add_i32 s22, s22, s35
	v_lshl_add_u64 v[252:253], s[20:21], 0, v[130:131]
	s_mov_b32 m0, s22
	s_nop 0
	global_load_lds_dwordx4 v[252:253], off
	v_lshl_add_u64 v[252:253], s[20:21], 0, v[134:135]
	s_add_i32 m0, s22, 0x2000
	s_nop 0
	global_load_lds_dwordx4 v[252:253], off
	s_waitcnt lgkmcnt(0)
	s_waitcnt vmcnt(8)
	s_setprio 1
	s_barrier
	v_mfma_f32_16x16x32_bf16 v[60:63], v[144:147], v[168:171], v[60:63]
	v_mfma_f32_16x16x32_bf16 v[56:59], v[160:163], v[168:171], v[56:59]
	v_mfma_f32_16x16x32_bf16 v[48:51], v[144:147], v[176:179], v[48:51]
	v_mfma_f32_16x16x32_bf16 v[40:43], v[160:163], v[176:179], v[40:43]
	v_mfma_f32_16x16x32_bf16 v[28:31], v[144:147], v[184:187], v[28:31]
	v_mfma_f32_16x16x32_bf16 v[24:27], v[160:163], v[184:187], v[24:27]
	v_mfma_f32_16x16x32_bf16 v[20:23], v[144:147], v[192:195], v[20:23]
	v_mfma_f32_16x16x32_bf16 v[12:15], v[160:163], v[192:195], v[12:15]
	v_mfma_f32_16x16x32_bf16 v[60:63], v[156:159], v[172:175], v[60:63]
	v_mfma_f32_16x16x32_bf16 v[56:59], v[164:167], v[172:175], v[56:59]
	v_mfma_f32_16x16x32_bf16 v[48:51], v[156:159], v[180:183], v[48:51]
	v_mfma_f32_16x16x32_bf16 v[40:43], v[164:167], v[180:183], v[40:43]
	v_mfma_f32_16x16x32_bf16 v[28:31], v[156:159], v[188:191], v[28:31]
	v_mfma_f32_16x16x32_bf16 v[24:27], v[164:167], v[188:191], v[24:27]
	v_mfma_f32_16x16x32_bf16 v[20:23], v[156:159], v[196:199], v[20:23]
	v_mfma_f32_16x16x32_bf16 v[12:15], v[164:167], v[196:199], v[12:15]
	v_mfma_f32_16x16x32_bf16 v[52:55], v[200:203], v[168:171], v[52:55]
	v_mfma_f32_16x16x32_bf16 v[44:47], v[208:211], v[168:171], v[44:47]
	v_mfma_f32_16x16x32_bf16 v[36:39], v[200:203], v[176:179], v[36:39]
	v_mfma_f32_16x16x32_bf16 v[32:35], v[208:211], v[176:179], v[32:35]
	v_mfma_f32_16x16x32_bf16 v[16:19], v[200:203], v[184:187], v[16:19]
	v_mfma_f32_16x16x32_bf16 v[8:11], v[208:211], v[184:187], v[8:11]
	v_mfma_f32_16x16x32_bf16 v[4:7], v[200:203], v[192:195], v[4:7]
	v_mfma_f32_16x16x32_bf16 v[0:3], v[208:211], v[192:195], v[0:3]
	v_mfma_f32_16x16x32_bf16 v[52:55], v[204:207], v[172:175], v[52:55]
	v_mfma_f32_16x16x32_bf16 v[44:47], v[212:215], v[172:175], v[44:47]
	v_mfma_f32_16x16x32_bf16 v[36:39], v[204:207], v[180:183], v[36:39]
	v_mfma_f32_16x16x32_bf16 v[32:35], v[212:215], v[180:183], v[32:35]
	v_mfma_f32_16x16x32_bf16 v[16:19], v[204:207], v[188:191], v[16:19]
	v_mfma_f32_16x16x32_bf16 v[8:11], v[212:215], v[188:191], v[8:11]
	v_mfma_f32_16x16x32_bf16 v[4:7], v[204:207], v[196:199], v[4:7]
	v_mfma_f32_16x16x32_bf16 v[0:3], v[212:215], v[196:199], v[0:3]
	s_barrier
	s_setprio 0
	s_add_i32 s64, s64, 2
	s_add_u32 s18, s18, 0x100
	s_addc_u32 s19, s19, 0
	s_add_u32 s62, s62, 0x100
	s_addc_u32 s63, s63, 0
	s_cmpk_gt_u32 s64, 0x53
	.p2align	6
